# GEMM K-loops: priority flip pair after every 8 MFMAs instead of every 16 (lets the loading partner wave issue more often)
# speedup vs baseline: 1.0015x; 1.0015x over previous
;     __device__ bool next(int i, Unit& u) const { const int L = i * G + c; if (L >= 192) return false; u.pm = L / 6; u.pn = L % 6; return true; }
;     __device__ __forceinline__ size_t a_extra(const Unit& u) const { return (size_t)(u.pn >> 1) * ((size_t)T * 512 * 2); }
;     __device__ bool next(int i, Unit& u) const { const int L = i * G + c; if (L >= 256) return false; u.pm = L >> 3; u.pn = L & 7; return true; }
;     __device__ __forceinline__ size_t a_extra(const Unit& u) const { return (size_t)(u.pn >> 1) * 512 * 2; }
;     __device__ __forceinline__ size_t b_extra(const Unit& u) const { return (size_t)(u.pn >> 1) * 512 * 2 - (size_t)(u.pn & ~1) * ((size_t)256 * D * 2); }
; #define PG8_STAGE(bufoff, gbase, voff) do { _Pragma("unroll") for (int _i = 0; _i < 2; ++_i) \
;         __builtin_amdgcn_global_load_lds((const unsigned*)((const char*)(gbase) + (voff)[_i]), (PG8_LAS unsigned*)(lds + (bufoff) + ldsw + _i * 8192), 16, 0, 0); } while (0)
; template <class Epi, class Sched, bool ALIGN_EPI = true, bool SP2 = true, bool GS = false>
; __device__ __forceinline__ void gemm_phase(PG8_LAS unsigned char* lds, const Gemm g, const Sched& S, const Epi& E, const float* gs_ss = nullptr) {
;     ...
;         const bool has_next = S.next(ui + 1, nxt);
;         const char* nA = has_next ? (const char*)g.A + S.a_extra(nxt) + (size_t)nxt.pm * tstep : cA; const char* nB = has_next ? (const char*)g.Bt + S.b_extra(nxt) + (size_t)nxt.pn * tstep : cB;
;         for (int t = 0; t < nt; t += 2) {
;             const bool last = (t == nt - 2);
;             const char* a1 = cA + (size_t)(t + 1) * kstep;
;             const char* a2 = last ? nA : cA + (size_t)(t + 2) * kstep; const char* b2 = last ? nB : cB + (size_t)(t + 2) * kstep;
;             const char* a3 = a2 + kstep; const char* b3 = b2 + kstep;
;             if constexpr (SP2) {
;             PG8_LDB(B0, 0, 0); PG8_LDB(B1, 0, 1); PG8_SCHED; PG8_LDA(At, 0, 0); PG8_STAGE(PG8_SA(1, 1), a1 + hstep, voffA);
;             PG8_WAIT_V(8); PG8_WAIT_L(0); PG8_BAR; PG8_MMA(0, 0, At, B0); PG8_MMA(0, 1, At, B1); PG8_BAR; PG8_SCHED;
;             PG8_LDA(At, 0, 1); PG8_STAGE(PG8_SB(0, 0), b2, voffB); PG8_STAGE(PG8_SB(0, 1), b2 + hstep, voffB); PG8_STAGE(PG8_SA(0, 0), a2, voffA);
;             PG8_WAIT_V(8); PG8_WAIT_L(0); PG8_BAR; PG8_MMA(1, 0, At, B0); PG8_MMA(1, 1, At, B1); PG8_BAR; PG8_SCHED;
.LBB0_151:
	s_add_u32 s2, s40, 0xfff80080
	s_addc_u32 s3, s41, -1
	s_add_i32 s67, 0, 0x10000
	s_cmp_eq_u32 s65, 28
	s_cselect_b32 s21, s13, s3
	s_cselect_b32 s20, s53, s2
	v_add_u32_e32 v0, s67, v167
	s_cselect_b32 s3, s51, s43
	s_cselect_b32 s2, s64, s42
	s_add_i32 s69, 0, 0x14000
	ds_read_b128 v[146:149], v0
	ds_read_b128 v[150:153], v0 offset:1024
	ds_read_b128 v[154:157], v0 offset:2048
	ds_read_b128 v[158:161], v0 offset:3072
	v_add_u32_e32 v0, s69, v167
	ds_read_b128 v[162:165], v0
	ds_read_b128 v[172:175], v0 offset:1024
	ds_read_b128 v[180:183], v0 offset:2048
	ds_read_b128 v[184:187], v0 offset:3072
	v_lshl_add_u64 v[176:177], s[40:41], 0, v[142:143]
	s_add_i32 m0, s24, 0xc000
	ds_read_b128 v[188:191], v171
	ds_read_b128 v[192:195], v171 offset:1024
	ds_read_b128 v[196:199], v171 offset:2048
	ds_read_b128 v[200:203], v171 offset:3072
	ds_read_b128 v[204:207], v171 offset:4096
	ds_read_b128 v[208:211], v171 offset:5120
	ds_read_b128 v[212:215], v171 offset:6144
	ds_read_b128 v[216:219], v171 offset:7168
	global_load_lds_dwordx4 v[176:177], off
	v_lshl_add_u64 v[176:177], s[40:41], 0, v[144:145]
	s_add_i32 m0, s24, 0xe000
	s_nop 0
	global_load_lds_dwordx4 v[176:177], off
	s_waitcnt vmcnt(8)
	s_waitcnt lgkmcnt(0)
	s_barrier
	s_setprio 1
	s_waitcnt lgkmcnt(0)
	v_mfma_f32_16x16x32_bf16 v[126:129], v[146:149], v[188:191], v[126:129]
	v_mfma_f32_16x16x32_bf16 v[122:125], v[154:157], v[188:191], v[122:125]
	v_mfma_f32_16x16x32_bf16 v[110:113], v[146:149], v[196:199], v[110:113]
	v_mfma_f32_16x16x32_bf16 v[106:109], v[154:157], v[196:199], v[106:109]
	v_mfma_f32_16x16x32_bf16 v[94:97], v[146:149], v[204:207], v[94:97]
	v_mfma_f32_16x16x32_bf16 v[90:93], v[154:157], v[204:207], v[90:93]
	v_mfma_f32_16x16x32_bf16 v[78:81], v[146:149], v[212:215], v[78:81]
	v_mfma_f32_16x16x32_bf16 v[74:77], v[154:157], v[212:215], v[74:77]
	s_setprio 0
	s_setprio 1
	v_mfma_f32_16x16x32_bf16 v[126:129], v[150:153], v[192:195], v[126:129]
	v_mfma_f32_16x16x32_bf16 v[122:125], v[158:161], v[192:195], v[122:125]
	v_mfma_f32_16x16x32_bf16 v[110:113], v[150:153], v[200:203], v[110:113]
	v_mfma_f32_16x16x32_bf16 v[106:109], v[158:161], v[200:203], v[106:109]
	v_mfma_f32_16x16x32_bf16 v[94:97], v[150:153], v[208:211], v[94:97]
	v_mfma_f32_16x16x32_bf16 v[90:93], v[158:161], v[208:211], v[90:93]
	v_mfma_f32_16x16x32_bf16 v[78:81], v[150:153], v[216:219], v[78:81]
	v_mfma_f32_16x16x32_bf16 v[74:77], v[158:161], v[216:219], v[74:77]
	s_setprio 0
	s_setprio 1
	v_mfma_f32_16x16x32_bf16 v[118:121], v[162:165], v[188:191], v[118:121]
	v_mfma_f32_16x16x32_bf16 v[114:117], v[180:183], v[188:191], v[114:117]
	v_mfma_f32_16x16x32_bf16 v[102:105], v[162:165], v[196:199], v[102:105]
	v_mfma_f32_16x16x32_bf16 v[98:101], v[180:183], v[196:199], v[98:101]
	v_mfma_f32_16x16x32_bf16 v[86:89], v[162:165], v[204:207], v[86:89]
	v_mfma_f32_16x16x32_bf16 v[82:85], v[180:183], v[204:207], v[82:85]
	v_mfma_f32_16x16x32_bf16 v[70:73], v[162:165], v[212:215], v[70:73]
	v_mfma_f32_16x16x32_bf16 v[66:69], v[180:183], v[212:215], v[66:69]
	s_setprio 0
	s_setprio 1
	v_mfma_f32_16x16x32_bf16 v[118:121], v[172:175], v[192:195], v[118:121]
	v_mfma_f32_16x16x32_bf16 v[114:117], v[184:187], v[192:195], v[114:117]
	v_mfma_f32_16x16x32_bf16 v[102:105], v[172:175], v[200:203], v[102:105]
	v_mfma_f32_16x16x32_bf16 v[98:101], v[184:187], v[200:203], v[98:101]
	v_mfma_f32_16x16x32_bf16 v[86:89], v[172:175], v[208:211], v[86:89]
	v_mfma_f32_16x16x32_bf16 v[82:85], v[184:187], v[208:211], v[82:85]
	v_mfma_f32_16x16x32_bf16 v[70:73], v[172:175], v[216:219], v[70:73]
	v_mfma_f32_16x16x32_bf16 v[66:69], v[184:187], v[216:219], v[66:69]
	s_setprio 0
	s_barrier
	s_add_i32 s67, s67, s23
	v_lshl_add_u64 v[176:177], s[2:3], 0, v[132:133]
	s_mov_b32 m0, s67
	ds_read_b128 v[188:191], v171 offset:16384
	ds_read_b128 v[192:195], v171 offset:17408
	ds_read_b128 v[196:199], v171 offset:18432
	ds_read_b128 v[200:203], v171 offset:19456
	ds_read_b128 v[204:207], v171 offset:20480
	ds_read_b128 v[208:211], v171 offset:21504
	ds_read_b128 v[212:215], v171 offset:22528
	ds_read_b128 v[216:219], v171 offset:23552
	global_load_lds_dwordx4 v[176:177], off
	s_add_i32 m0, s67, 0x2000
	s_add_u32 s70, s2, 0x80000
	v_lshl_add_u64 v[220:221], s[2:3], 0, v[136:137]
	s_addc_u32 s71, s3, 0
	s_add_i32 s67, s69, s23
	global_load_lds_dwordx4 v[220:221], off
	v_lshl_add_u64 v[236:237], s[70:71], 0, v[132:133]
	s_mov_b32 m0, s67
	v_lshl_add_u64 v[238:239], s[20:21], 0, v[134:135]
	global_load_lds_dwordx4 v[236:237], off
	v_lshl_add_u64 v[236:237], s[70:71], 0, v[136:137]
	s_add_i32 m0, s67, 0x2000
	s_nop 0
	global_load_lds_dwordx4 v[236:237], off
	v_lshl_add_u64 v[236:237], s[20:21], 0, v[130:131]
	s_mov_b32 m0, s24
	s_nop 0
	global_load_lds_dwordx4 v[236:237], off
	s_mov_b32 m0, s25
	s_nop 0
	global_load_lds_dwordx4 v[238:239], off
	s_waitcnt vmcnt(8)
	s_waitcnt lgkmcnt(0)
	s_barrier
; #define PG8_STAGE(bufoff, gbase, voff) do { _Pragma("unroll") for (int _i = 0; _i < 2; ++_i) \
;         __builtin_amdgcn_global_load_lds((const unsigned*)((const char*)(gbase) + (voff)[_i]), (PG8_LAS unsigned*)(lds + (bufoff) + ldsw + _i * 8192), 16, 0, 0); } while (0)
; #define PG8_LDA(dst, b, h) do { _Pragma("unroll") for (int m = 0; m < 4; ++m) _Pragma("unroll") for (int k = 0; k < 2; ++k) dst[m][k] = *(const PG8_LAS bf16x8*)(lds + PG8_SA(b, h) + aoff + m * 2048 + k * 1024); } while (0)
; #define PG8_LDB(dst, b, h) do { _Pragma("unroll") for (int n = 0; n < 2; ++n) _Pragma("unroll") for (int k = 0; k < 2; ++k) dst[n][k] = *(const PG8_LAS bf16x8*)(lds + PG8_SB(b, h) + boff + n * 2048 + k * 1024); } while (0)
; #define PG8_MMA(ai, bj, At, Bt) do { __builtin_amdgcn_s_setprio(1); _Pragma("unroll") for (int m = 0; m < 4; ++m) _Pragma("unroll") for (int n = 0; n < 2; ++n) _Pragma("unroll") for (int k = 0; k < 2; ++k) \
;         acc[ai][bj][m][n] = __builtin_amdgcn_mfma_f32_16x16x32_bf16(Bt[n][k], At[m][k], acc[ai][bj][m][n], 0, 0, 0); __builtin_amdgcn_s_setprio(0); } while (0)
; #define PG8_WAIT_V(n) asm volatile("s_waitcnt vmcnt(" #n ")" ::: "memory")
; #define PG8_WAIT_L(n) asm volatile("s_waitcnt lgkmcnt(" #n ")" ::: "memory")
; #define PG8_BAR __builtin_amdgcn_s_barrier()
; #define PG8_SCHED __builtin_amdgcn_sched_barrier(0)
; template <class Epi, class Sched, bool ALIGN_EPI = true, bool SP2 = true, bool GS = false>
; __device__ __forceinline__ void gemm_phase(PG8_LAS unsigned char* lds, const Gemm g, const Sched& S, const Epi& E, const float* gs_ss = nullptr) {
;     ...
;             PG8_WAIT_V(8); PG8_WAIT_L(0); PG8_BAR; PG8_MMA(1, 0, At, B0); PG8_MMA(1, 1, At, B1); PG8_BAR; PG8_SCHED;
;             PG8_LDB(B0, 1, 0); PG8_LDB(B1, 1, 1); PG8_SCHED; PG8_LDA(At, 1, 0); PG8_STAGE(PG8_SA(0, 1), a2 + hstep, voffA);
;             PG8_WAIT_V(8); PG8_WAIT_L(0); PG8_BAR; PG8_MMA(0, 0, At, B0); PG8_MMA(0, 1, At, B1); PG8_BAR; PG8_SCHED;
;             PG8_LDA(At, 1, 1); PG8_STAGE(PG8_SB(1, 0), b3, voffB); PG8_STAGE(PG8_SB(1, 1), b3 + hstep, voffB); PG8_STAGE(PG8_SA(1, 0), a3, voffA);
	s_setprio 1
	s_waitcnt lgkmcnt(0)
	v_mfma_f32_16x16x32_bf16 v[62:65], v[146:149], v[188:191], v[62:65]
	v_mfma_f32_16x16x32_bf16 v[58:61], v[154:157], v[188:191], v[58:61]
	v_mfma_f32_16x16x32_bf16 v[46:49], v[146:149], v[196:199], v[46:49]
	v_mfma_f32_16x16x32_bf16 v[42:45], v[154:157], v[196:199], v[42:45]
	v_mfma_f32_16x16x32_bf16 v[30:33], v[146:149], v[204:207], v[30:33]
	v_mfma_f32_16x16x32_bf16 v[26:29], v[154:157], v[204:207], v[26:29]
	v_mfma_f32_16x16x32_bf16 v[14:17], v[146:149], v[212:215], v[14:17]
	v_mfma_f32_16x16x32_bf16 v[10:13], v[154:157], v[212:215], v[10:13]
	s_setprio 0
	s_setprio 1
	v_mfma_f32_16x16x32_bf16 v[62:65], v[150:153], v[192:195], v[62:65]
	v_mfma_f32_16x16x32_bf16 v[58:61], v[158:161], v[192:195], v[58:61]
	v_mfma_f32_16x16x32_bf16 v[46:49], v[150:153], v[200:203], v[46:49]
	v_mfma_f32_16x16x32_bf16 v[42:45], v[158:161], v[200:203], v[42:45]
	v_mfma_f32_16x16x32_bf16 v[30:33], v[150:153], v[208:211], v[30:33]
	v_mfma_f32_16x16x32_bf16 v[26:29], v[158:161], v[208:211], v[26:29]
	v_mfma_f32_16x16x32_bf16 v[14:17], v[150:153], v[216:219], v[14:17]
	v_mfma_f32_16x16x32_bf16 v[10:13], v[158:161], v[216:219], v[10:13]
	s_setprio 0
	s_setprio 1
	v_mfma_f32_16x16x32_bf16 v[54:57], v[162:165], v[188:191], v[54:57]
	v_mfma_f32_16x16x32_bf16 v[50:53], v[180:183], v[188:191], v[50:53]
	v_mfma_f32_16x16x32_bf16 v[38:41], v[162:165], v[196:199], v[38:41]
	v_mfma_f32_16x16x32_bf16 v[34:37], v[180:183], v[196:199], v[34:37]
	v_mfma_f32_16x16x32_bf16 v[22:25], v[162:165], v[204:207], v[22:25]
	v_mfma_f32_16x16x32_bf16 v[18:21], v[180:183], v[204:207], v[18:21]
	v_mfma_f32_16x16x32_bf16 v[6:9], v[162:165], v[212:215], v[6:9]
	v_mfma_f32_16x16x32_bf16 v[2:5], v[180:183], v[212:215], v[2:5]
	s_setprio 0
	s_setprio 1
	v_mfma_f32_16x16x32_bf16 v[54:57], v[172:175], v[192:195], v[54:57]
	v_mfma_f32_16x16x32_bf16 v[50:53], v[184:187], v[192:195], v[50:53]
	v_mfma_f32_16x16x32_bf16 v[38:41], v[172:175], v[200:203], v[38:41]
	v_mfma_f32_16x16x32_bf16 v[34:37], v[184:187], v[200:203], v[34:37]
	v_mfma_f32_16x16x32_bf16 v[22:25], v[172:175], v[208:211], v[22:25]
	v_mfma_f32_16x16x32_bf16 v[18:21], v[184:187], v[208:211], v[18:21]
	v_mfma_f32_16x16x32_bf16 v[6:9], v[172:175], v[216:219], v[6:9]
	v_mfma_f32_16x16x32_bf16 v[2:5], v[184:187], v[216:219], v[2:5]
	s_setprio 0
	s_barrier
	s_add_i32 s67, 0, 0x18000
	v_add_u32_e32 v0, s67, v167
	s_add_i32 s69, 0, 0x1c000
	ds_read_b128 v[146:149], v0
	ds_read_b128 v[150:153], v0 offset:1024
	ds_read_b128 v[154:157], v0 offset:2048
	ds_read_b128 v[158:161], v0 offset:3072
	v_add_u32_e32 v0, s69, v167
	ds_read_b128 v[162:165], v0
	ds_read_b128 v[172:175], v0 offset:1024
	ds_read_b128 v[180:183], v0 offset:2048
	ds_read_b128 v[184:187], v0 offset:3072
	s_add_u32 s20, s20, 0x80000
	s_addc_u32 s21, s21, 0
	s_mov_b32 m0, s30
	v_lshl_add_u64 v[240:241], s[20:21], 0, v[130:131]
	ds_read_b128 v[188:191], v171 offset:32768
	ds_read_b128 v[192:195], v171 offset:33792
	ds_read_b128 v[196:199], v171 offset:34816
	ds_read_b128 v[200:203], v171 offset:35840
	ds_read_b128 v[204:207], v171 offset:36864
	ds_read_b128 v[208:211], v171 offset:37888
	ds_read_b128 v[212:215], v171 offset:38912
	ds_read_b128 v[216:219], v171 offset:39936
	global_load_lds_dwordx4 v[240:241], off
	v_lshl_add_u64 v[240:241], s[20:21], 0, v[134:135]
	s_mov_b32 m0, s35
	s_nop 0
	global_load_lds_dwordx4 v[240:241], off
	s_waitcnt vmcnt(8)
	s_waitcnt lgkmcnt(0)
	s_barrier
	s_setprio 1
	s_waitcnt lgkmcnt(0)
	v_mfma_f32_16x16x32_bf16 v[126:129], v[146:149], v[188:191], v[126:129]
	v_mfma_f32_16x16x32_bf16 v[122:125], v[154:157], v[188:191], v[122:125]
	v_mfma_f32_16x16x32_bf16 v[110:113], v[146:149], v[196:199], v[110:113]
	v_mfma_f32_16x16x32_bf16 v[106:109], v[154:157], v[196:199], v[106:109]
	v_mfma_f32_16x16x32_bf16 v[94:97], v[146:149], v[204:207], v[94:97]
	v_mfma_f32_16x16x32_bf16 v[90:93], v[154:157], v[204:207], v[90:93]
	v_mfma_f32_16x16x32_bf16 v[78:81], v[146:149], v[212:215], v[78:81]
	v_mfma_f32_16x16x32_bf16 v[74:77], v[154:157], v[212:215], v[74:77]
	s_setprio 0
	s_setprio 1
	v_mfma_f32_16x16x32_bf16 v[126:129], v[150:153], v[192:195], v[126:129]
	v_mfma_f32_16x16x32_bf16 v[122:125], v[158:161], v[192:195], v[122:125]
	v_mfma_f32_16x16x32_bf16 v[110:113], v[150:153], v[200:203], v[110:113]
	v_mfma_f32_16x16x32_bf16 v[106:109], v[158:161], v[200:203], v[106:109]
	v_mfma_f32_16x16x32_bf16 v[94:97], v[150:153], v[208:211], v[94:97]
	v_mfma_f32_16x16x32_bf16 v[90:93], v[158:161], v[208:211], v[90:93]
	v_mfma_f32_16x16x32_bf16 v[78:81], v[150:153], v[216:219], v[78:81]
	v_mfma_f32_16x16x32_bf16 v[74:77], v[158:161], v[216:219], v[74:77]
	s_setprio 0
	s_setprio 1
	v_mfma_f32_16x16x32_bf16 v[118:121], v[162:165], v[188:191], v[118:121]
	v_mfma_f32_16x16x32_bf16 v[114:117], v[180:183], v[188:191], v[114:117]
	v_mfma_f32_16x16x32_bf16 v[102:105], v[162:165], v[196:199], v[102:105]
	v_mfma_f32_16x16x32_bf16 v[98:101], v[180:183], v[196:199], v[98:101]
	v_mfma_f32_16x16x32_bf16 v[86:89], v[162:165], v[204:207], v[86:89]
	v_mfma_f32_16x16x32_bf16 v[82:85], v[180:183], v[204:207], v[82:85]
	v_mfma_f32_16x16x32_bf16 v[70:73], v[162:165], v[212:215], v[70:73]
	v_mfma_f32_16x16x32_bf16 v[66:69], v[180:183], v[212:215], v[66:69]
	s_setprio 0
	s_setprio 1
	v_mfma_f32_16x16x32_bf16 v[118:121], v[172:175], v[192:195], v[118:121]
	v_mfma_f32_16x16x32_bf16 v[114:117], v[184:187], v[192:195], v[114:117]
	v_mfma_f32_16x16x32_bf16 v[102:105], v[172:175], v[200:203], v[102:105]
	v_mfma_f32_16x16x32_bf16 v[98:101], v[184:187], v[200:203], v[98:101]
	v_mfma_f32_16x16x32_bf16 v[86:89], v[172:175], v[208:211], v[86:89]
	v_mfma_f32_16x16x32_bf16 v[82:85], v[184:187], v[208:211], v[82:85]
	v_mfma_f32_16x16x32_bf16 v[70:73], v[172:175], v[216:219], v[70:73]
	v_mfma_f32_16x16x32_bf16 v[66:69], v[184:187], v[216:219], v[66:69]
	s_setprio 0
	s_barrier
; #define PG8_STAGE(bufoff, gbase, voff) do { _Pragma("unroll") for (int _i = 0; _i < 2; ++_i) \
;         __builtin_amdgcn_global_load_lds((const unsigned*)((const char*)(gbase) + (voff)[_i]), (PG8_LAS unsigned*)(lds + (bufoff) + ldsw + _i * 8192), 16, 0, 0); } while (0)
; #define PG8_LDA(dst, b, h) do { _Pragma("unroll") for (int m = 0; m < 4; ++m) _Pragma("unroll") for (int k = 0; k < 2; ++k) dst[m][k] = *(const PG8_LAS bf16x8*)(lds + PG8_SA(b, h) + aoff + m * 2048 + k * 1024); } while (0)
; #define PG8_MMA(ai, bj, At, Bt) do { __builtin_amdgcn_s_setprio(1); _Pragma("unroll") for (int m = 0; m < 4; ++m) _Pragma("unroll") for (int n = 0; n < 2; ++n) _Pragma("unroll") for (int k = 0; k < 2; ++k) \
;         acc[ai][bj][m][n] = __builtin_amdgcn_mfma_f32_16x16x32_bf16(Bt[n][k], At[m][k], acc[ai][bj][m][n], 0, 0, 0); __builtin_amdgcn_s_setprio(0); } while (0)
; #define PG8_WAIT_V(n) asm volatile("s_waitcnt vmcnt(" #n ")" ::: "memory")
; #define PG8_WAIT_L(n) asm volatile("s_waitcnt lgkmcnt(" #n ")" ::: "memory")
; #define PG8_BAR __builtin_amdgcn_s_barrier()
; #define PG8_SCHED __builtin_amdgcn_sched_barrier(0)
; template <class Epi, class Sched, bool ALIGN_EPI = true, bool SP2 = true, bool GS = false>
; __device__ __forceinline__ void gemm_phase(PG8_LAS unsigned char* lds, const Gemm g, const Sched& S, const Epi& E, const float* gs_ss = nullptr) {
;     ...
;             PG8_LDA(At, 1, 1); PG8_STAGE(PG8_SB(1, 0), b3, voffB); PG8_STAGE(PG8_SB(1, 1), b3 + hstep, voffB); PG8_STAGE(PG8_SA(1, 0), a3, voffA);
;             PG8_WAIT_V(8); PG8_WAIT_L(0); PG8_BAR; PG8_MMA(1, 0, At, B0); PG8_MMA(1, 1, At, B1); PG8_BAR; PG8_SCHED;
	s_add_i32 s20, s67, s23
	v_lshl_add_u64 v[176:177], v[176:177], 0, s[26:27]
	s_mov_b32 m0, s20
	ds_read_b128 v[188:191], v171 offset:49152
	ds_read_b128 v[192:195], v171 offset:50176
	ds_read_b128 v[196:199], v171 offset:51200
	ds_read_b128 v[200:203], v171 offset:52224
	ds_read_b128 v[204:207], v171 offset:53248
	ds_read_b128 v[208:211], v171 offset:54272
	ds_read_b128 v[212:215], v171 offset:55296
	ds_read_b128 v[216:219], v171 offset:56320
	global_load_lds_dwordx4 v[176:177], off
	s_add_i32 m0, s20, 0x2000
	s_add_u32 s2, s2, 0x80080
	v_lshl_add_u64 v[176:177], v[220:221], 0, s[26:27]
	s_addc_u32 s3, s3, 0
	s_add_i32 s20, s69, s23
	global_load_lds_dwordx4 v[176:177], off
	v_lshl_add_u64 v[176:177], s[2:3], 0, v[132:133]
	s_mov_b32 m0, s20
	s_nop 0
	global_load_lds_dwordx4 v[176:177], off
	v_lshl_add_u64 v[176:177], s[2:3], 0, v[136:137]
	s_add_i32 m0, s20, 0x2000
	s_nop 0
	global_load_lds_dwordx4 v[176:177], off
	v_lshl_add_u64 v[176:177], v[236:237], 0, s[26:27]
	s_mov_b32 m0, s59
	s_nop 0
	global_load_lds_dwordx4 v[176:177], off
	v_lshl_add_u64 v[176:177], v[238:239], 0, s[26:27]
	s_mov_b32 m0, s60
	s_nop 0
	global_load_lds_dwordx4 v[176:177], off
	s_waitcnt vmcnt(8)
	s_waitcnt lgkmcnt(0)
	s_barrier
	s_setprio 1
	s_waitcnt lgkmcnt(0)
	v_mfma_f32_16x16x32_bf16 v[62:65], v[146:149], v[188:191], v[62:65]
	v_mfma_f32_16x16x32_bf16 v[58:61], v[154:157], v[188:191], v[58:61]
	v_mfma_f32_16x16x32_bf16 v[46:49], v[146:149], v[196:199], v[46:49]
	v_mfma_f32_16x16x32_bf16 v[42:45], v[154:157], v[196:199], v[42:45]
	v_mfma_f32_16x16x32_bf16 v[30:33], v[146:149], v[204:207], v[30:33]
	v_mfma_f32_16x16x32_bf16 v[26:29], v[154:157], v[204:207], v[26:29]
	v_mfma_f32_16x16x32_bf16 v[14:17], v[146:149], v[212:215], v[14:17]
	v_mfma_f32_16x16x32_bf16 v[10:13], v[154:157], v[212:215], v[10:13]
	s_setprio 0
	s_setprio 1
	v_mfma_f32_16x16x32_bf16 v[62:65], v[150:153], v[192:195], v[62:65]
	v_mfma_f32_16x16x32_bf16 v[58:61], v[158:161], v[192:195], v[58:61]
	v_mfma_f32_16x16x32_bf16 v[46:49], v[150:153], v[200:203], v[46:49]
	v_mfma_f32_16x16x32_bf16 v[42:45], v[158:161], v[200:203], v[42:45]
	v_mfma_f32_16x16x32_bf16 v[30:33], v[150:153], v[208:211], v[30:33]
	v_mfma_f32_16x16x32_bf16 v[26:29], v[158:161], v[208:211], v[26:29]
	v_mfma_f32_16x16x32_bf16 v[14:17], v[150:153], v[216:219], v[14:17]
	v_mfma_f32_16x16x32_bf16 v[10:13], v[158:161], v[216:219], v[10:13]
	s_setprio 0
	s_setprio 1
	v_mfma_f32_16x16x32_bf16 v[54:57], v[162:165], v[188:191], v[54:57]
	v_mfma_f32_16x16x32_bf16 v[50:53], v[180:183], v[188:191], v[50:53]
	v_mfma_f32_16x16x32_bf16 v[38:41], v[162:165], v[196:199], v[38:41]
	v_mfma_f32_16x16x32_bf16 v[34:37], v[180:183], v[196:199], v[34:37]
	v_mfma_f32_16x16x32_bf16 v[22:25], v[162:165], v[204:207], v[22:25]
	v_mfma_f32_16x16x32_bf16 v[18:21], v[180:183], v[204:207], v[18:21]
	v_mfma_f32_16x16x32_bf16 v[6:9], v[162:165], v[212:215], v[6:9]
	v_mfma_f32_16x16x32_bf16 v[2:5], v[180:183], v[212:215], v[2:5]
	s_setprio 0
	s_setprio 1
	v_mfma_f32_16x16x32_bf16 v[54:57], v[172:175], v[192:195], v[54:57]
	v_mfma_f32_16x16x32_bf16 v[50:53], v[184:187], v[192:195], v[50:53]
	v_mfma_f32_16x16x32_bf16 v[38:41], v[172:175], v[200:203], v[38:41]
	v_mfma_f32_16x16x32_bf16 v[34:37], v[184:187], v[200:203], v[34:37]
	v_mfma_f32_16x16x32_bf16 v[22:25], v[172:175], v[208:211], v[22:25]
	v_mfma_f32_16x16x32_bf16 v[18:21], v[184:187], v[208:211], v[18:21]
	v_mfma_f32_16x16x32_bf16 v[6:9], v[172:175], v[216:219], v[6:9]
	v_mfma_f32_16x16x32_bf16 v[2:5], v[184:187], v[216:219], v[2:5]
	s_setprio 0
	s_barrier
	s_add_i32 s65, s65, 2
	s_add_u32 s40, s40, 0x100
	s_addc_u32 s41, s41, 0
	s_add_u32 s42, s42, 0x100
	s_addc_u32 s43, s43, 0
	s_cmp_gt_u32 s65, 29
	s_cbranch_scc0 .LBB0_151
	s_and_b64 vcc, exec, s[46:47]
	s_cbranch_vccz .LBB0_154
	s_barrier

;     __device__ bool next(int i, Unit& u) const { const int L = i * G + c; if (L >= 192) return false; u.pm = L / 6; u.pn = L % 6; return true; }
;     __device__ __forceinline__ size_t a_extra(const Unit& u) const { return (size_t)(u.pn >> 1) * ((size_t)T * 512 * 2); }
;     __device__ bool next(int i, Unit& u) const { const int L = i * G + c; if (L >= 256) return false; u.pm = L >> 3; u.pn = L & 7; return true; }
;     __device__ __forceinline__ size_t a_extra(const Unit& u) const { return (size_t)(u.pn >> 1) * 512 * 2; }
;     __device__ __forceinline__ size_t b_extra(const Unit& u) const { return (size_t)(u.pn >> 1) * 512 * 2 - (size_t)(u.pn & ~1) * ((size_t)256 * D * 2); }
; #define PG8_STAGE(bufoff, gbase, voff) do { _Pragma("unroll") for (int _i = 0; _i < 2; ++_i) \
;         __builtin_amdgcn_global_load_lds((const unsigned*)((const char*)(gbase) + (voff)[_i]), (PG8_LAS unsigned*)(lds + (bufoff) + ldsw + _i * 8192), 16, 0, 0); } while (0)
; template <class Epi, class Sched, bool ALIGN_EPI = true, bool SP2 = true, bool GS = false>
; __device__ __forceinline__ void gemm_phase(PG8_LAS unsigned char* lds, const Gemm g, const Sched& S, const Epi& E, const float* gs_ss = nullptr) {
;     ...
;         const bool has_next = S.next(ui + 1, nxt);
;         const char* nA = has_next ? (const char*)g.A + S.a_extra(nxt) + (size_t)nxt.pm * tstep : cA; const char* nB = has_next ? (const char*)g.Bt + S.b_extra(nxt) + (size_t)nxt.pn * tstep : cB;
;         for (int t = 0; t < nt; t += 2) {
;             const bool last = (t == nt - 2);
;             const char* a1 = cA + (size_t)(t + 1) * kstep;
;             const char* a2 = last ? nA : cA + (size_t)(t + 2) * kstep; const char* b2 = last ? nB : cB + (size_t)(t + 2) * kstep;
;             const char* a3 = a2 + kstep; const char* b3 = b2 + kstep;
;             if constexpr (SP2) {
;             PG8_LDB(B0, 0, 0); PG8_LDB(B1, 0, 1); PG8_SCHED; PG8_LDA(At, 0, 0); PG8_STAGE(PG8_SA(1, 1), a1 + hstep, voffA);
;             PG8_WAIT_V(8); PG8_WAIT_L(0); PG8_BAR; PG8_MMA(0, 0, At, B0); PG8_MMA(0, 1, At, B1); PG8_BAR; PG8_SCHED;
;             PG8_LDA(At, 0, 1); PG8_STAGE(PG8_SB(0, 0), b2, voffB); PG8_STAGE(PG8_SB(0, 1), b2 + hstep, voffB); PG8_STAGE(PG8_SA(0, 0), a2, voffA);
;             PG8_WAIT_V(8); PG8_WAIT_L(0); PG8_BAR; PG8_MMA(1, 0, At, B0); PG8_MMA(1, 1, At, B1); PG8_BAR; PG8_SCHED;
.LBB0_314:
	s_add_u32 s2, s38, 0xfff80080
	s_addc_u32 s3, s39, -1
	s_add_i32 s64, 0, 0x10000
	s_cmp_eq_u32 s51, 28
	s_cselect_b32 s21, s13, s3
	s_cselect_b32 s20, s16, s2
	v_add_u32_e32 v0, s64, v173
	s_cselect_b32 s3, s17, s41
	s_cselect_b32 s2, s49, s40
	s_add_i32 s67, 0, 0x14000
	ds_read_b128 v[130:133], v0
	ds_read_b128 v[150:153], v0 offset:1024
	ds_read_b128 v[154:157], v0 offset:2048
	ds_read_b128 v[158:161], v0 offset:3072
	v_add_u32_e32 v0, s67, v173
	ds_read_b128 v[162:165], v0
	ds_read_b128 v[166:169], v0 offset:1024
	ds_read_b128 v[188:191], v0 offset:2048
	ds_read_b128 v[192:195], v0 offset:3072
	v_lshl_add_u64 v[170:171], s[38:39], 0, v[146:147]
	s_add_i32 m0, s24, 0xc000
	ds_read_b128 v[196:199], v177
	ds_read_b128 v[200:203], v177 offset:1024
	ds_read_b128 v[204:207], v177 offset:2048
	ds_read_b128 v[208:211], v177 offset:3072
	ds_read_b128 v[212:215], v177 offset:4096
	ds_read_b128 v[216:219], v177 offset:5120
	ds_read_b128 v[236:239], v177 offset:6144
	ds_read_b128 v[240:243], v177 offset:7168
	global_load_lds_dwordx4 v[170:171], off
	v_lshl_add_u64 v[170:171], s[38:39], 0, v[148:149]
	s_add_i32 m0, s24, 0xe000
	s_nop 0
	global_load_lds_dwordx4 v[170:171], off
	s_waitcnt vmcnt(8)
	s_waitcnt lgkmcnt(0)
	s_barrier
	s_setprio 1
	s_waitcnt lgkmcnt(0)
	v_mfma_f32_16x16x32_bf16 v[126:129], v[130:133], v[196:199], v[126:129]
	v_mfma_f32_16x16x32_bf16 v[122:125], v[154:157], v[196:199], v[122:125]
	v_mfma_f32_16x16x32_bf16 v[118:121], v[130:133], v[204:207], v[118:121]
	v_mfma_f32_16x16x32_bf16 v[110:113], v[154:157], v[204:207], v[110:113]
	v_mfma_f32_16x16x32_bf16 v[102:105], v[130:133], v[212:215], v[102:105]
	v_mfma_f32_16x16x32_bf16 v[94:97], v[154:157], v[212:215], v[94:97]
	v_mfma_f32_16x16x32_bf16 v[86:89], v[130:133], v[236:239], v[86:89]
	v_mfma_f32_16x16x32_bf16 v[78:81], v[154:157], v[236:239], v[78:81]
	s_setprio 0
	s_setprio 1
	v_mfma_f32_16x16x32_bf16 v[126:129], v[150:153], v[200:203], v[126:129]
	v_mfma_f32_16x16x32_bf16 v[122:125], v[158:161], v[200:203], v[122:125]
	v_mfma_f32_16x16x32_bf16 v[118:121], v[150:153], v[208:211], v[118:121]
	v_mfma_f32_16x16x32_bf16 v[110:113], v[158:161], v[208:211], v[110:113]
	v_mfma_f32_16x16x32_bf16 v[102:105], v[150:153], v[216:219], v[102:105]
	v_mfma_f32_16x16x32_bf16 v[94:97], v[158:161], v[216:219], v[94:97]
	v_mfma_f32_16x16x32_bf16 v[86:89], v[150:153], v[240:243], v[86:89]
	v_mfma_f32_16x16x32_bf16 v[78:81], v[158:161], v[240:243], v[78:81]
	s_setprio 0
	s_setprio 1
	v_mfma_f32_16x16x32_bf16 v[114:117], v[162:165], v[196:199], v[114:117]
	v_mfma_f32_16x16x32_bf16 v[106:109], v[188:191], v[196:199], v[106:109]
	v_mfma_f32_16x16x32_bf16 v[98:101], v[162:165], v[204:207], v[98:101]
	v_mfma_f32_16x16x32_bf16 v[90:93], v[188:191], v[204:207], v[90:93]
	v_mfma_f32_16x16x32_bf16 v[82:85], v[162:165], v[212:215], v[82:85]
	v_mfma_f32_16x16x32_bf16 v[74:77], v[188:191], v[212:215], v[74:77]
	v_mfma_f32_16x16x32_bf16 v[70:73], v[162:165], v[236:239], v[70:73]
	v_mfma_f32_16x16x32_bf16 v[66:69], v[188:191], v[236:239], v[66:69]
	s_setprio 0
	s_setprio 1
	v_mfma_f32_16x16x32_bf16 v[114:117], v[166:169], v[200:203], v[114:117]
	v_mfma_f32_16x16x32_bf16 v[106:109], v[192:195], v[200:203], v[106:109]
	v_mfma_f32_16x16x32_bf16 v[98:101], v[166:169], v[208:211], v[98:101]
	v_mfma_f32_16x16x32_bf16 v[90:93], v[192:195], v[208:211], v[90:93]
	v_mfma_f32_16x16x32_bf16 v[82:85], v[166:169], v[216:219], v[82:85]
	v_mfma_f32_16x16x32_bf16 v[74:77], v[192:195], v[216:219], v[74:77]
	v_mfma_f32_16x16x32_bf16 v[70:73], v[166:169], v[240:243], v[70:73]
	v_mfma_f32_16x16x32_bf16 v[66:69], v[192:195], v[240:243], v[66:69]
	s_setprio 0
	s_barrier
	s_add_i32 s64, s64, s23
	v_lshl_add_u64 v[170:171], s[2:3], 0, v[136:137]
	s_mov_b32 m0, s64
	ds_read_b128 v[196:199], v177 offset:16384
	ds_read_b128 v[200:203], v177 offset:17408
	ds_read_b128 v[204:207], v177 offset:18432
	ds_read_b128 v[208:211], v177 offset:19456
	ds_read_b128 v[212:215], v177 offset:20480
	ds_read_b128 v[216:219], v177 offset:21504
	ds_read_b128 v[236:239], v177 offset:22528
	ds_read_b128 v[240:243], v177 offset:23552
	global_load_lds_dwordx4 v[170:171], off
	s_add_i32 m0, s64, 0x2000
	s_add_u32 s64, s2, 0x80000
	v_lshl_add_u64 v[180:181], s[2:3], 0, v[140:141]
	s_addc_u32 s65, s3, 0
	s_add_i32 s67, s67, s23
	global_load_lds_dwordx4 v[180:181], off
	v_lshl_add_u64 v[182:183], s[64:65], 0, v[136:137]
	s_mov_b32 m0, s67
	v_lshl_add_u64 v[184:185], s[20:21], 0, v[138:139]
	global_load_lds_dwordx4 v[182:183], off
	v_lshl_add_u64 v[182:183], s[64:65], 0, v[140:141]
	s_add_i32 m0, s67, 0x2000
	s_nop 0
	global_load_lds_dwordx4 v[182:183], off
	v_lshl_add_u64 v[182:183], s[20:21], 0, v[134:135]
	s_mov_b32 m0, s24
	s_nop 0
	global_load_lds_dwordx4 v[182:183], off
	s_mov_b32 m0, s25
	s_nop 0
	global_load_lds_dwordx4 v[184:185], off
	s_waitcnt vmcnt(8)
	s_waitcnt lgkmcnt(0)
	s_barrier
; #define PG8_STAGE(bufoff, gbase, voff) do { _Pragma("unroll") for (int _i = 0; _i < 2; ++_i) \
;         __builtin_amdgcn_global_load_lds((const unsigned*)((const char*)(gbase) + (voff)[_i]), (PG8_LAS unsigned*)(lds + (bufoff) + ldsw + _i * 8192), 16, 0, 0); } while (0)
; #define PG8_LDA(dst, b, h) do { _Pragma("unroll") for (int m = 0; m < 4; ++m) _Pragma("unroll") for (int k = 0; k < 2; ++k) dst[m][k] = *(const PG8_LAS bf16x8*)(lds + PG8_SA(b, h) + aoff + m * 2048 + k * 1024); } while (0)
; #define PG8_LDB(dst, b, h) do { _Pragma("unroll") for (int n = 0; n < 2; ++n) _Pragma("unroll") for (int k = 0; k < 2; ++k) dst[n][k] = *(const PG8_LAS bf16x8*)(lds + PG8_SB(b, h) + boff + n * 2048 + k * 1024); } while (0)
; #define PG8_MMA(ai, bj, At, Bt) do { __builtin_amdgcn_s_setprio(1); _Pragma("unroll") for (int m = 0; m < 4; ++m) _Pragma("unroll") for (int n = 0; n < 2; ++n) _Pragma("unroll") for (int k = 0; k < 2; ++k) \
;         acc[ai][bj][m][n] = __builtin_amdgcn_mfma_f32_16x16x32_bf16(Bt[n][k], At[m][k], acc[ai][bj][m][n], 0, 0, 0); __builtin_amdgcn_s_setprio(0); } while (0)
; #define PG8_WAIT_V(n) asm volatile("s_waitcnt vmcnt(" #n ")" ::: "memory")
; #define PG8_WAIT_L(n) asm volatile("s_waitcnt lgkmcnt(" #n ")" ::: "memory")
; #define PG8_BAR __builtin_amdgcn_s_barrier()
; #define PG8_SCHED __builtin_amdgcn_sched_barrier(0)
; template <class Epi, class Sched, bool ALIGN_EPI = true, bool SP2 = true, bool GS = false>
; __device__ __forceinline__ void gemm_phase(PG8_LAS unsigned char* lds, const Gemm g, const Sched& S, const Epi& E, const float* gs_ss = nullptr) {
;     ...
;             PG8_WAIT_V(8); PG8_WAIT_L(0); PG8_BAR; PG8_MMA(1, 0, At, B0); PG8_MMA(1, 1, At, B1); PG8_BAR; PG8_SCHED;
;             PG8_LDB(B0, 1, 0); PG8_LDB(B1, 1, 1); PG8_SCHED; PG8_LDA(At, 1, 0); PG8_STAGE(PG8_SA(0, 1), a2 + hstep, voffA);
;             PG8_WAIT_V(8); PG8_WAIT_L(0); PG8_BAR; PG8_MMA(0, 0, At, B0); PG8_MMA(0, 1, At, B1); PG8_BAR; PG8_SCHED;
;             PG8_LDA(At, 1, 1); PG8_STAGE(PG8_SB(1, 0), b3, voffB); PG8_STAGE(PG8_SB(1, 1), b3 + hstep, voffB); PG8_STAGE(PG8_SA(1, 0), a3, voffA);
	s_setprio 1
	s_waitcnt lgkmcnt(0)
	v_mfma_f32_16x16x32_bf16 v[62:65], v[130:133], v[196:199], v[62:65]
	v_mfma_f32_16x16x32_bf16 v[58:61], v[154:157], v[196:199], v[58:61]
	v_mfma_f32_16x16x32_bf16 v[54:57], v[130:133], v[204:207], v[54:57]
	v_mfma_f32_16x16x32_bf16 v[46:49], v[154:157], v[204:207], v[46:49]
	v_mfma_f32_16x16x32_bf16 v[38:41], v[130:133], v[212:215], v[38:41]
	v_mfma_f32_16x16x32_bf16 v[30:33], v[154:157], v[212:215], v[30:33]
	v_mfma_f32_16x16x32_bf16 v[22:25], v[130:133], v[236:239], v[22:25]
	v_mfma_f32_16x16x32_bf16 v[14:17], v[154:157], v[236:239], v[14:17]
	s_setprio 0
	s_setprio 1
	v_mfma_f32_16x16x32_bf16 v[62:65], v[150:153], v[200:203], v[62:65]
	v_mfma_f32_16x16x32_bf16 v[58:61], v[158:161], v[200:203], v[58:61]
	v_mfma_f32_16x16x32_bf16 v[54:57], v[150:153], v[208:211], v[54:57]
	v_mfma_f32_16x16x32_bf16 v[46:49], v[158:161], v[208:211], v[46:49]
	v_mfma_f32_16x16x32_bf16 v[38:41], v[150:153], v[216:219], v[38:41]
	v_mfma_f32_16x16x32_bf16 v[30:33], v[158:161], v[216:219], v[30:33]
	v_mfma_f32_16x16x32_bf16 v[22:25], v[150:153], v[240:243], v[22:25]
	v_mfma_f32_16x16x32_bf16 v[14:17], v[158:161], v[240:243], v[14:17]
	s_setprio 0
	s_setprio 1
	v_mfma_f32_16x16x32_bf16 v[50:53], v[162:165], v[196:199], v[50:53]
	v_mfma_f32_16x16x32_bf16 v[42:45], v[188:191], v[196:199], v[42:45]
	v_mfma_f32_16x16x32_bf16 v[34:37], v[162:165], v[204:207], v[34:37]
	v_mfma_f32_16x16x32_bf16 v[26:29], v[188:191], v[204:207], v[26:29]
	v_mfma_f32_16x16x32_bf16 v[18:21], v[162:165], v[212:215], v[18:21]
	v_mfma_f32_16x16x32_bf16 v[10:13], v[188:191], v[212:215], v[10:13]
	v_mfma_f32_16x16x32_bf16 v[6:9], v[162:165], v[236:239], v[6:9]
	v_mfma_f32_16x16x32_bf16 v[2:5], v[188:191], v[236:239], v[2:5]
	s_setprio 0
	s_setprio 1
	v_mfma_f32_16x16x32_bf16 v[50:53], v[166:169], v[200:203], v[50:53]
	v_mfma_f32_16x16x32_bf16 v[42:45], v[192:195], v[200:203], v[42:45]
	v_mfma_f32_16x16x32_bf16 v[34:37], v[166:169], v[208:211], v[34:37]
	v_mfma_f32_16x16x32_bf16 v[26:29], v[192:195], v[208:211], v[26:29]
	v_mfma_f32_16x16x32_bf16 v[18:21], v[166:169], v[216:219], v[18:21]
	v_mfma_f32_16x16x32_bf16 v[10:13], v[192:195], v[216:219], v[10:13]
	v_mfma_f32_16x16x32_bf16 v[6:9], v[166:169], v[240:243], v[6:9]
	v_mfma_f32_16x16x32_bf16 v[2:5], v[192:195], v[240:243], v[2:5]
	s_setprio 0
	s_barrier
	s_add_i32 s64, 0, 0x18000
	v_add_u32_e32 v0, s64, v173
	s_add_i32 s65, 0, 0x1c000
	ds_read_b128 v[130:133], v0
	ds_read_b128 v[150:153], v0 offset:1024
	ds_read_b128 v[154:157], v0 offset:2048
	ds_read_b128 v[158:161], v0 offset:3072
	v_add_u32_e32 v0, s65, v173
	ds_read_b128 v[162:165], v0
	ds_read_b128 v[166:169], v0 offset:1024
	ds_read_b128 v[188:191], v0 offset:2048
	ds_read_b128 v[192:195], v0 offset:3072
	s_add_u32 s20, s20, 0x80000
	s_addc_u32 s21, s21, 0
	s_mov_b32 m0, s30
	v_lshl_add_u64 v[186:187], s[20:21], 0, v[134:135]
	ds_read_b128 v[196:199], v177 offset:32768
	ds_read_b128 v[200:203], v177 offset:33792
	ds_read_b128 v[204:207], v177 offset:34816
	ds_read_b128 v[208:211], v177 offset:35840
	ds_read_b128 v[212:215], v177 offset:36864
	ds_read_b128 v[216:219], v177 offset:37888
	ds_read_b128 v[236:239], v177 offset:38912
	ds_read_b128 v[240:243], v177 offset:39936
	global_load_lds_dwordx4 v[186:187], off
	v_lshl_add_u64 v[186:187], s[20:21], 0, v[138:139]
	s_mov_b32 m0, s36
	s_nop 0
	global_load_lds_dwordx4 v[186:187], off
	s_waitcnt vmcnt(8)
	s_waitcnt lgkmcnt(0)
	s_barrier
	s_setprio 1
	s_waitcnt lgkmcnt(0)
	v_mfma_f32_16x16x32_bf16 v[126:129], v[130:133], v[196:199], v[126:129]
	v_mfma_f32_16x16x32_bf16 v[122:125], v[154:157], v[196:199], v[122:125]
	v_mfma_f32_16x16x32_bf16 v[118:121], v[130:133], v[204:207], v[118:121]
	v_mfma_f32_16x16x32_bf16 v[110:113], v[154:157], v[204:207], v[110:113]
	v_mfma_f32_16x16x32_bf16 v[102:105], v[130:133], v[212:215], v[102:105]
	v_mfma_f32_16x16x32_bf16 v[94:97], v[154:157], v[212:215], v[94:97]
	v_mfma_f32_16x16x32_bf16 v[86:89], v[130:133], v[236:239], v[86:89]
	v_mfma_f32_16x16x32_bf16 v[78:81], v[154:157], v[236:239], v[78:81]
	s_setprio 0
	s_setprio 1
	v_mfma_f32_16x16x32_bf16 v[126:129], v[150:153], v[200:203], v[126:129]
	v_mfma_f32_16x16x32_bf16 v[122:125], v[158:161], v[200:203], v[122:125]
	v_mfma_f32_16x16x32_bf16 v[118:121], v[150:153], v[208:211], v[118:121]
	v_mfma_f32_16x16x32_bf16 v[110:113], v[158:161], v[208:211], v[110:113]
	v_mfma_f32_16x16x32_bf16 v[102:105], v[150:153], v[216:219], v[102:105]
	v_mfma_f32_16x16x32_bf16 v[94:97], v[158:161], v[216:219], v[94:97]
	v_mfma_f32_16x16x32_bf16 v[86:89], v[150:153], v[240:243], v[86:89]
	v_mfma_f32_16x16x32_bf16 v[78:81], v[158:161], v[240:243], v[78:81]
	s_setprio 0
	s_setprio 1
	v_mfma_f32_16x16x32_bf16 v[114:117], v[162:165], v[196:199], v[114:117]
	v_mfma_f32_16x16x32_bf16 v[106:109], v[188:191], v[196:199], v[106:109]
	v_mfma_f32_16x16x32_bf16 v[98:101], v[162:165], v[204:207], v[98:101]
	v_mfma_f32_16x16x32_bf16 v[90:93], v[188:191], v[204:207], v[90:93]
	v_mfma_f32_16x16x32_bf16 v[82:85], v[162:165], v[212:215], v[82:85]
	v_mfma_f32_16x16x32_bf16 v[74:77], v[188:191], v[212:215], v[74:77]
	v_mfma_f32_16x16x32_bf16 v[70:73], v[162:165], v[236:239], v[70:73]
	v_mfma_f32_16x16x32_bf16 v[66:69], v[188:191], v[236:239], v[66:69]
	s_setprio 0
	s_setprio 1
	v_mfma_f32_16x16x32_bf16 v[114:117], v[166:169], v[200:203], v[114:117]
	v_mfma_f32_16x16x32_bf16 v[106:109], v[192:195], v[200:203], v[106:109]
	v_mfma_f32_16x16x32_bf16 v[98:101], v[166:169], v[208:211], v[98:101]
	v_mfma_f32_16x16x32_bf16 v[90:93], v[192:195], v[208:211], v[90:93]
	v_mfma_f32_16x16x32_bf16 v[82:85], v[166:169], v[216:219], v[82:85]
	v_mfma_f32_16x16x32_bf16 v[74:77], v[192:195], v[216:219], v[74:77]
	v_mfma_f32_16x16x32_bf16 v[70:73], v[166:169], v[240:243], v[70:73]
	v_mfma_f32_16x16x32_bf16 v[66:69], v[192:195], v[240:243], v[66:69]
	s_setprio 0
	s_barrier
; #define PG8_STAGE(bufoff, gbase, voff) do { _Pragma("unroll") for (int _i = 0; _i < 2; ++_i) \
;         __builtin_amdgcn_global_load_lds((const unsigned*)((const char*)(gbase) + (voff)[_i]), (PG8_LAS unsigned*)(lds + (bufoff) + ldsw + _i * 8192), 16, 0, 0); } while (0)
; #define PG8_LDA(dst, b, h) do { _Pragma("unroll") for (int m = 0; m < 4; ++m) _Pragma("unroll") for (int k = 0; k < 2; ++k) dst[m][k] = *(const PG8_LAS bf16x8*)(lds + PG8_SA(b, h) + aoff + m * 2048 + k * 1024); } while (0)
; #define PG8_MMA(ai, bj, At, Bt) do { __builtin_amdgcn_s_setprio(1); _Pragma("unroll") for (int m = 0; m < 4; ++m) _Pragma("unroll") for (int n = 0; n < 2; ++n) _Pragma("unroll") for (int k = 0; k < 2; ++k) \
;         acc[ai][bj][m][n] = __builtin_amdgcn_mfma_f32_16x16x32_bf16(Bt[n][k], At[m][k], acc[ai][bj][m][n], 0, 0, 0); __builtin_amdgcn_s_setprio(0); } while (0)
; #define PG8_WAIT_V(n) asm volatile("s_waitcnt vmcnt(" #n ")" ::: "memory")
; #define PG8_WAIT_L(n) asm volatile("s_waitcnt lgkmcnt(" #n ")" ::: "memory")
; #define PG8_BAR __builtin_amdgcn_s_barrier()
; #define PG8_SCHED __builtin_amdgcn_sched_barrier(0)
;     __device__ __forceinline__ void operator()(const f32x4 (&acc)[2][2][4][2], const Unit& u, int wr, int wc, int fr, int fq) const {
;         if (u.pn >= 14) { Unit v; v.pm = u.pm; v.pn = u.pn - 14; kv(acc, v, wr, wc, fr, fq); } else win(acc, u, wr, wc, fr, fq);
; template <class Epi, class Sched, bool ALIGN_EPI = true, bool SP2 = true, bool GS = false>
; __device__ __forceinline__ void gemm_phase(PG8_LAS unsigned char* lds, const Gemm g, const Sched& S, const Epi& E, const float* gs_ss = nullptr) {
;     ...
;             PG8_LDA(At, 1, 1); PG8_STAGE(PG8_SB(1, 0), b3, voffB); PG8_STAGE(PG8_SB(1, 1), b3 + hstep, voffB); PG8_STAGE(PG8_SA(1, 0), a3, voffA);
;             PG8_WAIT_V(8); PG8_WAIT_L(0); PG8_BAR; PG8_MMA(1, 0, At, B0); PG8_MMA(1, 1, At, B1); PG8_BAR; PG8_SCHED;
	s_add_i32 s20, s64, s23
	v_lshl_add_u64 v[170:171], v[170:171], 0, s[26:27]
	s_mov_b32 m0, s20
	ds_read_b128 v[196:199], v177 offset:49152
	ds_read_b128 v[200:203], v177 offset:50176
	ds_read_b128 v[204:207], v177 offset:51200
	ds_read_b128 v[208:211], v177 offset:52224
	ds_read_b128 v[212:215], v177 offset:53248
	ds_read_b128 v[216:219], v177 offset:54272
	ds_read_b128 v[236:239], v177 offset:55296
	ds_read_b128 v[240:243], v177 offset:56320
	global_load_lds_dwordx4 v[170:171], off
	s_add_i32 m0, s20, 0x2000
	s_add_u32 s2, s2, 0x80080
	v_lshl_add_u64 v[170:171], v[180:181], 0, s[26:27]
	s_addc_u32 s3, s3, 0
	s_add_i32 s20, s65, s23
	global_load_lds_dwordx4 v[170:171], off
	v_lshl_add_u64 v[170:171], s[2:3], 0, v[136:137]
	s_mov_b32 m0, s20
	s_nop 0
	global_load_lds_dwordx4 v[170:171], off
	v_lshl_add_u64 v[170:171], s[2:3], 0, v[140:141]
	s_add_i32 m0, s20, 0x2000
	s_nop 0
	global_load_lds_dwordx4 v[170:171], off
	v_lshl_add_u64 v[170:171], v[182:183], 0, s[26:27]
	s_mov_b32 m0, s59
	s_nop 0
	global_load_lds_dwordx4 v[170:171], off
	v_lshl_add_u64 v[170:171], v[184:185], 0, s[26:27]
	s_mov_b32 m0, s60
	s_nop 0
	global_load_lds_dwordx4 v[170:171], off
	s_waitcnt vmcnt(8)
	s_waitcnt lgkmcnt(0)
	s_barrier
	s_setprio 1
	s_waitcnt lgkmcnt(0)
	v_mfma_f32_16x16x32_bf16 v[62:65], v[130:133], v[196:199], v[62:65]
	v_mfma_f32_16x16x32_bf16 v[58:61], v[154:157], v[196:199], v[58:61]
	v_mfma_f32_16x16x32_bf16 v[54:57], v[130:133], v[204:207], v[54:57]
	v_mfma_f32_16x16x32_bf16 v[46:49], v[154:157], v[204:207], v[46:49]
	v_mfma_f32_16x16x32_bf16 v[38:41], v[130:133], v[212:215], v[38:41]
	v_mfma_f32_16x16x32_bf16 v[30:33], v[154:157], v[212:215], v[30:33]
	v_mfma_f32_16x16x32_bf16 v[22:25], v[130:133], v[236:239], v[22:25]
	v_mfma_f32_16x16x32_bf16 v[14:17], v[154:157], v[236:239], v[14:17]
	s_setprio 0
	s_setprio 1
	v_mfma_f32_16x16x32_bf16 v[62:65], v[150:153], v[200:203], v[62:65]
	v_mfma_f32_16x16x32_bf16 v[58:61], v[158:161], v[200:203], v[58:61]
	v_mfma_f32_16x16x32_bf16 v[54:57], v[150:153], v[208:211], v[54:57]
	v_mfma_f32_16x16x32_bf16 v[46:49], v[158:161], v[208:211], v[46:49]
	v_mfma_f32_16x16x32_bf16 v[38:41], v[150:153], v[216:219], v[38:41]
	v_mfma_f32_16x16x32_bf16 v[30:33], v[158:161], v[216:219], v[30:33]
	v_mfma_f32_16x16x32_bf16 v[22:25], v[150:153], v[240:243], v[22:25]
	v_mfma_f32_16x16x32_bf16 v[14:17], v[158:161], v[240:243], v[14:17]
	s_setprio 0
	s_setprio 1
	v_mfma_f32_16x16x32_bf16 v[50:53], v[162:165], v[196:199], v[50:53]
	v_mfma_f32_16x16x32_bf16 v[42:45], v[188:191], v[196:199], v[42:45]
	v_mfma_f32_16x16x32_bf16 v[34:37], v[162:165], v[204:207], v[34:37]
	v_mfma_f32_16x16x32_bf16 v[26:29], v[188:191], v[204:207], v[26:29]
	v_mfma_f32_16x16x32_bf16 v[18:21], v[162:165], v[212:215], v[18:21]
	v_mfma_f32_16x16x32_bf16 v[10:13], v[188:191], v[212:215], v[10:13]
	v_mfma_f32_16x16x32_bf16 v[6:9], v[162:165], v[236:239], v[6:9]
	v_mfma_f32_16x16x32_bf16 v[2:5], v[188:191], v[236:239], v[2:5]
	s_setprio 0
	s_setprio 1
	v_mfma_f32_16x16x32_bf16 v[50:53], v[166:169], v[200:203], v[50:53]
	v_mfma_f32_16x16x32_bf16 v[42:45], v[192:195], v[200:203], v[42:45]
	v_mfma_f32_16x16x32_bf16 v[34:37], v[166:169], v[208:211], v[34:37]
	v_mfma_f32_16x16x32_bf16 v[26:29], v[192:195], v[208:211], v[26:29]
	v_mfma_f32_16x16x32_bf16 v[18:21], v[166:169], v[216:219], v[18:21]
	v_mfma_f32_16x16x32_bf16 v[10:13], v[192:195], v[216:219], v[10:13]
	v_mfma_f32_16x16x32_bf16 v[6:9], v[166:169], v[240:243], v[6:9]
	v_mfma_f32_16x16x32_bf16 v[2:5], v[192:195], v[240:243], v[2:5]
	s_setprio 0
	s_barrier
	s_add_i32 s51, s51, 2
	s_add_u32 s38, s38, 0x100
	s_addc_u32 s39, s39, 0
	s_add_u32 s40, s40, 0x100
	s_addc_u32 s41, s41, 0
	s_cmp_gt_u32 s51, 29
	s_cbranch_scc0 .LBB0_314
	s_and_b64 vcc, exec, s[42:43]
	s_cbranch_vccz .LBB0_319
	s_barrier
	s_lshl_b32 s16, s12, 8
	s_cmp_lt_i32 s46, 14
	s_mov_b64 s[2:3], -1
	s_cbranch_scc1 .LBB0_320

;     __device__ bool next(int i, Unit& u) const { const int L = i * G + c; if (L >= 192) return false; u.pm = L / 6; u.pn = L % 6; return true; }
;     __device__ __forceinline__ size_t a_extra(const Unit& u) const { return (size_t)(u.pn >> 1) * ((size_t)T * 512 * 2); }
;     __device__ bool next(int i, Unit& u) const { const int L = i * G + c; if (L >= 256) return false; u.pm = L >> 3; u.pn = L & 7; return true; }
;     __device__ __forceinline__ size_t a_extra(const Unit& u) const { return (size_t)(u.pn >> 1) * 512 * 2; }
;     __device__ __forceinline__ size_t b_extra(const Unit& u) const { return (size_t)(u.pn >> 1) * 512 * 2 - (size_t)(u.pn & ~1) * ((size_t)256 * D * 2); }
; #define PG8_STAGE(bufoff, gbase, voff) do { _Pragma("unroll") for (int _i = 0; _i < 2; ++_i) \
;         __builtin_amdgcn_global_load_lds((const unsigned*)((const char*)(gbase) + (voff)[_i]), (PG8_LAS unsigned*)(lds + (bufoff) + ldsw + _i * 8192), 16, 0, 0); } while (0)
; template <class Epi, class Sched, bool ALIGN_EPI = true, bool SP2 = true, bool GS = false>
; __device__ __forceinline__ void gemm_phase(PG8_LAS unsigned char* lds, const Gemm g, const Sched& S, const Epi& E, const float* gs_ss = nullptr) {
;     ...
;         const bool has_next = S.next(ui + 1, nxt);
;         const char* nA = has_next ? (const char*)g.A + S.a_extra(nxt) + (size_t)nxt.pm * tstep : cA; const char* nB = has_next ? (const char*)g.Bt + S.b_extra(nxt) + (size_t)nxt.pn * tstep : cB;
;         for (int t = 0; t < nt; t += 2) {
;             const bool last = (t == nt - 2);
;             const char* a1 = cA + (size_t)(t + 1) * kstep;
;             const char* a2 = last ? nA : cA + (size_t)(t + 2) * kstep; const char* b2 = last ? nB : cB + (size_t)(t + 2) * kstep;
;             const char* a3 = a2 + kstep; const char* b3 = b2 + kstep;
;             if constexpr (SP2) {
;             PG8_LDB(B0, 0, 0); PG8_LDB(B1, 0, 1); PG8_SCHED; PG8_LDA(At, 0, 0); PG8_STAGE(PG8_SA(1, 1), a1 + hstep, voffA);
;             PG8_WAIT_V(8); PG8_WAIT_L(0); PG8_BAR; PG8_MMA(0, 0, At, B0); PG8_MMA(0, 1, At, B1); PG8_BAR; PG8_SCHED;
;             PG8_LDA(At, 0, 1); PG8_STAGE(PG8_SB(0, 0), b2, voffB); PG8_STAGE(PG8_SB(0, 1), b2 + hstep, voffB); PG8_STAGE(PG8_SA(0, 0), a2, voffA);
;             PG8_WAIT_V(8); PG8_WAIT_L(0); PG8_BAR; PG8_MMA(1, 0, At, B0); PG8_MMA(1, 1, At, B1); PG8_BAR; PG8_SCHED;
.LBB0_788:
	s_add_u32 s2, s34, 0xfffe0080
	s_addc_u32 s3, s35, -1
	s_add_i32 s42, 0, 0x10000
	s_cmp_eq_u32 s41, 4
	s_cselect_b32 s21, s16, s3
	s_cselect_b32 s20, s17, s2
	v_add_u32_e32 v0, s42, v183
	s_cselect_b32 s3, s13, s40
	s_cselect_b32 s2, s18, s29
	s_add_i32 s57, 0, 0x14000
	ds_read_b128 v[18:21], v0
	ds_read_b128 v[26:29], v0 offset:1024
	ds_read_b128 v[30:33], v0 offset:2048
	ds_read_b128 v[38:41], v0 offset:3072
	v_add_u32_e32 v0, s57, v183
	ds_read_b128 v[42:45], v0
	ds_read_b128 v[46:49], v0 offset:1024
	ds_read_b128 v[58:61], v0 offset:2048
	ds_read_b128 v[70:73], v0 offset:3072
	v_lshl_add_u64 v[180:181], s[34:35], 0, v[196:197]
	s_add_i32 m0, s37, 0xc000
	ds_read_b128 v[82:85], v219
	ds_read_b128 v[94:97], v219 offset:1024
	ds_read_b128 v[106:109], v219 offset:2048
	ds_read_b128 v[118:121], v219 offset:3072
	ds_read_b128 v[184:187], v219 offset:4096
	ds_read_b128 v[200:203], v219 offset:5120
	ds_read_b128 v[204:207], v219 offset:6144
	ds_read_b128 v[208:211], v219 offset:7168
	global_load_lds_dwordx4 v[180:181], off
	v_lshl_add_u64 v[180:181], s[34:35], 0, v[198:199]
	s_add_i32 m0, s37, 0xe000
	s_nop 0
	global_load_lds_dwordx4 v[180:181], off
	s_waitcnt vmcnt(8)
	s_waitcnt lgkmcnt(0)
	s_barrier
	s_setprio 1
	s_waitcnt lgkmcnt(0)
	v_mfma_f32_16x16x32_bf16 v[174:177], v[18:21], v[82:85], v[174:177]
	v_mfma_f32_16x16x32_bf16 v[170:173], v[30:33], v[82:85], v[170:173]
	v_mfma_f32_16x16x32_bf16 v[158:161], v[18:21], v[106:109], v[158:161]
	v_mfma_f32_16x16x32_bf16 v[154:157], v[30:33], v[106:109], v[154:157]
	v_mfma_f32_16x16x32_bf16 v[142:145], v[18:21], v[184:187], v[142:145]
	v_mfma_f32_16x16x32_bf16 v[138:141], v[30:33], v[184:187], v[138:141]
	v_mfma_f32_16x16x32_bf16 v[126:129], v[18:21], v[204:207], v[126:129]
	v_mfma_f32_16x16x32_bf16 v[122:125], v[30:33], v[204:207], v[122:125]
	s_setprio 0
	s_setprio 1
	v_mfma_f32_16x16x32_bf16 v[174:177], v[26:29], v[94:97], v[174:177]
	v_mfma_f32_16x16x32_bf16 v[170:173], v[38:41], v[94:97], v[170:173]
	v_mfma_f32_16x16x32_bf16 v[158:161], v[26:29], v[118:121], v[158:161]
	v_mfma_f32_16x16x32_bf16 v[154:157], v[38:41], v[118:121], v[154:157]
	v_mfma_f32_16x16x32_bf16 v[142:145], v[26:29], v[200:203], v[142:145]
	v_mfma_f32_16x16x32_bf16 v[138:141], v[38:41], v[200:203], v[138:141]
	v_mfma_f32_16x16x32_bf16 v[126:129], v[26:29], v[208:211], v[126:129]
	v_mfma_f32_16x16x32_bf16 v[122:125], v[38:41], v[208:211], v[122:125]
	s_setprio 0
	s_setprio 1
	v_mfma_f32_16x16x32_bf16 v[166:169], v[42:45], v[82:85], v[166:169]
	v_mfma_f32_16x16x32_bf16 v[82:85], v[58:61], v[82:85], v[162:165]
	v_mfma_f32_16x16x32_bf16 v[166:169], v[46:49], v[94:97], v[166:169]
	v_mfma_f32_16x16x32_bf16 v[82:85], v[70:73], v[94:97], v[82:85]
	v_mfma_f32_16x16x32_bf16 v[94:97], v[42:45], v[106:109], v[150:153]
	v_mfma_f32_16x16x32_bf16 v[106:109], v[58:61], v[106:109], v[146:149]
	v_mfma_f32_16x16x32_bf16 v[130:133], v[58:61], v[184:187], v[130:133]
	v_mfma_f32_16x16x32_bf16 v[114:117], v[42:45], v[204:207], v[114:117]
	s_setprio 0
	s_setprio 1
	v_mfma_f32_16x16x32_bf16 v[110:113], v[58:61], v[204:207], v[110:113]
	v_mfma_f32_16x16x32_bf16 v[94:97], v[46:49], v[118:121], v[94:97]
	v_mfma_f32_16x16x32_bf16 v[106:109], v[70:73], v[118:121], v[106:109]
	v_mfma_f32_16x16x32_bf16 v[118:121], v[42:45], v[184:187], v[134:137]
	v_mfma_f32_16x16x32_bf16 v[130:133], v[70:73], v[200:203], v[130:133]
	v_mfma_f32_16x16x32_bf16 v[114:117], v[46:49], v[208:211], v[114:117]
	v_mfma_f32_16x16x32_bf16 v[110:113], v[70:73], v[208:211], v[110:113]
	v_mfma_f32_16x16x32_bf16 v[118:121], v[46:49], v[200:203], v[118:121]
	s_setprio 0
	s_barrier
	s_add_i32 s42, s42, s25
	v_lshl_add_u64 v[180:181], s[2:3], 0, v[190:191]
	s_mov_b32 m0, s42
	ds_read_b128 v[134:137], v219 offset:16384
	ds_read_b128 v[146:149], v219 offset:17408
	ds_read_b128 v[150:153], v219 offset:18432
	ds_read_b128 v[162:165], v219 offset:19456
	ds_read_b128 v[184:187], v219 offset:20480
	ds_read_b128 v[200:203], v219 offset:21504
	ds_read_b128 v[204:207], v219 offset:22528
	ds_read_b128 v[208:211], v219 offset:23552
	global_load_lds_dwordx4 v[180:181], off
	s_add_i32 m0, s42, 0x2000
	s_add_u32 s42, s2, 0x20000
	v_lshl_add_u64 v[216:217], s[2:3], 0, v[194:195]
	s_addc_u32 s43, s3, 0
	s_add_i32 s57, s57, s25
	global_load_lds_dwordx4 v[216:217], off
	v_lshl_add_u64 v[212:213], s[42:43], 0, v[190:191]
	s_mov_b32 m0, s57
	v_lshl_add_u64 v[220:221], s[20:21], 0, v[188:189]
	global_load_lds_dwordx4 v[212:213], off
	v_lshl_add_u64 v[212:213], s[42:43], 0, v[194:195]
	s_add_i32 m0, s57, 0x2000
	v_lshl_add_u64 v[244:245], s[20:21], 0, v[192:193]
	global_load_lds_dwordx4 v[212:213], off
	s_mov_b32 m0, s37
	s_nop 0
	global_load_lds_dwordx4 v[220:221], off
	s_mov_b32 m0, s59
	s_nop 0
	global_load_lds_dwordx4 v[244:245], off
	s_waitcnt vmcnt(8)
	s_waitcnt lgkmcnt(0)
	s_barrier
; #define PG8_STAGE(bufoff, gbase, voff) do { _Pragma("unroll") for (int _i = 0; _i < 2; ++_i) \
;         __builtin_amdgcn_global_load_lds((const unsigned*)((const char*)(gbase) + (voff)[_i]), (PG8_LAS unsigned*)(lds + (bufoff) + ldsw + _i * 8192), 16, 0, 0); } while (0)
; #define PG8_LDA(dst, b, h) do { _Pragma("unroll") for (int m = 0; m < 4; ++m) _Pragma("unroll") for (int k = 0; k < 2; ++k) dst[m][k] = *(const PG8_LAS bf16x8*)(lds + PG8_SA(b, h) + aoff + m * 2048 + k * 1024); } while (0)
; #define PG8_LDB(dst, b, h) do { _Pragma("unroll") for (int n = 0; n < 2; ++n) _Pragma("unroll") for (int k = 0; k < 2; ++k) dst[n][k] = *(const PG8_LAS bf16x8*)(lds + PG8_SB(b, h) + boff + n * 2048 + k * 1024); } while (0)
; #define PG8_MMA(ai, bj, At, Bt) do { __builtin_amdgcn_s_setprio(1); _Pragma("unroll") for (int m = 0; m < 4; ++m) _Pragma("unroll") for (int n = 0; n < 2; ++n) _Pragma("unroll") for (int k = 0; k < 2; ++k) \
;         acc[ai][bj][m][n] = __builtin_amdgcn_mfma_f32_16x16x32_bf16(Bt[n][k], At[m][k], acc[ai][bj][m][n], 0, 0, 0); __builtin_amdgcn_s_setprio(0); } while (0)
; #define PG8_WAIT_V(n) asm volatile("s_waitcnt vmcnt(" #n ")" ::: "memory")
; #define PG8_WAIT_L(n) asm volatile("s_waitcnt lgkmcnt(" #n ")" ::: "memory")
; #define PG8_BAR __builtin_amdgcn_s_barrier()
; #define PG8_SCHED __builtin_amdgcn_sched_barrier(0)
; template <class Epi, class Sched, bool ALIGN_EPI = true, bool SP2 = true, bool GS = false>
; __device__ __forceinline__ void gemm_phase(PG8_LAS unsigned char* lds, const Gemm g, const Sched& S, const Epi& E, const float* gs_ss = nullptr) {
;     ...
;             PG8_WAIT_V(8); PG8_WAIT_L(0); PG8_BAR; PG8_MMA(1, 0, At, B0); PG8_MMA(1, 1, At, B1); PG8_BAR; PG8_SCHED;
;             PG8_LDB(B0, 1, 0); PG8_LDB(B1, 1, 1); PG8_SCHED; PG8_LDA(At, 1, 0); PG8_STAGE(PG8_SA(0, 1), a2 + hstep, voffA);
;             PG8_WAIT_V(8); PG8_WAIT_L(0); PG8_BAR; PG8_MMA(0, 0, At, B0); PG8_MMA(0, 1, At, B1); PG8_BAR; PG8_SCHED;
;             PG8_LDA(At, 1, 1); PG8_STAGE(PG8_SB(1, 0), b3, voffB); PG8_STAGE(PG8_SB(1, 1), b3 + hstep, voffB); PG8_STAGE(PG8_SA(1, 0), a3, voffA);
	s_setprio 1
	s_waitcnt lgkmcnt(0)
	v_mfma_f32_16x16x32_bf16 v[102:105], v[18:21], v[134:137], v[102:105]
	v_mfma_f32_16x16x32_bf16 v[98:101], v[30:33], v[134:137], v[98:101]
	v_mfma_f32_16x16x32_bf16 v[78:81], v[18:21], v[150:153], v[78:81]
	v_mfma_f32_16x16x32_bf16 v[74:77], v[30:33], v[150:153], v[74:77]
	v_mfma_f32_16x16x32_bf16 v[54:57], v[18:21], v[184:187], v[54:57]
	v_mfma_f32_16x16x32_bf16 v[50:53], v[30:33], v[184:187], v[50:53]
	v_mfma_f32_16x16x32_bf16 v[14:17], v[18:21], v[204:207], v[14:17]
	v_mfma_f32_16x16x32_bf16 v[10:13], v[30:33], v[204:207], v[10:13]
	s_setprio 0
	s_setprio 1
	v_mfma_f32_16x16x32_bf16 v[102:105], v[26:29], v[146:149], v[102:105]
	v_mfma_f32_16x16x32_bf16 v[98:101], v[38:41], v[146:149], v[98:101]
	v_mfma_f32_16x16x32_bf16 v[78:81], v[26:29], v[162:165], v[78:81]
	v_mfma_f32_16x16x32_bf16 v[74:77], v[38:41], v[162:165], v[74:77]
	v_mfma_f32_16x16x32_bf16 v[54:57], v[26:29], v[200:203], v[54:57]
	v_mfma_f32_16x16x32_bf16 v[50:53], v[38:41], v[200:203], v[50:53]
	v_mfma_f32_16x16x32_bf16 v[14:17], v[26:29], v[208:211], v[14:17]
	v_mfma_f32_16x16x32_bf16 v[10:13], v[38:41], v[208:211], v[10:13]
	s_setprio 0
	s_setprio 1
	v_mfma_f32_16x16x32_bf16 v[34:37], v[42:45], v[184:187], v[34:37]
	v_mfma_f32_16x16x32_bf16 v[22:25], v[58:61], v[184:187], v[22:25]
	v_mfma_f32_16x16x32_bf16 v[6:9], v[42:45], v[204:207], v[6:9]
	v_mfma_f32_16x16x32_bf16 v[2:5], v[58:61], v[204:207], v[2:5]
	v_mfma_f32_16x16x32_bf16 v[18:21], v[42:45], v[134:137], v[90:93]
	v_mfma_f32_16x16x32_bf16 v[26:29], v[58:61], v[134:137], v[86:89]
	v_mfma_f32_16x16x32_bf16 v[30:33], v[42:45], v[150:153], v[66:69]
	v_mfma_f32_16x16x32_bf16 v[38:41], v[58:61], v[150:153], v[62:65]
	s_setprio 0
	s_setprio 1
	v_mfma_f32_16x16x32_bf16 v[34:37], v[46:49], v[200:203], v[34:37]
	v_mfma_f32_16x16x32_bf16 v[22:25], v[70:73], v[200:203], v[22:25]
	v_mfma_f32_16x16x32_bf16 v[6:9], v[46:49], v[208:211], v[6:9]
	v_mfma_f32_16x16x32_bf16 v[2:5], v[70:73], v[208:211], v[2:5]
	v_mfma_f32_16x16x32_bf16 v[18:21], v[46:49], v[146:149], v[18:21]
	v_mfma_f32_16x16x32_bf16 v[26:29], v[70:73], v[146:149], v[26:29]
	v_mfma_f32_16x16x32_bf16 v[30:33], v[46:49], v[162:165], v[30:33]
	v_mfma_f32_16x16x32_bf16 v[38:41], v[70:73], v[162:165], v[38:41]
	s_setprio 0
	s_barrier
	s_add_i32 s42, 0, 0x18000
	v_add_u32_e32 v0, s42, v183
	s_add_i32 s43, 0, 0x1c000
	ds_read_b128 v[42:45], v0
	ds_read_b128 v[46:49], v0 offset:1024
	ds_read_b128 v[58:61], v0 offset:2048
	ds_read_b128 v[62:65], v0 offset:3072
	v_add_u32_e32 v0, s43, v183
	ds_read_b128 v[70:73], v0
	ds_read_b128 v[184:187], v0 offset:1024
	ds_read_b128 v[200:203], v0 offset:2048
	ds_read_b128 v[204:207], v0 offset:3072
	s_add_u32 s20, s20, 0x20000
	s_addc_u32 s21, s21, 0
	s_mov_b32 m0, s69
	v_lshl_add_u64 v[146:147], s[20:21], 0, v[188:189]
	ds_read_b128 v[66:69], v219 offset:32768
	ds_read_b128 v[86:89], v219 offset:33792
	ds_read_b128 v[90:93], v219 offset:34816
	ds_read_b128 v[134:137], v219 offset:35840
	ds_read_b128 v[208:211], v219 offset:36864
	ds_read_b128 v[212:215], v219 offset:37888
	ds_read_b128 v[236:239], v219 offset:38912
	ds_read_b128 v[240:243], v219 offset:39936
	global_load_lds_dwordx4 v[146:147], off
	v_lshl_add_u64 v[146:147], s[20:21], 0, v[192:193]
	s_mov_b32 m0, s64
	s_nop 0
	global_load_lds_dwordx4 v[146:147], off
	s_waitcnt vmcnt(8)
	s_waitcnt lgkmcnt(0)
	s_barrier
	s_setprio 1
	s_waitcnt lgkmcnt(0)
	v_mfma_f32_16x16x32_bf16 v[146:149], v[42:45], v[66:69], v[174:177]
	v_mfma_f32_16x16x32_bf16 v[174:177], v[46:49], v[86:89], v[146:149]
	v_mfma_f32_16x16x32_bf16 v[146:149], v[58:61], v[66:69], v[170:173]
	v_mfma_f32_16x16x32_bf16 v[170:173], v[62:65], v[86:89], v[146:149]
	v_mfma_f32_16x16x32_bf16 v[146:149], v[42:45], v[90:93], v[158:161]
	v_mfma_f32_16x16x32_bf16 v[158:161], v[46:49], v[134:137], v[146:149]
	v_mfma_f32_16x16x32_bf16 v[146:149], v[58:61], v[90:93], v[154:157]
	v_mfma_f32_16x16x32_bf16 v[142:145], v[42:45], v[208:211], v[142:145]
	s_setprio 0
	s_setprio 1
	v_mfma_f32_16x16x32_bf16 v[138:141], v[58:61], v[208:211], v[138:141]
	v_mfma_f32_16x16x32_bf16 v[126:129], v[42:45], v[236:239], v[126:129]
	v_mfma_f32_16x16x32_bf16 v[122:125], v[58:61], v[236:239], v[122:125]
	v_mfma_f32_16x16x32_bf16 v[154:157], v[62:65], v[134:137], v[146:149]
	v_mfma_f32_16x16x32_bf16 v[142:145], v[46:49], v[212:215], v[142:145]
	v_mfma_f32_16x16x32_bf16 v[138:141], v[62:65], v[212:215], v[138:141]
	v_mfma_f32_16x16x32_bf16 v[126:129], v[46:49], v[240:243], v[126:129]
	v_mfma_f32_16x16x32_bf16 v[122:125], v[62:65], v[240:243], v[122:125]
	s_setprio 0
	s_setprio 1
	v_mfma_f32_16x16x32_bf16 v[146:149], v[70:73], v[66:69], v[166:169]
	v_mfma_f32_16x16x32_bf16 v[66:69], v[200:203], v[66:69], v[82:85]
	v_mfma_f32_16x16x32_bf16 v[162:165], v[204:207], v[86:89], v[66:69]
	v_mfma_f32_16x16x32_bf16 v[66:69], v[70:73], v[90:93], v[94:97]
	v_mfma_f32_16x16x32_bf16 v[150:153], v[184:187], v[134:137], v[66:69]
	v_mfma_f32_16x16x32_bf16 v[66:69], v[200:203], v[90:93], v[106:109]
	v_mfma_f32_16x16x32_bf16 v[166:169], v[184:187], v[86:89], v[146:149]
	v_mfma_f32_16x16x32_bf16 v[146:149], v[204:207], v[134:137], v[66:69]
	s_setprio 0
	s_setprio 1
	v_mfma_f32_16x16x32_bf16 v[66:69], v[70:73], v[208:211], v[118:121]
	v_mfma_f32_16x16x32_bf16 v[134:137], v[184:187], v[212:215], v[66:69]
	v_mfma_f32_16x16x32_bf16 v[66:69], v[200:203], v[208:211], v[130:133]
	v_mfma_f32_16x16x32_bf16 v[130:133], v[204:207], v[212:215], v[66:69]
	v_mfma_f32_16x16x32_bf16 v[66:69], v[70:73], v[236:239], v[114:117]
	v_mfma_f32_16x16x32_bf16 v[114:117], v[184:187], v[240:243], v[66:69]
	v_mfma_f32_16x16x32_bf16 v[66:69], v[200:203], v[236:239], v[110:113]
	v_mfma_f32_16x16x32_bf16 v[110:113], v[204:207], v[240:243], v[66:69]
	s_setprio 0
	s_barrier
; #define PG8_STAGE(bufoff, gbase, voff) do { _Pragma("unroll") for (int _i = 0; _i < 2; ++_i) \
;         __builtin_amdgcn_global_load_lds((const unsigned*)((const char*)(gbase) + (voff)[_i]), (PG8_LAS unsigned*)(lds + (bufoff) + ldsw + _i * 8192), 16, 0, 0); } while (0)
; #define PG8_LDA(dst, b, h) do { _Pragma("unroll") for (int m = 0; m < 4; ++m) _Pragma("unroll") for (int k = 0; k < 2; ++k) dst[m][k] = *(const PG8_LAS bf16x8*)(lds + PG8_SA(b, h) + aoff + m * 2048 + k * 1024); } while (0)
; #define PG8_MMA(ai, bj, At, Bt) do { __builtin_amdgcn_s_setprio(1); _Pragma("unroll") for (int m = 0; m < 4; ++m) _Pragma("unroll") for (int n = 0; n < 2; ++n) _Pragma("unroll") for (int k = 0; k < 2; ++k) \
;         acc[ai][bj][m][n] = __builtin_amdgcn_mfma_f32_16x16x32_bf16(Bt[n][k], At[m][k], acc[ai][bj][m][n], 0, 0, 0); __builtin_amdgcn_s_setprio(0); } while (0)
; #define PG8_WAIT_V(n) asm volatile("s_waitcnt vmcnt(" #n ")" ::: "memory")
; #define PG8_WAIT_L(n) asm volatile("s_waitcnt lgkmcnt(" #n ")" ::: "memory")
; #define PG8_BAR __builtin_amdgcn_s_barrier()
; #define PG8_SCHED __builtin_amdgcn_sched_barrier(0)
; template <class Epi, class Sched, bool ALIGN_EPI = true, bool SP2 = true, bool GS = false>
; __device__ __forceinline__ void gemm_phase(PG8_LAS unsigned char* lds, const Gemm g, const Sched& S, const Epi& E, const float* gs_ss = nullptr) {
;     ...
;             PG8_LDA(At, 1, 1); PG8_STAGE(PG8_SB(1, 0), b3, voffB); PG8_STAGE(PG8_SB(1, 1), b3 + hstep, voffB); PG8_STAGE(PG8_SA(1, 0), a3, voffA);
;             PG8_WAIT_V(8); PG8_WAIT_L(0); PG8_BAR; PG8_MMA(1, 0, At, B0); PG8_MMA(1, 1, At, B1); PG8_BAR; PG8_SCHED;
	s_add_i32 s20, s42, s25
	v_lshl_add_u64 v[86:87], v[180:181], 0, s[26:27]
	s_mov_b32 m0, s20
	s_nop 1
	ds_read_b128 v[66:69], v219 offset:49152
	ds_read_b128 v[82:85], v219 offset:50176
	ds_read_b128 v[94:97], v219 offset:51200
	ds_read_b128 v[106:109], v219 offset:52224
	ds_read_b128 v[118:121], v219 offset:53248
	ds_read_b128 v[208:211], v219 offset:54272
	ds_read_b128 v[212:215], v219 offset:55296
	ds_read_b128 v[236:239], v219 offset:56320
	global_load_lds_dwordx4 v[86:87], off
	s_add_i32 m0, s20, 0x2000
	s_add_u32 s2, s2, 0x20080
	v_lshl_add_u64 v[86:87], v[216:217], 0, s[26:27]
	s_addc_u32 s3, s3, 0
	s_add_i32 s20, s43, s25
	global_load_lds_dwordx4 v[86:87], off
	v_lshl_add_u64 v[86:87], s[2:3], 0, v[190:191]
	s_mov_b32 m0, s20
	s_nop 0
	global_load_lds_dwordx4 v[86:87], off
	v_lshl_add_u64 v[86:87], s[2:3], 0, v[194:195]
	s_add_i32 m0, s20, 0x2000
	s_nop 0
	global_load_lds_dwordx4 v[86:87], off
	v_lshl_add_u64 v[86:87], v[220:221], 0, s[26:27]
	s_mov_b32 m0, s30
	s_nop 0
	global_load_lds_dwordx4 v[86:87], off
	v_lshl_add_u64 v[86:87], v[244:245], 0, s[26:27]
	s_mov_b32 m0, s14
	s_nop 0
	global_load_lds_dwordx4 v[86:87], off
	s_waitcnt vmcnt(8)
	s_waitcnt lgkmcnt(0)
	s_barrier
	s_setprio 1
	s_waitcnt lgkmcnt(0)
	v_mfma_f32_16x16x32_bf16 v[86:89], v[42:45], v[66:69], v[102:105]
	v_mfma_f32_16x16x32_bf16 v[102:105], v[46:49], v[82:85], v[86:89]
	v_mfma_f32_16x16x32_bf16 v[86:89], v[58:61], v[66:69], v[98:101]
	v_mfma_f32_16x16x32_bf16 v[78:81], v[42:45], v[94:97], v[78:81]
	v_mfma_f32_16x16x32_bf16 v[74:77], v[58:61], v[94:97], v[74:77]
	v_mfma_f32_16x16x32_bf16 v[54:57], v[42:45], v[118:121], v[54:57]
	v_mfma_f32_16x16x32_bf16 v[50:53], v[58:61], v[118:121], v[50:53]
	v_mfma_f32_16x16x32_bf16 v[14:17], v[42:45], v[212:215], v[14:17]
	s_setprio 0
	s_setprio 1
	v_mfma_f32_16x16x32_bf16 v[10:13], v[58:61], v[212:215], v[10:13]
	v_mfma_f32_16x16x32_bf16 v[98:101], v[62:65], v[82:85], v[86:89]
	v_mfma_f32_16x16x32_bf16 v[78:81], v[46:49], v[106:109], v[78:81]
	v_mfma_f32_16x16x32_bf16 v[74:77], v[62:65], v[106:109], v[74:77]
	v_mfma_f32_16x16x32_bf16 v[54:57], v[46:49], v[208:211], v[54:57]
	v_mfma_f32_16x16x32_bf16 v[50:53], v[62:65], v[208:211], v[50:53]
	v_mfma_f32_16x16x32_bf16 v[14:17], v[46:49], v[236:239], v[14:17]
	v_mfma_f32_16x16x32_bf16 v[10:13], v[62:65], v[236:239], v[10:13]
	s_setprio 0
	s_setprio 1
	v_mfma_f32_16x16x32_bf16 v[18:21], v[70:73], v[66:69], v[18:21]
	v_mfma_f32_16x16x32_bf16 v[90:93], v[184:187], v[82:85], v[18:21]
	v_mfma_f32_16x16x32_bf16 v[18:21], v[200:203], v[66:69], v[26:29]
	v_mfma_f32_16x16x32_bf16 v[86:89], v[204:207], v[82:85], v[18:21]
	v_mfma_f32_16x16x32_bf16 v[18:21], v[70:73], v[94:97], v[30:33]
	v_mfma_f32_16x16x32_bf16 v[66:69], v[184:187], v[106:109], v[18:21]
	v_mfma_f32_16x16x32_bf16 v[18:21], v[200:203], v[94:97], v[38:41]
	v_mfma_f32_16x16x32_bf16 v[62:65], v[204:207], v[106:109], v[18:21]
	s_setprio 0
	s_setprio 1
	v_mfma_f32_16x16x32_bf16 v[18:21], v[70:73], v[118:121], v[34:37]
	v_mfma_f32_16x16x32_bf16 v[34:37], v[184:187], v[208:211], v[18:21]
	v_mfma_f32_16x16x32_bf16 v[18:21], v[200:203], v[118:121], v[22:25]
	v_mfma_f32_16x16x32_bf16 v[6:9], v[70:73], v[212:215], v[6:9]
	v_mfma_f32_16x16x32_bf16 v[2:5], v[200:203], v[212:215], v[2:5]
	v_mfma_f32_16x16x32_bf16 v[22:25], v[204:207], v[208:211], v[18:21]
	v_mfma_f32_16x16x32_bf16 v[6:9], v[184:187], v[236:239], v[6:9]
	v_mfma_f32_16x16x32_bf16 v[2:5], v[204:207], v[236:239], v[2:5]
	s_setprio 0
	s_barrier
	s_add_i32 s41, s41, 2
	s_add_u32 s34, s34, 0x100
	s_addc_u32 s35, s35, 0
	s_add_u32 s29, s29, 0x100
	s_addc_u32 s40, s40, 0
	s_cmp_gt_u32 s41, 5
	s_cbranch_scc0 .LBB0_788
	s_and_b64 vcc, exec, s[54:55]
	s_cbranch_vccz .LBB0_791
	s_barrier

;     __device__ bool next(int i, Unit& u) const { const int L = i * G + c; if (L >= 192) return false; u.pm = L / 6; u.pn = L % 6; return true; }
;     __device__ __forceinline__ size_t a_extra(const Unit& u) const { return (size_t)(u.pn >> 1) * ((size_t)T * 512 * 2); }
;     __device__ bool next(int i, Unit& u) const { const int L = i * G + c; if (L >= 256) return false; u.pm = L >> 3; u.pn = L & 7; return true; }
;     __device__ __forceinline__ size_t a_extra(const Unit& u) const { return (size_t)(u.pn >> 1) * 512 * 2; }
;     __device__ __forceinline__ size_t b_extra(const Unit& u) const { return (size_t)(u.pn >> 1) * 512 * 2 - (size_t)(u.pn & ~1) * ((size_t)256 * D * 2); }
; #define PG8_STAGE(bufoff, gbase, voff) do { _Pragma("unroll") for (int _i = 0; _i < 2; ++_i) \
;         __builtin_amdgcn_global_load_lds((const unsigned*)((const char*)(gbase) + (voff)[_i]), (PG8_LAS unsigned*)(lds + (bufoff) + ldsw + _i * 8192), 16, 0, 0); } while (0)
; template <class Epi, class Sched, bool ALIGN_EPI = true, bool SP2 = true, bool GS = false>
; __device__ __forceinline__ void gemm_phase(PG8_LAS unsigned char* lds, const Gemm g, const Sched& S, const Epi& E, const float* gs_ss = nullptr) {
;     ...
;         const bool has_next = S.next(ui + 1, nxt);
;         const char* nA = has_next ? (const char*)g.A + S.a_extra(nxt) + (size_t)nxt.pm * tstep : cA; const char* nB = has_next ? (const char*)g.Bt + S.b_extra(nxt) + (size_t)nxt.pn * tstep : cB;
;         for (int t = 0; t < nt; t += 2) {
;             const bool last = (t == nt - 2);
;             const char* a1 = cA + (size_t)(t + 1) * kstep;
;             const char* a2 = last ? nA : cA + (size_t)(t + 2) * kstep; const char* b2 = last ? nB : cB + (size_t)(t + 2) * kstep;
;             const char* a3 = a2 + kstep; const char* b3 = b2 + kstep;
;             if constexpr (SP2) {
;             PG8_LDB(B0, 0, 0); PG8_LDB(B1, 0, 1); PG8_SCHED; PG8_LDA(At, 0, 0); PG8_STAGE(PG8_SA(1, 1), a1 + hstep, voffA);
;             PG8_WAIT_V(8); PG8_WAIT_L(0); PG8_BAR; PG8_MMA(0, 0, At, B0); PG8_MMA(0, 1, At, B1); PG8_BAR; PG8_SCHED;
;             PG8_LDA(At, 0, 1); PG8_STAGE(PG8_SB(0, 0), b2, voffB); PG8_STAGE(PG8_SB(0, 1), b2 + hstep, voffB); PG8_STAGE(PG8_SA(0, 0), a2, voffA);
;             PG8_WAIT_V(8); PG8_WAIT_L(0); PG8_BAR; PG8_MMA(1, 0, At, B0); PG8_MMA(1, 1, At, B1); PG8_BAR; PG8_SCHED;
.LBB0_990:
	s_add_i32 s73, s73, 2
	s_add_u32 s2, s60, s62
	s_addc_u32 s3, s61, s63
	s_add_u32 s20, s2, 0x100
	s_addc_u32 s21, s3, 0
	s_add_u32 s74, s71, s62
	s_addc_u32 s75, s72, s63
	s_add_i32 s76, 0, 0x10000
	s_cmpk_eq_i32 s62, 0xf00
	s_cselect_b64 vcc, -1, 0
	s_and_b64 s[2:3], vcc, exec
	s_cselect_b32 s21, s53, s21
	s_cselect_b32 s20, s67, s20
	v_add_u32_e32 v0, s76, v195
	s_cselect_b32 s3, s51, s75
	s_cselect_b32 s2, s70, s74
	s_add_i32 s77, 0, 0x14000
	ds_read_b128 v[154:157], v0
	ds_read_b128 v[158:161], v0 offset:1024
	ds_read_b128 v[162:165], v0 offset:2048
	ds_read_b128 v[166:169], v0 offset:3072
	v_add_u32_e32 v0, s77, v195
	ds_read_b128 v[170:173], v0
	ds_read_b128 v[174:177], v0 offset:1024
	ds_read_b128 v[184:187], v0 offset:2048
	ds_read_b128 v[188:191], v0 offset:3072
	v_lshl_add_u64 v[2:3], v[132:133], 0, s[62:63]
	s_add_i32 m0, s13, 0xc000
	ds_read_b128 v[198:201], v197
	ds_read_b128 v[202:205], v197 offset:1024
	ds_read_b128 v[206:209], v197 offset:2048
	ds_read_b128 v[210:213], v197 offset:3072
	ds_read_b128 v[214:217], v197 offset:4096
	ds_read_b128 v[218:221], v197 offset:5120
	ds_read_b128 v[236:239], v197 offset:6144
	ds_read_b128 v[240:243], v197 offset:7168
	global_load_lds_dwordx4 v[2:3], off
	v_lshl_add_u64 v[2:3], v[134:135], 0, s[62:63]
	s_add_i32 m0, s13, 0xe000
	s_nop 0
	global_load_lds_dwordx4 v[2:3], off
	s_waitcnt vmcnt(8)
	s_waitcnt lgkmcnt(0)
	s_barrier
	s_setprio 1
	s_waitcnt lgkmcnt(0)
	v_mfma_f32_16x16x32_bf16 v[128:131], v[154:157], v[198:201], v[128:131]
	v_mfma_f32_16x16x32_bf16 v[124:127], v[162:165], v[198:201], v[124:127]
	v_mfma_f32_16x16x32_bf16 v[112:115], v[154:157], v[206:209], v[112:115]
	v_mfma_f32_16x16x32_bf16 v[108:111], v[162:165], v[206:209], v[108:111]
	v_mfma_f32_16x16x32_bf16 v[96:99], v[154:157], v[214:217], v[96:99]
	v_mfma_f32_16x16x32_bf16 v[92:95], v[162:165], v[214:217], v[92:95]
	v_mfma_f32_16x16x32_bf16 v[80:83], v[154:157], v[236:239], v[80:83]
	v_mfma_f32_16x16x32_bf16 v[76:79], v[162:165], v[236:239], v[76:79]
	s_setprio 0
	s_setprio 1
	v_mfma_f32_16x16x32_bf16 v[128:131], v[158:161], v[202:205], v[128:131]
	v_mfma_f32_16x16x32_bf16 v[124:127], v[166:169], v[202:205], v[124:127]
	v_mfma_f32_16x16x32_bf16 v[112:115], v[158:161], v[210:213], v[112:115]
	v_mfma_f32_16x16x32_bf16 v[108:111], v[166:169], v[210:213], v[108:111]
	v_mfma_f32_16x16x32_bf16 v[96:99], v[158:161], v[218:221], v[96:99]
	v_mfma_f32_16x16x32_bf16 v[92:95], v[166:169], v[218:221], v[92:95]
	v_mfma_f32_16x16x32_bf16 v[80:83], v[158:161], v[240:243], v[80:83]
	v_mfma_f32_16x16x32_bf16 v[76:79], v[166:169], v[240:243], v[76:79]
	s_setprio 0
	s_setprio 1
	v_mfma_f32_16x16x32_bf16 v[120:123], v[170:173], v[198:201], v[120:123]
	v_mfma_f32_16x16x32_bf16 v[116:119], v[184:187], v[198:201], v[116:119]
	v_mfma_f32_16x16x32_bf16 v[104:107], v[170:173], v[206:209], v[104:107]
	v_mfma_f32_16x16x32_bf16 v[100:103], v[184:187], v[206:209], v[100:103]
	v_mfma_f32_16x16x32_bf16 v[88:91], v[170:173], v[214:217], v[88:91]
	v_mfma_f32_16x16x32_bf16 v[84:87], v[184:187], v[214:217], v[84:87]
	v_mfma_f32_16x16x32_bf16 v[72:75], v[170:173], v[236:239], v[72:75]
	v_mfma_f32_16x16x32_bf16 v[68:71], v[184:187], v[236:239], v[68:71]
	s_setprio 0
	s_setprio 1
	v_mfma_f32_16x16x32_bf16 v[120:123], v[174:177], v[202:205], v[120:123]
	v_mfma_f32_16x16x32_bf16 v[116:119], v[188:191], v[202:205], v[116:119]
	v_mfma_f32_16x16x32_bf16 v[104:107], v[174:177], v[210:213], v[104:107]
	v_mfma_f32_16x16x32_bf16 v[100:103], v[188:191], v[210:213], v[100:103]
	v_mfma_f32_16x16x32_bf16 v[88:91], v[174:177], v[218:221], v[88:91]
	v_mfma_f32_16x16x32_bf16 v[84:87], v[188:191], v[218:221], v[84:87]
	v_mfma_f32_16x16x32_bf16 v[72:75], v[174:177], v[240:243], v[72:75]
	v_mfma_f32_16x16x32_bf16 v[68:71], v[188:191], v[240:243], v[68:71]
	s_setprio 0
	s_barrier
	s_add_i32 s74, s76, s14
	v_lshl_add_u64 v[138:139], s[2:3], 0, v[142:143]
	s_mov_b32 m0, s74
	ds_read_b128 v[198:201], v197 offset:16384
	ds_read_b128 v[202:205], v197 offset:17408
	ds_read_b128 v[206:209], v197 offset:18432
	ds_read_b128 v[210:213], v197 offset:19456
	ds_read_b128 v[214:217], v197 offset:20480
	ds_read_b128 v[218:221], v197 offset:21504
	ds_read_b128 v[236:239], v197 offset:22528
	ds_read_b128 v[240:243], v197 offset:23552
	global_load_lds_dwordx4 v[138:139], off
	s_add_i32 m0, s74, 0x2000
	s_add_u32 s74, s2, 0x80000
	v_lshl_add_u64 v[180:181], s[2:3], 0, v[146:147]
	s_addc_u32 s75, s3, 0
	s_add_i32 s76, s77, s14
	global_load_lds_dwordx4 v[180:181], off
	v_lshl_add_u64 v[2:3], s[74:75], 0, v[142:143]
	s_mov_b32 m0, s76
	v_lshl_add_u64 v[244:245], s[20:21], 0, v[140:141]
	global_load_lds_dwordx4 v[2:3], off
	v_lshl_add_u64 v[2:3], s[74:75], 0, v[146:147]
	s_add_i32 m0, s76, 0x2000
	v_lshl_add_u64 v[246:247], s[20:21], 0, v[144:145]
	global_load_lds_dwordx4 v[2:3], off
	s_mov_b32 m0, s13
	s_nop 0
	global_load_lds_dwordx4 v[244:245], off
	s_mov_b32 m0, s25
	s_nop 0
	global_load_lds_dwordx4 v[246:247], off
	s_waitcnt vmcnt(8)
	s_waitcnt lgkmcnt(0)
	s_barrier
; #define PG8_STAGE(bufoff, gbase, voff) do { _Pragma("unroll") for (int _i = 0; _i < 2; ++_i) \
;         __builtin_amdgcn_global_load_lds((const unsigned*)((const char*)(gbase) + (voff)[_i]), (PG8_LAS unsigned*)(lds + (bufoff) + ldsw + _i * 8192), 16, 0, 0); } while (0)
; #define PG8_LDA(dst, b, h) do { _Pragma("unroll") for (int m = 0; m < 4; ++m) _Pragma("unroll") for (int k = 0; k < 2; ++k) dst[m][k] = *(const PG8_LAS bf16x8*)(lds + PG8_SA(b, h) + aoff + m * 2048 + k * 1024); } while (0)
; #define PG8_LDB(dst, b, h) do { _Pragma("unroll") for (int n = 0; n < 2; ++n) _Pragma("unroll") for (int k = 0; k < 2; ++k) dst[n][k] = *(const PG8_LAS bf16x8*)(lds + PG8_SB(b, h) + boff + n * 2048 + k * 1024); } while (0)
; #define PG8_MMA(ai, bj, At, Bt) do { __builtin_amdgcn_s_setprio(1); _Pragma("unroll") for (int m = 0; m < 4; ++m) _Pragma("unroll") for (int n = 0; n < 2; ++n) _Pragma("unroll") for (int k = 0; k < 2; ++k) \
;         acc[ai][bj][m][n] = __builtin_amdgcn_mfma_f32_16x16x32_bf16(Bt[n][k], At[m][k], acc[ai][bj][m][n], 0, 0, 0); __builtin_amdgcn_s_setprio(0); } while (0)
; #define PG8_WAIT_V(n) asm volatile("s_waitcnt vmcnt(" #n ")" ::: "memory")
; #define PG8_WAIT_L(n) asm volatile("s_waitcnt lgkmcnt(" #n ")" ::: "memory")
; #define PG8_BAR __builtin_amdgcn_s_barrier()
; #define PG8_SCHED __builtin_amdgcn_sched_barrier(0)
; template <class Epi, class Sched, bool ALIGN_EPI = true, bool SP2 = true, bool GS = false>
; __device__ __forceinline__ void gemm_phase(PG8_LAS unsigned char* lds, const Gemm g, const Sched& S, const Epi& E, const float* gs_ss = nullptr) {
;     ...
;             PG8_WAIT_V(8); PG8_WAIT_L(0); PG8_BAR; PG8_MMA(1, 0, At, B0); PG8_MMA(1, 1, At, B1); PG8_BAR; PG8_SCHED;
;             PG8_LDB(B0, 1, 0); PG8_LDB(B1, 1, 1); PG8_SCHED; PG8_LDA(At, 1, 0); PG8_STAGE(PG8_SA(0, 1), a2 + hstep, voffA);
;             PG8_WAIT_V(8); PG8_WAIT_L(0); PG8_BAR; PG8_MMA(0, 0, At, B0); PG8_MMA(0, 1, At, B1); PG8_BAR; PG8_SCHED;
	s_setprio 1
	s_waitcnt lgkmcnt(0)
	v_mfma_f32_16x16x32_bf16 v[64:67], v[154:157], v[198:201], v[64:67]
	v_mfma_f32_16x16x32_bf16 v[60:63], v[162:165], v[198:201], v[60:63]
	v_mfma_f32_16x16x32_bf16 v[48:51], v[154:157], v[206:209], v[48:51]
	v_mfma_f32_16x16x32_bf16 v[44:47], v[162:165], v[206:209], v[44:47]
	v_mfma_f32_16x16x32_bf16 v[32:35], v[154:157], v[214:217], v[32:35]
	v_mfma_f32_16x16x32_bf16 v[28:31], v[162:165], v[214:217], v[28:31]
	v_mfma_f32_16x16x32_bf16 v[16:19], v[154:157], v[236:239], v[16:19]
	v_mfma_f32_16x16x32_bf16 v[12:15], v[162:165], v[236:239], v[12:15]
	s_setprio 0
	s_setprio 1
	v_mfma_f32_16x16x32_bf16 v[64:67], v[158:161], v[202:205], v[64:67]
	v_mfma_f32_16x16x32_bf16 v[60:63], v[166:169], v[202:205], v[60:63]
	v_mfma_f32_16x16x32_bf16 v[48:51], v[158:161], v[210:213], v[48:51]
	v_mfma_f32_16x16x32_bf16 v[44:47], v[166:169], v[210:213], v[44:47]
	v_mfma_f32_16x16x32_bf16 v[32:35], v[158:161], v[218:221], v[32:35]
	v_mfma_f32_16x16x32_bf16 v[28:31], v[166:169], v[218:221], v[28:31]
	v_mfma_f32_16x16x32_bf16 v[16:19], v[158:161], v[240:243], v[16:19]
	v_mfma_f32_16x16x32_bf16 v[12:15], v[166:169], v[240:243], v[12:15]
	s_setprio 0
	s_setprio 1
	v_mfma_f32_16x16x32_bf16 v[56:59], v[170:173], v[198:201], v[56:59]
	v_mfma_f32_16x16x32_bf16 v[52:55], v[184:187], v[198:201], v[52:55]
	v_mfma_f32_16x16x32_bf16 v[40:43], v[170:173], v[206:209], v[40:43]
	v_mfma_f32_16x16x32_bf16 v[36:39], v[184:187], v[206:209], v[36:39]
	v_mfma_f32_16x16x32_bf16 v[24:27], v[170:173], v[214:217], v[24:27]
	v_mfma_f32_16x16x32_bf16 v[20:23], v[184:187], v[214:217], v[20:23]
	v_mfma_f32_16x16x32_bf16 v[8:11], v[170:173], v[236:239], v[8:11]
	v_mfma_f32_16x16x32_bf16 v[2:5], v[184:187], v[236:239], v[4:7]
	s_setprio 0
	s_setprio 1
	v_mfma_f32_16x16x32_bf16 v[56:59], v[174:177], v[202:205], v[56:59]
	v_mfma_f32_16x16x32_bf16 v[52:55], v[188:191], v[202:205], v[52:55]
	v_mfma_f32_16x16x32_bf16 v[40:43], v[174:177], v[210:213], v[40:43]
	v_mfma_f32_16x16x32_bf16 v[36:39], v[188:191], v[210:213], v[36:39]
	v_mfma_f32_16x16x32_bf16 v[24:27], v[174:177], v[218:221], v[24:27]
	v_mfma_f32_16x16x32_bf16 v[20:23], v[188:191], v[218:221], v[20:23]
	v_mfma_f32_16x16x32_bf16 v[8:11], v[174:177], v[240:243], v[8:11]
	v_mfma_f32_16x16x32_bf16 v[2:5], v[188:191], v[240:243], v[2:5]
	s_setprio 0
	s_barrier
	s_add_i32 s74, 0, 0x18000
	v_add_u32_e32 v0, s74, v195
	s_add_i32 s75, 0, 0x1c000
	ds_read_b128 v[154:157], v0
	ds_read_b128 v[158:161], v0 offset:1024
	ds_read_b128 v[162:165], v0 offset:2048
	ds_read_b128 v[166:169], v0 offset:3072
	v_add_u32_e32 v0, s75, v195
	ds_read_b128 v[170:173], v0
	ds_read_b128 v[174:177], v0 offset:1024
	ds_read_b128 v[184:187], v0 offset:2048
	ds_read_b128 v[188:191], v0 offset:3072
	s_add_u32 s20, s20, 0x80000
	s_addc_u32 s21, s21, 0
	s_mov_b32 m0, s30
	v_lshl_add_u64 v[6:7], s[20:21], 0, v[140:141]
	ds_read_b128 v[198:201], v197 offset:32768
	ds_read_b128 v[202:205], v197 offset:33792
	ds_read_b128 v[206:209], v197 offset:34816
	ds_read_b128 v[210:213], v197 offset:35840
	ds_read_b128 v[214:217], v197 offset:36864
	ds_read_b128 v[218:221], v197 offset:37888
	ds_read_b128 v[236:239], v197 offset:38912
	ds_read_b128 v[240:243], v197 offset:39936
	global_load_lds_dwordx4 v[6:7], off
	v_lshl_add_u64 v[6:7], s[20:21], 0, v[144:145]
	s_mov_b32 m0, s36
	s_nop 0
	global_load_lds_dwordx4 v[6:7], off
	s_waitcnt vmcnt(8)
	s_waitcnt lgkmcnt(0)
	s_barrier
	s_setprio 1
	s_waitcnt lgkmcnt(0)
	v_mfma_f32_16x16x32_bf16 v[128:131], v[154:157], v[198:201], v[128:131]
	v_mfma_f32_16x16x32_bf16 v[124:127], v[162:165], v[198:201], v[124:127]
	v_mfma_f32_16x16x32_bf16 v[112:115], v[154:157], v[206:209], v[112:115]
	v_mfma_f32_16x16x32_bf16 v[108:111], v[162:165], v[206:209], v[108:111]
	v_mfma_f32_16x16x32_bf16 v[96:99], v[154:157], v[214:217], v[96:99]
	v_mfma_f32_16x16x32_bf16 v[92:95], v[162:165], v[214:217], v[92:95]
	v_mfma_f32_16x16x32_bf16 v[80:83], v[154:157], v[236:239], v[80:83]
	v_mfma_f32_16x16x32_bf16 v[76:79], v[162:165], v[236:239], v[76:79]
	s_setprio 0
	s_setprio 1
	v_mfma_f32_16x16x32_bf16 v[128:131], v[158:161], v[202:205], v[128:131]
	v_mfma_f32_16x16x32_bf16 v[124:127], v[166:169], v[202:205], v[124:127]
	v_mfma_f32_16x16x32_bf16 v[112:115], v[158:161], v[210:213], v[112:115]
	v_mfma_f32_16x16x32_bf16 v[108:111], v[166:169], v[210:213], v[108:111]
	v_mfma_f32_16x16x32_bf16 v[96:99], v[158:161], v[218:221], v[96:99]
	v_mfma_f32_16x16x32_bf16 v[92:95], v[166:169], v[218:221], v[92:95]
	v_mfma_f32_16x16x32_bf16 v[80:83], v[158:161], v[240:243], v[80:83]
	v_mfma_f32_16x16x32_bf16 v[76:79], v[166:169], v[240:243], v[76:79]
	s_setprio 0
	s_setprio 1
	v_mfma_f32_16x16x32_bf16 v[120:123], v[170:173], v[198:201], v[120:123]
	v_mfma_f32_16x16x32_bf16 v[116:119], v[184:187], v[198:201], v[116:119]
	v_mfma_f32_16x16x32_bf16 v[104:107], v[170:173], v[206:209], v[104:107]
	v_mfma_f32_16x16x32_bf16 v[100:103], v[184:187], v[206:209], v[100:103]
	v_mfma_f32_16x16x32_bf16 v[88:91], v[170:173], v[214:217], v[88:91]
	v_mfma_f32_16x16x32_bf16 v[84:87], v[184:187], v[214:217], v[84:87]
	v_mfma_f32_16x16x32_bf16 v[72:75], v[170:173], v[236:239], v[72:75]
	v_mfma_f32_16x16x32_bf16 v[68:71], v[184:187], v[236:239], v[68:71]
	s_setprio 0
	s_setprio 1
	v_mfma_f32_16x16x32_bf16 v[120:123], v[174:177], v[202:205], v[120:123]
	v_mfma_f32_16x16x32_bf16 v[116:119], v[188:191], v[202:205], v[116:119]
	v_mfma_f32_16x16x32_bf16 v[104:107], v[174:177], v[210:213], v[104:107]
	v_mfma_f32_16x16x32_bf16 v[100:103], v[188:191], v[210:213], v[100:103]
	v_mfma_f32_16x16x32_bf16 v[88:91], v[174:177], v[218:221], v[88:91]
	v_mfma_f32_16x16x32_bf16 v[84:87], v[188:191], v[218:221], v[84:87]
	v_mfma_f32_16x16x32_bf16 v[72:75], v[174:177], v[240:243], v[72:75]
	v_mfma_f32_16x16x32_bf16 v[68:71], v[188:191], v[240:243], v[68:71]
	s_setprio 0
	s_barrier
; #define PG8_STAGE(bufoff, gbase, voff) do { _Pragma("unroll") for (int _i = 0; _i < 2; ++_i) \
;         __builtin_amdgcn_global_load_lds((const unsigned*)((const char*)(gbase) + (voff)[_i]), (PG8_LAS unsigned*)(lds + (bufoff) + ldsw + _i * 8192), 16, 0, 0); } while (0)
; #define PG8_LDA(dst, b, h) do { _Pragma("unroll") for (int m = 0; m < 4; ++m) _Pragma("unroll") for (int k = 0; k < 2; ++k) dst[m][k] = *(const PG8_LAS bf16x8*)(lds + PG8_SA(b, h) + aoff + m * 2048 + k * 1024); } while (0)
; #define PG8_MMA(ai, bj, At, Bt) do { __builtin_amdgcn_s_setprio(1); _Pragma("unroll") for (int m = 0; m < 4; ++m) _Pragma("unroll") for (int n = 0; n < 2; ++n) _Pragma("unroll") for (int k = 0; k < 2; ++k) \
;         acc[ai][bj][m][n] = __builtin_amdgcn_mfma_f32_16x16x32_bf16(Bt[n][k], At[m][k], acc[ai][bj][m][n], 0, 0, 0); __builtin_amdgcn_s_setprio(0); } while (0)
; #define PG8_WAIT_V(n) asm volatile("s_waitcnt vmcnt(" #n ")" ::: "memory")
; #define PG8_WAIT_L(n) asm volatile("s_waitcnt lgkmcnt(" #n ")" ::: "memory")
; #define PG8_BAR __builtin_amdgcn_s_barrier()
; #define PG8_SCHED __builtin_amdgcn_sched_barrier(0)
; template <class Epi, class Sched, bool ALIGN_EPI = true, bool SP2 = true, bool GS = false>
; __device__ __forceinline__ void gemm_phase(PG8_LAS unsigned char* lds, const Gemm g, const Sched& S, const Epi& E, const float* gs_ss = nullptr) {
;     ...
;             PG8_LDA(At, 1, 1); PG8_STAGE(PG8_SB(1, 0), b3, voffB); PG8_STAGE(PG8_SB(1, 1), b3 + hstep, voffB); PG8_STAGE(PG8_SA(1, 0), a3, voffA);
;             PG8_WAIT_V(8); PG8_WAIT_L(0); PG8_BAR; PG8_MMA(1, 0, At, B0); PG8_MMA(1, 1, At, B1); PG8_BAR; PG8_SCHED;
;     ...
;             if constexpr (GS) { if ((t & 7) == 6 && !last) { PG8_GS_SCALE(t >> 3, gpar); } }
	s_add_i32 s20, s74, s14
	v_lshl_add_u64 v[6:7], v[138:139], 0, s[26:27]
	s_mov_b32 m0, s20
	ds_read_b128 v[198:201], v197 offset:49152
	ds_read_b128 v[202:205], v197 offset:50176
	ds_read_b128 v[206:209], v197 offset:51200
	ds_read_b128 v[210:213], v197 offset:52224
	ds_read_b128 v[214:217], v197 offset:53248
	ds_read_b128 v[218:221], v197 offset:54272
	ds_read_b128 v[236:239], v197 offset:55296
	ds_read_b128 v[240:243], v197 offset:56320
	global_load_lds_dwordx4 v[6:7], off
	s_add_i32 m0, s20, 0x2000
	s_add_u32 s2, s2, 0x80080
	v_lshl_add_u64 v[6:7], v[180:181], 0, s[26:27]
	s_addc_u32 s3, s3, 0
	s_add_i32 s20, s75, s14
	global_load_lds_dwordx4 v[6:7], off
	v_lshl_add_u64 v[6:7], s[2:3], 0, v[142:143]
	s_mov_b32 m0, s20
	s_nop 0
	global_load_lds_dwordx4 v[6:7], off
	v_lshl_add_u64 v[6:7], s[2:3], 0, v[146:147]
	s_add_i32 m0, s20, 0x2000
	s_nop 0
	global_load_lds_dwordx4 v[6:7], off
	v_lshl_add_u64 v[6:7], v[244:245], 0, s[26:27]
	s_mov_b32 m0, s59
	s_nop 0
	global_load_lds_dwordx4 v[6:7], off
	v_lshl_add_u64 v[6:7], v[246:247], 0, s[26:27]
	s_mov_b32 m0, s64
	s_nop 0
	global_load_lds_dwordx4 v[6:7], off
	s_waitcnt vmcnt(8)
	s_waitcnt lgkmcnt(0)
	s_barrier
	s_setprio 1
	s_waitcnt lgkmcnt(0)
	v_mfma_f32_16x16x32_bf16 v[64:67], v[154:157], v[198:201], v[64:67]
	v_mfma_f32_16x16x32_bf16 v[60:63], v[162:165], v[198:201], v[60:63]
	v_mfma_f32_16x16x32_bf16 v[48:51], v[154:157], v[206:209], v[48:51]
	v_mfma_f32_16x16x32_bf16 v[44:47], v[162:165], v[206:209], v[44:47]
	v_mfma_f32_16x16x32_bf16 v[32:35], v[154:157], v[214:217], v[32:35]
	v_mfma_f32_16x16x32_bf16 v[28:31], v[162:165], v[214:217], v[28:31]
	v_mfma_f32_16x16x32_bf16 v[16:19], v[154:157], v[236:239], v[16:19]
	v_mfma_f32_16x16x32_bf16 v[12:15], v[162:165], v[236:239], v[12:15]
	s_setprio 0
	s_setprio 1
	v_mfma_f32_16x16x32_bf16 v[64:67], v[158:161], v[202:205], v[64:67]
	v_mfma_f32_16x16x32_bf16 v[60:63], v[166:169], v[202:205], v[60:63]
	v_mfma_f32_16x16x32_bf16 v[48:51], v[158:161], v[210:213], v[48:51]
	v_mfma_f32_16x16x32_bf16 v[44:47], v[166:169], v[210:213], v[44:47]
	v_mfma_f32_16x16x32_bf16 v[32:35], v[158:161], v[218:221], v[32:35]
	v_mfma_f32_16x16x32_bf16 v[28:31], v[166:169], v[218:221], v[28:31]
	v_mfma_f32_16x16x32_bf16 v[16:19], v[158:161], v[240:243], v[16:19]
	v_mfma_f32_16x16x32_bf16 v[12:15], v[166:169], v[240:243], v[12:15]
	s_setprio 0
	s_setprio 1
	v_mfma_f32_16x16x32_bf16 v[56:59], v[170:173], v[198:201], v[56:59]
	v_mfma_f32_16x16x32_bf16 v[52:55], v[184:187], v[198:201], v[52:55]
	v_mfma_f32_16x16x32_bf16 v[40:43], v[170:173], v[206:209], v[40:43]
	v_mfma_f32_16x16x32_bf16 v[36:39], v[184:187], v[206:209], v[36:39]
	v_mfma_f32_16x16x32_bf16 v[24:27], v[170:173], v[214:217], v[24:27]
	v_mfma_f32_16x16x32_bf16 v[20:23], v[184:187], v[214:217], v[20:23]
	v_mfma_f32_16x16x32_bf16 v[6:9], v[170:173], v[236:239], v[8:11]
	v_mfma_f32_16x16x32_bf16 v[2:5], v[184:187], v[236:239], v[2:5]
	s_setprio 0
	s_setprio 1
	v_mfma_f32_16x16x32_bf16 v[56:59], v[174:177], v[202:205], v[56:59]
	v_mfma_f32_16x16x32_bf16 v[52:55], v[188:191], v[202:205], v[52:55]
	v_mfma_f32_16x16x32_bf16 v[40:43], v[174:177], v[210:213], v[40:43]
	v_mfma_f32_16x16x32_bf16 v[36:39], v[188:191], v[210:213], v[36:39]
	v_mfma_f32_16x16x32_bf16 v[24:27], v[174:177], v[218:221], v[24:27]
	v_mfma_f32_16x16x32_bf16 v[20:23], v[188:191], v[218:221], v[20:23]
	v_mfma_f32_16x16x32_bf16 v[8:11], v[174:177], v[240:243], v[6:9]
	v_mfma_f32_16x16x32_bf16 v[4:7], v[188:191], v[240:243], v[2:5]
	s_setprio 0
	s_barrier
	s_and_b32 s2, s73, 6
	s_cmp_lg_u32 s2, 6
	s_cselect_b64 s[2:3], -1, 0
	s_or_b64 s[2:3], vcc, s[2:3]
	s_and_b64 vcc, exec, s[2:3]
	s_cbranch_vccnz .LBB0_989
	s_and_b32 s2, s62, 0xc00
	v_add_u32_e32 v137, s2, v136
	v_add_u32_e32 v154, 0x400, v137
	ds_read2_b32 v[2:3], v137 offset1:16
	ds_read2_b32 v[138:139], v154 offset1:16
	s_waitcnt lgkmcnt(0)
	v_div_scale_f32 v0, s[2:3], v138, v138, v2
	v_rcp_f32_e32 v155, v0
	v_div_scale_f32 v156, vcc, v2, v138, v2
	v_fma_f32 v157, -v0, v155, 1.0
	v_fmac_f32_e32 v155, v157, v155
	v_mul_f32_e32 v157, v156, v155
	v_fma_f32 v158, -v0, v157, v156
	v_fmac_f32_e32 v157, v158, v155
	v_fma_f32 v0, -v0, v157, v156
	v_div_fmas_f32 v0, v0, v155, v157
	v_div_fixup_f32 v0, v0, v138, v2
	v_div_scale_f32 v2, s[2:3], v139, v139, v3
	v_rcp_f32_e32 v138, v2
	v_pk_mul_f32 v[130:131], v[130:131], v[0:1] op_sel_hi:[1,0]
	v_pk_mul_f32 v[128:129], v[128:129], v[0:1] op_sel_hi:[1,0]
	v_pk_mul_f32 v[126:127], v[126:127], v[0:1] op_sel_hi:[1,0]
	v_pk_mul_f32 v[124:125], v[124:125], v[0:1] op_sel_hi:[1,0]
	v_pk_mul_f32 v[122:123], v[122:123], v[0:1] op_sel_hi:[1,0]
	v_pk_mul_f32 v[120:121], v[120:121], v[0:1] op_sel_hi:[1,0]
	v_pk_mul_f32 v[118:119], v[118:119], v[0:1] op_sel_hi:[1,0]
	v_pk_mul_f32 v[116:117], v[116:117], v[0:1] op_sel_hi:[1,0]
	v_fma_f32 v0, -v2, v138, 1.0
	v_fmac_f32_e32 v138, v0, v138
	v_div_scale_f32 v0, vcc, v3, v139, v3
	v_mul_f32_e32 v155, v0, v138
	v_fma_f32 v156, -v2, v155, v0
	v_fmac_f32_e32 v155, v156, v138
	v_fma_f32 v0, -v2, v155, v0
	v_div_fmas_f32 v0, v0, v138, v155
	v_div_fixup_f32 v0, v0, v139, v3
	ds_read2_b32 v[2:3], v137 offset0:32 offset1:48
	ds_read2_b32 v[138:139], v154 offset0:32 offset1:48
	v_pk_mul_f32 v[114:115], v[114:115], v[0:1] op_sel_hi:[1,0]
	v_pk_mul_f32 v[112:113], v[112:113], v[0:1] op_sel_hi:[1,0]
	v_pk_mul_f32 v[110:111], v[110:111], v[0:1] op_sel_hi:[1,0]
	v_pk_mul_f32 v[108:109], v[108:109], v[0:1] op_sel_hi:[1,0]
	s_waitcnt lgkmcnt(0)
	v_div_scale_f32 v155, s[2:3], v138, v138, v2
	v_rcp_f32_e32 v156, v155
	v_pk_mul_f32 v[106:107], v[106:107], v[0:1] op_sel_hi:[1,0]
	v_pk_mul_f32 v[104:105], v[104:105], v[0:1] op_sel_hi:[1,0]
	v_pk_mul_f32 v[102:103], v[102:103], v[0:1] op_sel_hi:[1,0]
	v_pk_mul_f32 v[100:101], v[100:101], v[0:1] op_sel_hi:[1,0]
	v_fma_f32 v0, -v155, v156, 1.0
	v_fmac_f32_e32 v156, v0, v156
	v_div_scale_f32 v0, vcc, v2, v138, v2
	v_mul_f32_e32 v157, v0, v156
	v_fma_f32 v158, -v155, v157, v0
	v_fmac_f32_e32 v157, v158, v156
	v_fma_f32 v0, -v155, v157, v0
	v_div_fmas_f32 v0, v0, v156, v157
	v_div_fixup_f32 v0, v0, v138, v2
	v_div_scale_f32 v2, s[2:3], v139, v139, v3
	v_rcp_f32_e32 v138, v2
	v_pk_mul_f32 v[98:99], v[98:99], v[0:1] op_sel_hi:[1,0]
	v_pk_mul_f32 v[96:97], v[96:97], v[0:1] op_sel_hi:[1,0]
	v_pk_mul_f32 v[94:95], v[94:95], v[0:1] op_sel_hi:[1,0]
	v_pk_mul_f32 v[92:93], v[92:93], v[0:1] op_sel_hi:[1,0]
	v_pk_mul_f32 v[90:91], v[90:91], v[0:1] op_sel_hi:[1,0]
	v_pk_mul_f32 v[88:89], v[88:89], v[0:1] op_sel_hi:[1,0]
	v_pk_mul_f32 v[86:87], v[86:87], v[0:1] op_sel_hi:[1,0]
	v_pk_mul_f32 v[84:85], v[84:85], v[0:1] op_sel_hi:[1,0]
	v_fma_f32 v0, -v2, v138, 1.0
	v_fmac_f32_e32 v138, v0, v138
	v_div_scale_f32 v0, vcc, v3, v139, v3
	v_mul_f32_e32 v155, v0, v138
	v_fma_f32 v156, -v2, v155, v0
	v_fmac_f32_e32 v155, v156, v138
	v_fma_f32 v0, -v2, v155, v0
	v_div_fmas_f32 v0, v0, v138, v155
	v_div_fixup_f32 v0, v0, v139, v3
	ds_read2_b32 v[2:3], v137 offset0:128 offset1:144
	ds_read2_b32 v[138:139], v154 offset0:128 offset1:144
	v_pk_mul_f32 v[82:83], v[82:83], v[0:1] op_sel_hi:[1,0]
	v_pk_mul_f32 v[80:81], v[80:81], v[0:1] op_sel_hi:[1,0]
	v_pk_mul_f32 v[78:79], v[78:79], v[0:1] op_sel_hi:[1,0]
	v_pk_mul_f32 v[76:77], v[76:77], v[0:1] op_sel_hi:[1,0]
	s_waitcnt lgkmcnt(0)
	v_div_scale_f32 v155, s[2:3], v138, v138, v2
	v_rcp_f32_e32 v156, v155
	v_pk_mul_f32 v[74:75], v[74:75], v[0:1] op_sel_hi:[1,0]
	v_pk_mul_f32 v[72:73], v[72:73], v[0:1] op_sel_hi:[1,0]
	v_pk_mul_f32 v[70:71], v[70:71], v[0:1] op_sel_hi:[1,0]
	v_pk_mul_f32 v[68:69], v[68:69], v[0:1] op_sel_hi:[1,0]
	v_fma_f32 v0, -v155, v156, 1.0
	v_fmac_f32_e32 v156, v0, v156
	v_div_scale_f32 v0, vcc, v2, v138, v2
	v_mul_f32_e32 v157, v0, v156
	v_fma_f32 v158, -v155, v157, v0
	v_fmac_f32_e32 v157, v158, v156
	v_fma_f32 v0, -v155, v157, v0
	v_div_fmas_f32 v0, v0, v156, v157
	v_div_fixup_f32 v0, v0, v138, v2
	v_div_scale_f32 v2, s[2:3], v139, v139, v3
	v_rcp_f32_e32 v138, v2
	v_pk_mul_f32 v[66:67], v[66:67], v[0:1] op_sel_hi:[1,0]
	v_pk_mul_f32 v[64:65], v[64:65], v[0:1] op_sel_hi:[1,0]
	v_pk_mul_f32 v[62:63], v[62:63], v[0:1] op_sel_hi:[1,0]
	v_pk_mul_f32 v[60:61], v[60:61], v[0:1] op_sel_hi:[1,0]
	v_pk_mul_f32 v[58:59], v[58:59], v[0:1] op_sel_hi:[1,0]
	v_pk_mul_f32 v[56:57], v[56:57], v[0:1] op_sel_hi:[1,0]
	v_pk_mul_f32 v[54:55], v[54:55], v[0:1] op_sel_hi:[1,0]
	v_pk_mul_f32 v[52:53], v[52:53], v[0:1] op_sel_hi:[1,0]
	v_fma_f32 v0, -v2, v138, 1.0
	v_fmac_f32_e32 v138, v0, v138
	v_div_scale_f32 v0, vcc, v3, v139, v3
	v_mul_f32_e32 v155, v0, v138
	v_fma_f32 v156, -v2, v155, v0
	v_fmac_f32_e32 v155, v156, v138
	v_fma_f32 v0, -v2, v155, v0
	v_div_fmas_f32 v0, v0, v138, v155
	v_div_fixup_f32 v0, v0, v139, v3
	ds_read2_b32 v[2:3], v137 offset0:160 offset1:176
	ds_read2_b32 v[138:139], v154 offset0:160 offset1:176
	v_pk_mul_f32 v[50:51], v[50:51], v[0:1] op_sel_hi:[1,0]
	v_pk_mul_f32 v[48:49], v[48:49], v[0:1] op_sel_hi:[1,0]
	v_pk_mul_f32 v[46:47], v[46:47], v[0:1] op_sel_hi:[1,0]
	v_pk_mul_f32 v[44:45], v[44:45], v[0:1] op_sel_hi:[1,0]
	s_waitcnt lgkmcnt(0)
	v_div_scale_f32 v137, s[2:3], v138, v138, v2
	v_rcp_f32_e32 v154, v137
	v_pk_mul_f32 v[42:43], v[42:43], v[0:1] op_sel_hi:[1,0]
	v_pk_mul_f32 v[40:41], v[40:41], v[0:1] op_sel_hi:[1,0]
	v_pk_mul_f32 v[38:39], v[38:39], v[0:1] op_sel_hi:[1,0]
	v_pk_mul_f32 v[36:37], v[36:37], v[0:1] op_sel_hi:[1,0]
	v_fma_f32 v0, -v137, v154, 1.0
	v_fmac_f32_e32 v154, v0, v154
	v_div_scale_f32 v0, vcc, v2, v138, v2
	v_mul_f32_e32 v155, v0, v154
	v_fma_f32 v156, -v137, v155, v0
	v_fmac_f32_e32 v155, v156, v154
	v_fma_f32 v0, -v137, v155, v0
	v_div_fmas_f32 v0, v0, v154, v155
	v_div_fixup_f32 v0, v0, v138, v2
	v_div_scale_f32 v2, s[2:3], v139, v139, v3
	v_rcp_f32_e32 v137, v2
	v_pk_mul_f32 v[34:35], v[34:35], v[0:1] op_sel_hi:[1,0]
	v_pk_mul_f32 v[32:33], v[32:33], v[0:1] op_sel_hi:[1,0]
	v_pk_mul_f32 v[30:31], v[30:31], v[0:1] op_sel_hi:[1,0]
	v_pk_mul_f32 v[28:29], v[28:29], v[0:1] op_sel_hi:[1,0]
	v_pk_mul_f32 v[26:27], v[26:27], v[0:1] op_sel_hi:[1,0]
	v_pk_mul_f32 v[24:25], v[24:25], v[0:1] op_sel_hi:[1,0]
	v_pk_mul_f32 v[22:23], v[22:23], v[0:1] op_sel_hi:[1,0]
	v_pk_mul_f32 v[20:21], v[20:21], v[0:1] op_sel_hi:[1,0]
	v_fma_f32 v0, -v2, v137, 1.0
	v_fmac_f32_e32 v137, v0, v137
	v_div_scale_f32 v0, vcc, v3, v139, v3
	v_mul_f32_e32 v138, v0, v137
	v_fma_f32 v154, -v2, v138, v0
	v_fmac_f32_e32 v138, v154, v137
	v_fma_f32 v0, -v2, v138, v0
	v_div_fmas_f32 v0, v0, v137, v138
	v_div_fixup_f32 v0, v0, v139, v3
	v_pk_mul_f32 v[18:19], v[18:19], v[0:1] op_sel_hi:[1,0]
	v_pk_mul_f32 v[16:17], v[16:17], v[0:1] op_sel_hi:[1,0]
	v_pk_mul_f32 v[14:15], v[14:15], v[0:1] op_sel_hi:[1,0]
	v_pk_mul_f32 v[12:13], v[12:13], v[0:1] op_sel_hi:[1,0]
	v_pk_mul_f32 v[10:11], v[10:11], v[0:1] op_sel_hi:[1,0]
	v_pk_mul_f32 v[8:9], v[8:9], v[0:1] op_sel_hi:[1,0]
	v_pk_mul_f32 v[6:7], v[6:7], v[0:1] op_sel_hi:[1,0]
	v_pk_mul_f32 v[4:5], v[4:5], v[0:1] op_sel_hi:[1,0]
	s_branch .LBB0_989

;     __device__ bool next(int i, Unit& u) const { const int L = i * G + c; if (L >= 192) return false; u.pm = L / 6; u.pn = L % 6; return true; }
;     __device__ __forceinline__ size_t a_extra(const Unit& u) const { return (size_t)(u.pn >> 1) * ((size_t)T * 512 * 2); }
;     __device__ bool next(int i, Unit& u) const { const int L = i * G + c; if (L >= 256) return false; u.pm = L >> 3; u.pn = L & 7; return true; }
;     __device__ __forceinline__ size_t a_extra(const Unit& u) const { return (size_t)(u.pn >> 1) * 512 * 2; }
;     __device__ __forceinline__ size_t b_extra(const Unit& u) const { return (size_t)(u.pn >> 1) * 512 * 2 - (size_t)(u.pn & ~1) * ((size_t)256 * D * 2); }
; #define PG8_STAGE(bufoff, gbase, voff) do { _Pragma("unroll") for (int _i = 0; _i < 2; ++_i) \
;         __builtin_amdgcn_global_load_lds((const unsigned*)((const char*)(gbase) + (voff)[_i]), (PG8_LAS unsigned*)(lds + (bufoff) + ldsw + _i * 8192), 16, 0, 0); } while (0)
; #define PG8_LDA(dst, b, h) do { _Pragma("unroll") for (int m = 0; m < 4; ++m) _Pragma("unroll") for (int k = 0; k < 2; ++k) dst[m][k] = *(const PG8_LAS bf16x8*)(lds + PG8_SA(b, h) + aoff + m * 2048 + k * 1024); } while (0)
; #define PG8_WAIT_V(n) asm volatile("s_waitcnt vmcnt(" #n ")" ::: "memory")
; template <class Epi, class Sched, bool ALIGN_EPI = true, bool SP2 = true, bool GS = false>
; __device__ __forceinline__ void gemm_phase(PG8_LAS unsigned char* lds, const Gemm g, const Sched& S, const Epi& E, const float* gs_ss = nullptr) {
;     ...
;         const bool has_next = S.next(ui + 1, nxt);
;         const char* nA = has_next ? (const char*)g.A + S.a_extra(nxt) + (size_t)nxt.pm * tstep : cA; const char* nB = has_next ? (const char*)g.Bt + S.b_extra(nxt) + (size_t)nxt.pn * tstep : cB;
;         for (int t = 0; t < nt; t += 2) {
;             const bool last = (t == nt - 2);
;             const char* a1 = cA + (size_t)(t + 1) * kstep;
;             const char* a2 = last ? nA : cA + (size_t)(t + 2) * kstep; const char* b2 = last ? nB : cB + (size_t)(t + 2) * kstep;
;             const char* a3 = a2 + kstep; const char* b3 = b2 + kstep;
;             if constexpr (SP2) {
;             PG8_LDB(B0, 0, 0); PG8_LDB(B1, 0, 1); PG8_SCHED; PG8_LDA(At, 0, 0); PG8_STAGE(PG8_SA(1, 1), a1 + hstep, voffA);
;             PG8_WAIT_V(8); PG8_WAIT_L(0); PG8_BAR; PG8_MMA(0, 0, At, B0); PG8_MMA(0, 1, At, B1); PG8_BAR; PG8_SCHED;
.LBB0_1036:
	s_add_i32 s75, s75, 2
	s_add_u32 s2, s58, s60
	s_addc_u32 s3, s59, s61
	s_add_u32 s20, s2, 0x100
	s_addc_u32 s21, s3, 0
	s_add_u32 vcc_lo, s73, s60
	s_addc_u32 vcc_hi, s74, s61
	s_add_i32 s76, 0, 0x10000
	s_cmpk_eq_i32 s60, 0xf00
	s_cselect_b64 s[62:63], -1, 0
	s_and_b64 s[2:3], s[62:63], exec
	s_cselect_b32 s21, s51, s21
	s_cselect_b32 s20, s71, s20
	v_add_u32_e32 v0, s76, v188
	s_cselect_b32 s3, s49, vcc_hi
	s_cselect_b32 s2, s72, vcc_lo
	s_add_i32 s77, 0, 0x14000
	ds_read_b128 v[138:141], v0
	ds_read_b128 v[142:145], v0 offset:1024
	ds_read_b128 v[162:165], v0 offset:2048
	ds_read_b128 v[166:169], v0 offset:3072
	v_add_u32_e32 v0, s77, v188
	ds_read_b128 v[170:173], v0
	ds_read_b128 v[184:187], v0 offset:1024
	ds_read_b128 v[192:195], v0 offset:2048
	ds_read_b128 v[196:199], v0 offset:3072
	v_lshl_add_u64 v[2:3], v[132:133], 0, s[60:61]
	s_add_i32 m0, s13, 0xc000
	ds_read_b128 v[200:203], v190
	ds_read_b128 v[204:207], v190 offset:1024
	ds_read_b128 v[208:211], v190 offset:2048
	ds_read_b128 v[212:215], v190 offset:3072
	ds_read_b128 v[216:219], v190 offset:4096
	ds_read_b128 v[236:239], v190 offset:5120
	ds_read_b128 v[240:243], v190 offset:6144
	ds_read_b128 v[244:247], v190 offset:7168
	global_load_lds_dwordx4 v[2:3], off
	v_lshl_add_u64 v[2:3], v[134:135], 0, s[60:61]
	s_add_i32 m0, s13, 0xe000
	s_nop 0
	global_load_lds_dwordx4 v[2:3], off
	s_waitcnt vmcnt(8)
	s_waitcnt lgkmcnt(0)
	s_barrier
	s_setprio 1
	s_waitcnt lgkmcnt(0)
	v_mfma_f32_16x16x32_bf16 v[128:131], v[138:141], v[200:203], v[128:131]
	v_mfma_f32_16x16x32_bf16 v[124:127], v[162:165], v[200:203], v[124:127]
	v_mfma_f32_16x16x32_bf16 v[112:115], v[138:141], v[208:211], v[112:115]
	v_mfma_f32_16x16x32_bf16 v[108:111], v[162:165], v[208:211], v[108:111]
	v_mfma_f32_16x16x32_bf16 v[96:99], v[138:141], v[216:219], v[96:99]
	v_mfma_f32_16x16x32_bf16 v[92:95], v[162:165], v[216:219], v[92:95]
	v_mfma_f32_16x16x32_bf16 v[80:83], v[138:141], v[240:243], v[80:83]
	v_mfma_f32_16x16x32_bf16 v[76:79], v[162:165], v[240:243], v[76:79]
	s_setprio 0
	s_setprio 1
	v_mfma_f32_16x16x32_bf16 v[128:131], v[142:145], v[204:207], v[128:131]
	v_mfma_f32_16x16x32_bf16 v[124:127], v[166:169], v[204:207], v[124:127]
	v_mfma_f32_16x16x32_bf16 v[112:115], v[142:145], v[212:215], v[112:115]
	v_mfma_f32_16x16x32_bf16 v[108:111], v[166:169], v[212:215], v[108:111]
	v_mfma_f32_16x16x32_bf16 v[96:99], v[142:145], v[236:239], v[96:99]
	v_mfma_f32_16x16x32_bf16 v[92:95], v[166:169], v[236:239], v[92:95]
	v_mfma_f32_16x16x32_bf16 v[80:83], v[142:145], v[244:247], v[80:83]
	v_mfma_f32_16x16x32_bf16 v[76:79], v[166:169], v[244:247], v[76:79]
	s_setprio 0
	s_setprio 1
	v_mfma_f32_16x16x32_bf16 v[120:123], v[170:173], v[200:203], v[120:123]
	v_mfma_f32_16x16x32_bf16 v[116:119], v[192:195], v[200:203], v[116:119]
	v_mfma_f32_16x16x32_bf16 v[104:107], v[170:173], v[208:211], v[104:107]
	v_mfma_f32_16x16x32_bf16 v[100:103], v[192:195], v[208:211], v[100:103]
	v_mfma_f32_16x16x32_bf16 v[88:91], v[170:173], v[216:219], v[88:91]
	v_mfma_f32_16x16x32_bf16 v[84:87], v[192:195], v[216:219], v[84:87]
	v_mfma_f32_16x16x32_bf16 v[72:75], v[170:173], v[240:243], v[72:75]
	v_mfma_f32_16x16x32_bf16 v[68:71], v[192:195], v[240:243], v[68:71]
	s_setprio 0
	s_setprio 1
	v_mfma_f32_16x16x32_bf16 v[120:123], v[184:187], v[204:207], v[120:123]
	v_mfma_f32_16x16x32_bf16 v[116:119], v[196:199], v[204:207], v[116:119]
	v_mfma_f32_16x16x32_bf16 v[104:107], v[184:187], v[212:215], v[104:107]
	v_mfma_f32_16x16x32_bf16 v[100:103], v[196:199], v[212:215], v[100:103]
	v_mfma_f32_16x16x32_bf16 v[88:91], v[184:187], v[236:239], v[88:91]
	v_mfma_f32_16x16x32_bf16 v[84:87], v[196:199], v[236:239], v[84:87]
	v_mfma_f32_16x16x32_bf16 v[72:75], v[184:187], v[244:247], v[72:75]
	v_mfma_f32_16x16x32_bf16 v[68:71], v[196:199], v[244:247], v[68:71]
	s_setprio 0
	s_barrier
	s_add_i32 s76, s76, s14
	v_lshl_add_u64 v[146:147], s[2:3], 0, v[150:151]
	s_mov_b32 m0, s76
	ds_read_b128 v[200:203], v190 offset:16384
	ds_read_b128 v[204:207], v190 offset:17408
	ds_read_b128 v[208:211], v190 offset:18432
	ds_read_b128 v[212:215], v190 offset:19456
	ds_read_b128 v[216:219], v190 offset:20480
	ds_read_b128 v[236:239], v190 offset:21504
	ds_read_b128 v[240:243], v190 offset:22528
	ds_read_b128 v[244:247], v190 offset:23552
	global_load_lds_dwordx4 v[146:147], off
	s_add_i32 m0, s76, 0x2000
	s_add_u32 vcc_lo, s2, 0x80000
	v_lshl_add_u64 v[174:175], s[2:3], 0, v[154:155]
	s_addc_u32 vcc_hi, s3, 0
	s_add_i32 s76, s77, s14
	global_load_lds_dwordx4 v[174:175], off
	v_lshl_add_u64 v[2:3], vcc, 0, v[150:151]
	s_mov_b32 m0, s76
	v_lshl_add_u64 v[180:181], s[20:21], 0, v[148:149]
	global_load_lds_dwordx4 v[2:3], off
	v_lshl_add_u64 v[2:3], vcc, 0, v[154:155]
	s_add_i32 m0, s76, 0x2000
	v_lshl_add_u64 v[220:221], s[20:21], 0, v[152:153]
	global_load_lds_dwordx4 v[2:3], off
	s_mov_b32 m0, s13
	s_nop 0
	global_load_lds_dwordx4 v[180:181], off
	s_mov_b32 m0, s25
	s_nop 0
	global_load_lds_dwordx4 v[220:221], off
	s_waitcnt vmcnt(8)
	s_waitcnt lgkmcnt(0)
	s_barrier
; #define PG8_STAGE(bufoff, gbase, voff) do { _Pragma("unroll") for (int _i = 0; _i < 2; ++_i) \
;         __builtin_amdgcn_global_load_lds((const unsigned*)((const char*)(gbase) + (voff)[_i]), (PG8_LAS unsigned*)(lds + (bufoff) + ldsw + _i * 8192), 16, 0, 0); } while (0)
; #define PG8_LDA(dst, b, h) do { _Pragma("unroll") for (int m = 0; m < 4; ++m) _Pragma("unroll") for (int k = 0; k < 2; ++k) dst[m][k] = *(const PG8_LAS bf16x8*)(lds + PG8_SA(b, h) + aoff + m * 2048 + k * 1024); } while (0)
; #define PG8_LDB(dst, b, h) do { _Pragma("unroll") for (int n = 0; n < 2; ++n) _Pragma("unroll") for (int k = 0; k < 2; ++k) dst[n][k] = *(const PG8_LAS bf16x8*)(lds + PG8_SB(b, h) + boff + n * 2048 + k * 1024); } while (0)
; #define PG8_MMA(ai, bj, At, Bt) do { __builtin_amdgcn_s_setprio(1); _Pragma("unroll") for (int m = 0; m < 4; ++m) _Pragma("unroll") for (int n = 0; n < 2; ++n) _Pragma("unroll") for (int k = 0; k < 2; ++k) \
;         acc[ai][bj][m][n] = __builtin_amdgcn_mfma_f32_16x16x32_bf16(Bt[n][k], At[m][k], acc[ai][bj][m][n], 0, 0, 0); __builtin_amdgcn_s_setprio(0); } while (0)
; #define PG8_WAIT_V(n) asm volatile("s_waitcnt vmcnt(" #n ")" ::: "memory")
; #define PG8_WAIT_L(n) asm volatile("s_waitcnt lgkmcnt(" #n ")" ::: "memory")
; #define PG8_BAR __builtin_amdgcn_s_barrier()
; #define PG8_SCHED __builtin_amdgcn_sched_barrier(0)
; template <class Epi, class Sched, bool ALIGN_EPI = true, bool SP2 = true, bool GS = false>
; __device__ __forceinline__ void gemm_phase(PG8_LAS unsigned char* lds, const Gemm g, const Sched& S, const Epi& E, const float* gs_ss = nullptr) {
;     ...
;             PG8_WAIT_V(8); PG8_WAIT_L(0); PG8_BAR; PG8_MMA(1, 0, At, B0); PG8_MMA(1, 1, At, B1); PG8_BAR; PG8_SCHED;
;             PG8_LDB(B0, 1, 0); PG8_LDB(B1, 1, 1); PG8_SCHED; PG8_LDA(At, 1, 0); PG8_STAGE(PG8_SA(0, 1), a2 + hstep, voffA);
;             PG8_WAIT_V(8); PG8_WAIT_L(0); PG8_BAR; PG8_MMA(0, 0, At, B0); PG8_MMA(0, 1, At, B1); PG8_BAR; PG8_SCHED;
	s_setprio 1
	s_waitcnt lgkmcnt(0)
	v_mfma_f32_16x16x32_bf16 v[64:67], v[138:141], v[200:203], v[64:67]
	v_mfma_f32_16x16x32_bf16 v[60:63], v[162:165], v[200:203], v[60:63]
	v_mfma_f32_16x16x32_bf16 v[48:51], v[138:141], v[208:211], v[48:51]
	v_mfma_f32_16x16x32_bf16 v[44:47], v[162:165], v[208:211], v[44:47]
	v_mfma_f32_16x16x32_bf16 v[32:35], v[138:141], v[216:219], v[32:35]
	v_mfma_f32_16x16x32_bf16 v[28:31], v[162:165], v[216:219], v[28:31]
	v_mfma_f32_16x16x32_bf16 v[16:19], v[138:141], v[240:243], v[16:19]
	v_mfma_f32_16x16x32_bf16 v[12:15], v[162:165], v[240:243], v[12:15]
	s_setprio 0
	s_setprio 1
	v_mfma_f32_16x16x32_bf16 v[64:67], v[142:145], v[204:207], v[64:67]
	v_mfma_f32_16x16x32_bf16 v[60:63], v[166:169], v[204:207], v[60:63]
	v_mfma_f32_16x16x32_bf16 v[48:51], v[142:145], v[212:215], v[48:51]
	v_mfma_f32_16x16x32_bf16 v[44:47], v[166:169], v[212:215], v[44:47]
	v_mfma_f32_16x16x32_bf16 v[32:35], v[142:145], v[236:239], v[32:35]
	v_mfma_f32_16x16x32_bf16 v[28:31], v[166:169], v[236:239], v[28:31]
	v_mfma_f32_16x16x32_bf16 v[16:19], v[142:145], v[244:247], v[16:19]
	v_mfma_f32_16x16x32_bf16 v[12:15], v[166:169], v[244:247], v[12:15]
	s_setprio 0
	s_setprio 1
	v_mfma_f32_16x16x32_bf16 v[56:59], v[170:173], v[200:203], v[56:59]
	v_mfma_f32_16x16x32_bf16 v[52:55], v[192:195], v[200:203], v[52:55]
	v_mfma_f32_16x16x32_bf16 v[40:43], v[170:173], v[208:211], v[40:43]
	v_mfma_f32_16x16x32_bf16 v[36:39], v[192:195], v[208:211], v[36:39]
	v_mfma_f32_16x16x32_bf16 v[24:27], v[170:173], v[216:219], v[24:27]
	v_mfma_f32_16x16x32_bf16 v[20:23], v[192:195], v[216:219], v[20:23]
	v_mfma_f32_16x16x32_bf16 v[8:11], v[170:173], v[240:243], v[8:11]
	v_mfma_f32_16x16x32_bf16 v[2:5], v[192:195], v[240:243], v[4:7]
	s_setprio 0
	s_setprio 1
	v_mfma_f32_16x16x32_bf16 v[56:59], v[184:187], v[204:207], v[56:59]
	v_mfma_f32_16x16x32_bf16 v[52:55], v[196:199], v[204:207], v[52:55]
	v_mfma_f32_16x16x32_bf16 v[40:43], v[184:187], v[212:215], v[40:43]
	v_mfma_f32_16x16x32_bf16 v[36:39], v[196:199], v[212:215], v[36:39]
	v_mfma_f32_16x16x32_bf16 v[24:27], v[184:187], v[236:239], v[24:27]
	v_mfma_f32_16x16x32_bf16 v[20:23], v[196:199], v[236:239], v[20:23]
	v_mfma_f32_16x16x32_bf16 v[8:11], v[184:187], v[244:247], v[8:11]
	v_mfma_f32_16x16x32_bf16 v[2:5], v[196:199], v[244:247], v[2:5]
	s_setprio 0
	s_barrier
	s_add_i32 s76, 0, 0x18000
	v_add_u32_e32 v0, s76, v188
	s_add_i32 s77, 0, 0x1c000
	ds_read_b128 v[138:141], v0
	ds_read_b128 v[142:145], v0 offset:1024
	ds_read_b128 v[162:165], v0 offset:2048
	ds_read_b128 v[166:169], v0 offset:3072
	v_add_u32_e32 v0, s77, v188
	ds_read_b128 v[170:173], v0
	ds_read_b128 v[184:187], v0 offset:1024
	ds_read_b128 v[192:195], v0 offset:2048
	ds_read_b128 v[196:199], v0 offset:3072
	s_add_u32 s20, s20, 0x80000
	s_addc_u32 s21, s21, 0
	s_mov_b32 m0, s30
	v_lshl_add_u64 v[6:7], s[20:21], 0, v[148:149]
	ds_read_b128 v[200:203], v190 offset:32768
	ds_read_b128 v[204:207], v190 offset:33792
	ds_read_b128 v[208:211], v190 offset:34816
	ds_read_b128 v[212:215], v190 offset:35840
	ds_read_b128 v[216:219], v190 offset:36864
	ds_read_b128 v[236:239], v190 offset:37888
	ds_read_b128 v[240:243], v190 offset:38912
	ds_read_b128 v[244:247], v190 offset:39936
	global_load_lds_dwordx4 v[6:7], off
	v_lshl_add_u64 v[6:7], s[20:21], 0, v[152:153]
	s_mov_b32 m0, s36
	s_nop 0
	global_load_lds_dwordx4 v[6:7], off
	s_waitcnt vmcnt(8)
	s_waitcnt lgkmcnt(0)
	s_barrier
	s_setprio 1
	s_waitcnt lgkmcnt(0)
	v_mfma_f32_16x16x32_bf16 v[128:131], v[138:141], v[200:203], v[128:131]
	v_mfma_f32_16x16x32_bf16 v[124:127], v[162:165], v[200:203], v[124:127]
	v_mfma_f32_16x16x32_bf16 v[112:115], v[138:141], v[208:211], v[112:115]
	v_mfma_f32_16x16x32_bf16 v[108:111], v[162:165], v[208:211], v[108:111]
	v_mfma_f32_16x16x32_bf16 v[96:99], v[138:141], v[216:219], v[96:99]
	v_mfma_f32_16x16x32_bf16 v[92:95], v[162:165], v[216:219], v[92:95]
	v_mfma_f32_16x16x32_bf16 v[80:83], v[138:141], v[240:243], v[80:83]
	v_mfma_f32_16x16x32_bf16 v[76:79], v[162:165], v[240:243], v[76:79]
	s_setprio 0
	s_setprio 1
	v_mfma_f32_16x16x32_bf16 v[128:131], v[142:145], v[204:207], v[128:131]
	v_mfma_f32_16x16x32_bf16 v[124:127], v[166:169], v[204:207], v[124:127]
	v_mfma_f32_16x16x32_bf16 v[112:115], v[142:145], v[212:215], v[112:115]
	v_mfma_f32_16x16x32_bf16 v[108:111], v[166:169], v[212:215], v[108:111]
	v_mfma_f32_16x16x32_bf16 v[96:99], v[142:145], v[236:239], v[96:99]
	v_mfma_f32_16x16x32_bf16 v[92:95], v[166:169], v[236:239], v[92:95]
	v_mfma_f32_16x16x32_bf16 v[80:83], v[142:145], v[244:247], v[80:83]
	v_mfma_f32_16x16x32_bf16 v[76:79], v[166:169], v[244:247], v[76:79]
	s_setprio 0
	s_setprio 1
	v_mfma_f32_16x16x32_bf16 v[120:123], v[170:173], v[200:203], v[120:123]
	v_mfma_f32_16x16x32_bf16 v[116:119], v[192:195], v[200:203], v[116:119]
	v_mfma_f32_16x16x32_bf16 v[104:107], v[170:173], v[208:211], v[104:107]
	v_mfma_f32_16x16x32_bf16 v[100:103], v[192:195], v[208:211], v[100:103]
	v_mfma_f32_16x16x32_bf16 v[88:91], v[170:173], v[216:219], v[88:91]
	v_mfma_f32_16x16x32_bf16 v[84:87], v[192:195], v[216:219], v[84:87]
	v_mfma_f32_16x16x32_bf16 v[72:75], v[170:173], v[240:243], v[72:75]
	v_mfma_f32_16x16x32_bf16 v[68:71], v[192:195], v[240:243], v[68:71]
	s_setprio 0
	s_setprio 1
	v_mfma_f32_16x16x32_bf16 v[120:123], v[184:187], v[204:207], v[120:123]
	v_mfma_f32_16x16x32_bf16 v[116:119], v[196:199], v[204:207], v[116:119]
	v_mfma_f32_16x16x32_bf16 v[104:107], v[184:187], v[212:215], v[104:107]
	v_mfma_f32_16x16x32_bf16 v[100:103], v[196:199], v[212:215], v[100:103]
	v_mfma_f32_16x16x32_bf16 v[88:91], v[184:187], v[236:239], v[88:91]
	v_mfma_f32_16x16x32_bf16 v[84:87], v[196:199], v[236:239], v[84:87]
	v_mfma_f32_16x16x32_bf16 v[72:75], v[184:187], v[244:247], v[72:75]
	v_mfma_f32_16x16x32_bf16 v[68:71], v[196:199], v[244:247], v[68:71]
	s_setprio 0
	s_barrier
; #define PG8_STAGE(bufoff, gbase, voff) do { _Pragma("unroll") for (int _i = 0; _i < 2; ++_i) \
;         __builtin_amdgcn_global_load_lds((const unsigned*)((const char*)(gbase) + (voff)[_i]), (PG8_LAS unsigned*)(lds + (bufoff) + ldsw + _i * 8192), 16, 0, 0); } while (0)
; #define PG8_LDA(dst, b, h) do { _Pragma("unroll") for (int m = 0; m < 4; ++m) _Pragma("unroll") for (int k = 0; k < 2; ++k) dst[m][k] = *(const PG8_LAS bf16x8*)(lds + PG8_SA(b, h) + aoff + m * 2048 + k * 1024); } while (0)
; #define PG8_MMA(ai, bj, At, Bt) do { __builtin_amdgcn_s_setprio(1); _Pragma("unroll") for (int m = 0; m < 4; ++m) _Pragma("unroll") for (int n = 0; n < 2; ++n) _Pragma("unroll") for (int k = 0; k < 2; ++k) \
;         acc[ai][bj][m][n] = __builtin_amdgcn_mfma_f32_16x16x32_bf16(Bt[n][k], At[m][k], acc[ai][bj][m][n], 0, 0, 0); __builtin_amdgcn_s_setprio(0); } while (0)
; #define PG8_WAIT_V(n) asm volatile("s_waitcnt vmcnt(" #n ")" ::: "memory")
; #define PG8_WAIT_L(n) asm volatile("s_waitcnt lgkmcnt(" #n ")" ::: "memory")
; #define PG8_BAR __builtin_amdgcn_s_barrier()
; #define PG8_SCHED __builtin_amdgcn_sched_barrier(0)
; template <class Epi, class Sched, bool ALIGN_EPI = true, bool SP2 = true, bool GS = false>
; __device__ __forceinline__ void gemm_phase(PG8_LAS unsigned char* lds, const Gemm g, const Sched& S, const Epi& E, const float* gs_ss = nullptr) {
;     ...
;             PG8_LDA(At, 1, 1); PG8_STAGE(PG8_SB(1, 0), b3, voffB); PG8_STAGE(PG8_SB(1, 1), b3 + hstep, voffB); PG8_STAGE(PG8_SA(1, 0), a3, voffA);
;             PG8_WAIT_V(8); PG8_WAIT_L(0); PG8_BAR; PG8_MMA(1, 0, At, B0); PG8_MMA(1, 1, At, B1); PG8_BAR; PG8_SCHED;
;     ...
;             if constexpr (GS) { if ((t & 7) == 6 && !last) { PG8_GS_SCALE(t >> 3, gpar); } }
	s_add_i32 s20, s76, s14
	v_lshl_add_u64 v[6:7], v[146:147], 0, s[26:27]
	s_mov_b32 m0, s20
	ds_read_b128 v[200:203], v190 offset:49152
	ds_read_b128 v[204:207], v190 offset:50176
	ds_read_b128 v[208:211], v190 offset:51200
	ds_read_b128 v[212:215], v190 offset:52224
	ds_read_b128 v[216:219], v190 offset:53248
	ds_read_b128 v[236:239], v190 offset:54272
	ds_read_b128 v[240:243], v190 offset:55296
	ds_read_b128 v[244:247], v190 offset:56320
	global_load_lds_dwordx4 v[6:7], off
	s_add_i32 m0, s20, 0x2000
	s_add_u32 s2, s2, 0x80080
	v_lshl_add_u64 v[6:7], v[174:175], 0, s[26:27]
	s_addc_u32 s3, s3, 0
	s_add_i32 s20, s77, s14
	global_load_lds_dwordx4 v[6:7], off
	v_lshl_add_u64 v[6:7], s[2:3], 0, v[150:151]
	s_mov_b32 m0, s20
	s_nop 0
	global_load_lds_dwordx4 v[6:7], off
	v_lshl_add_u64 v[6:7], s[2:3], 0, v[154:155]
	s_add_i32 m0, s20, 0x2000
	s_nop 0
	global_load_lds_dwordx4 v[6:7], off
	v_lshl_add_u64 v[6:7], v[180:181], 0, s[26:27]
	s_mov_b32 m0, s57
	s_nop 0
	global_load_lds_dwordx4 v[6:7], off
	v_lshl_add_u64 v[6:7], v[220:221], 0, s[26:27]
	s_mov_b32 m0, s64
	s_nop 0
	global_load_lds_dwordx4 v[6:7], off
	s_waitcnt vmcnt(8)
	s_waitcnt lgkmcnt(0)
	s_barrier
	s_setprio 1
	s_waitcnt lgkmcnt(0)
	v_mfma_f32_16x16x32_bf16 v[64:67], v[138:141], v[200:203], v[64:67]
	v_mfma_f32_16x16x32_bf16 v[60:63], v[162:165], v[200:203], v[60:63]
	v_mfma_f32_16x16x32_bf16 v[48:51], v[138:141], v[208:211], v[48:51]
	v_mfma_f32_16x16x32_bf16 v[44:47], v[162:165], v[208:211], v[44:47]
	v_mfma_f32_16x16x32_bf16 v[32:35], v[138:141], v[216:219], v[32:35]
	v_mfma_f32_16x16x32_bf16 v[28:31], v[162:165], v[216:219], v[28:31]
	v_mfma_f32_16x16x32_bf16 v[16:19], v[138:141], v[240:243], v[16:19]
	v_mfma_f32_16x16x32_bf16 v[12:15], v[162:165], v[240:243], v[12:15]
	s_setprio 0
	s_setprio 1
	v_mfma_f32_16x16x32_bf16 v[64:67], v[142:145], v[204:207], v[64:67]
	v_mfma_f32_16x16x32_bf16 v[60:63], v[166:169], v[204:207], v[60:63]
	v_mfma_f32_16x16x32_bf16 v[48:51], v[142:145], v[212:215], v[48:51]
	v_mfma_f32_16x16x32_bf16 v[44:47], v[166:169], v[212:215], v[44:47]
	v_mfma_f32_16x16x32_bf16 v[32:35], v[142:145], v[236:239], v[32:35]
	v_mfma_f32_16x16x32_bf16 v[28:31], v[166:169], v[236:239], v[28:31]
	v_mfma_f32_16x16x32_bf16 v[16:19], v[142:145], v[244:247], v[16:19]
	v_mfma_f32_16x16x32_bf16 v[12:15], v[166:169], v[244:247], v[12:15]
	s_setprio 0
	s_setprio 1
	v_mfma_f32_16x16x32_bf16 v[56:59], v[170:173], v[200:203], v[56:59]
	v_mfma_f32_16x16x32_bf16 v[52:55], v[192:195], v[200:203], v[52:55]
	v_mfma_f32_16x16x32_bf16 v[40:43], v[170:173], v[208:211], v[40:43]
	v_mfma_f32_16x16x32_bf16 v[36:39], v[192:195], v[208:211], v[36:39]
	v_mfma_f32_16x16x32_bf16 v[24:27], v[170:173], v[216:219], v[24:27]
	v_mfma_f32_16x16x32_bf16 v[20:23], v[192:195], v[216:219], v[20:23]
	v_mfma_f32_16x16x32_bf16 v[6:9], v[170:173], v[240:243], v[8:11]
	v_mfma_f32_16x16x32_bf16 v[2:5], v[192:195], v[240:243], v[2:5]
	s_setprio 0
	s_setprio 1
	v_mfma_f32_16x16x32_bf16 v[56:59], v[184:187], v[204:207], v[56:59]
	v_mfma_f32_16x16x32_bf16 v[52:55], v[196:199], v[204:207], v[52:55]
	v_mfma_f32_16x16x32_bf16 v[40:43], v[184:187], v[212:215], v[40:43]
	v_mfma_f32_16x16x32_bf16 v[36:39], v[196:199], v[212:215], v[36:39]
	v_mfma_f32_16x16x32_bf16 v[24:27], v[184:187], v[236:239], v[24:27]
	v_mfma_f32_16x16x32_bf16 v[20:23], v[196:199], v[236:239], v[20:23]
	v_mfma_f32_16x16x32_bf16 v[8:11], v[184:187], v[244:247], v[6:9]
	v_mfma_f32_16x16x32_bf16 v[4:7], v[196:199], v[244:247], v[2:5]
	s_setprio 0
	s_barrier
	s_and_b32 s2, s75, 6
	s_cmp_lg_u32 s2, 6
	s_cselect_b64 s[2:3], -1, 0
	s_or_b64 s[2:3], s[62:63], s[2:3]
	s_and_b64 vcc, exec, s[2:3]
	s_cbranch_vccnz .LBB0_1035
	s_and_b32 s2, s60, 0xc00
	v_add_u32_e32 v137, s2, v136
	v_add_u32_e32 v140, 0x400, v137
	ds_read2_b32 v[2:3], v137 offset1:16
	ds_read2_b32 v[138:139], v140 offset1:16
	s_waitcnt lgkmcnt(0)
	v_div_scale_f32 v0, s[2:3], v138, v138, v2
	v_rcp_f32_e32 v141, v0
	v_div_scale_f32 v142, vcc, v2, v138, v2
	v_fma_f32 v143, -v0, v141, 1.0
	v_fmac_f32_e32 v141, v143, v141
	v_mul_f32_e32 v143, v142, v141
	v_fma_f32 v144, -v0, v143, v142
	v_fmac_f32_e32 v143, v144, v141
	v_fma_f32 v0, -v0, v143, v142
	v_div_fmas_f32 v0, v0, v141, v143
	v_div_fixup_f32 v0, v0, v138, v2
	v_div_scale_f32 v2, s[2:3], v139, v139, v3
	v_rcp_f32_e32 v138, v2
	v_pk_mul_f32 v[130:131], v[130:131], v[0:1] op_sel_hi:[1,0]
	v_pk_mul_f32 v[128:129], v[128:129], v[0:1] op_sel_hi:[1,0]
	v_pk_mul_f32 v[126:127], v[126:127], v[0:1] op_sel_hi:[1,0]
	v_pk_mul_f32 v[124:125], v[124:125], v[0:1] op_sel_hi:[1,0]
	v_pk_mul_f32 v[122:123], v[122:123], v[0:1] op_sel_hi:[1,0]
	v_pk_mul_f32 v[120:121], v[120:121], v[0:1] op_sel_hi:[1,0]
	v_pk_mul_f32 v[118:119], v[118:119], v[0:1] op_sel_hi:[1,0]
	v_pk_mul_f32 v[116:117], v[116:117], v[0:1] op_sel_hi:[1,0]
	v_fma_f32 v0, -v2, v138, 1.0
	v_fmac_f32_e32 v138, v0, v138
	v_div_scale_f32 v0, vcc, v3, v139, v3
	v_mul_f32_e32 v141, v0, v138
	v_fma_f32 v142, -v2, v141, v0
	v_fmac_f32_e32 v141, v142, v138
	v_fma_f32 v0, -v2, v141, v0
	v_div_fmas_f32 v0, v0, v138, v141
	v_div_fixup_f32 v0, v0, v139, v3
	ds_read2_b32 v[2:3], v137 offset0:32 offset1:48
	ds_read2_b32 v[138:139], v140 offset0:32 offset1:48
	v_pk_mul_f32 v[114:115], v[114:115], v[0:1] op_sel_hi:[1,0]
	v_pk_mul_f32 v[112:113], v[112:113], v[0:1] op_sel_hi:[1,0]
	v_pk_mul_f32 v[110:111], v[110:111], v[0:1] op_sel_hi:[1,0]
	v_pk_mul_f32 v[108:109], v[108:109], v[0:1] op_sel_hi:[1,0]
	s_waitcnt lgkmcnt(0)
	v_div_scale_f32 v141, s[2:3], v138, v138, v2
	v_rcp_f32_e32 v142, v141
	v_pk_mul_f32 v[106:107], v[106:107], v[0:1] op_sel_hi:[1,0]
	v_pk_mul_f32 v[104:105], v[104:105], v[0:1] op_sel_hi:[1,0]
	v_pk_mul_f32 v[102:103], v[102:103], v[0:1] op_sel_hi:[1,0]
	v_pk_mul_f32 v[100:101], v[100:101], v[0:1] op_sel_hi:[1,0]
	v_fma_f32 v0, -v141, v142, 1.0
	v_fmac_f32_e32 v142, v0, v142
	v_div_scale_f32 v0, vcc, v2, v138, v2
	v_mul_f32_e32 v143, v0, v142
	v_fma_f32 v144, -v141, v143, v0
	v_fmac_f32_e32 v143, v144, v142
	v_fma_f32 v0, -v141, v143, v0
	v_div_fmas_f32 v0, v0, v142, v143
	v_div_fixup_f32 v0, v0, v138, v2
	v_div_scale_f32 v2, s[2:3], v139, v139, v3
	v_rcp_f32_e32 v138, v2
	v_pk_mul_f32 v[98:99], v[98:99], v[0:1] op_sel_hi:[1,0]
	v_pk_mul_f32 v[96:97], v[96:97], v[0:1] op_sel_hi:[1,0]
	v_pk_mul_f32 v[94:95], v[94:95], v[0:1] op_sel_hi:[1,0]
	v_pk_mul_f32 v[92:93], v[92:93], v[0:1] op_sel_hi:[1,0]
	v_pk_mul_f32 v[90:91], v[90:91], v[0:1] op_sel_hi:[1,0]
	v_pk_mul_f32 v[88:89], v[88:89], v[0:1] op_sel_hi:[1,0]
	v_pk_mul_f32 v[86:87], v[86:87], v[0:1] op_sel_hi:[1,0]
	v_pk_mul_f32 v[84:85], v[84:85], v[0:1] op_sel_hi:[1,0]
	v_fma_f32 v0, -v2, v138, 1.0
	v_fmac_f32_e32 v138, v0, v138
	v_div_scale_f32 v0, vcc, v3, v139, v3
	v_mul_f32_e32 v141, v0, v138
	v_fma_f32 v142, -v2, v141, v0
	v_fmac_f32_e32 v141, v142, v138
	v_fma_f32 v0, -v2, v141, v0
	v_div_fmas_f32 v0, v0, v138, v141
	v_div_fixup_f32 v0, v0, v139, v3
	ds_read2_b32 v[2:3], v137 offset0:128 offset1:144
	ds_read2_b32 v[138:139], v140 offset0:128 offset1:144
	v_pk_mul_f32 v[82:83], v[82:83], v[0:1] op_sel_hi:[1,0]
	v_pk_mul_f32 v[80:81], v[80:81], v[0:1] op_sel_hi:[1,0]
	v_pk_mul_f32 v[78:79], v[78:79], v[0:1] op_sel_hi:[1,0]
	v_pk_mul_f32 v[76:77], v[76:77], v[0:1] op_sel_hi:[1,0]
	s_waitcnt lgkmcnt(0)
	v_div_scale_f32 v141, s[2:3], v138, v138, v2
	v_rcp_f32_e32 v142, v141
	v_pk_mul_f32 v[74:75], v[74:75], v[0:1] op_sel_hi:[1,0]
	v_pk_mul_f32 v[72:73], v[72:73], v[0:1] op_sel_hi:[1,0]
	v_pk_mul_f32 v[70:71], v[70:71], v[0:1] op_sel_hi:[1,0]
	v_pk_mul_f32 v[68:69], v[68:69], v[0:1] op_sel_hi:[1,0]
	v_fma_f32 v0, -v141, v142, 1.0
	v_fmac_f32_e32 v142, v0, v142
	v_div_scale_f32 v0, vcc, v2, v138, v2
	v_mul_f32_e32 v143, v0, v142
	v_fma_f32 v144, -v141, v143, v0
	v_fmac_f32_e32 v143, v144, v142
	v_fma_f32 v0, -v141, v143, v0
	v_div_fmas_f32 v0, v0, v142, v143
	v_div_fixup_f32 v0, v0, v138, v2
	v_div_scale_f32 v2, s[2:3], v139, v139, v3
	v_rcp_f32_e32 v138, v2
	v_pk_mul_f32 v[66:67], v[66:67], v[0:1] op_sel_hi:[1,0]
	v_pk_mul_f32 v[64:65], v[64:65], v[0:1] op_sel_hi:[1,0]
	v_pk_mul_f32 v[62:63], v[62:63], v[0:1] op_sel_hi:[1,0]
	v_pk_mul_f32 v[60:61], v[60:61], v[0:1] op_sel_hi:[1,0]
	v_pk_mul_f32 v[58:59], v[58:59], v[0:1] op_sel_hi:[1,0]
	v_pk_mul_f32 v[56:57], v[56:57], v[0:1] op_sel_hi:[1,0]
	v_pk_mul_f32 v[54:55], v[54:55], v[0:1] op_sel_hi:[1,0]
	v_pk_mul_f32 v[52:53], v[52:53], v[0:1] op_sel_hi:[1,0]
	v_fma_f32 v0, -v2, v138, 1.0
	v_fmac_f32_e32 v138, v0, v138
	v_div_scale_f32 v0, vcc, v3, v139, v3
	v_mul_f32_e32 v141, v0, v138
	v_fma_f32 v142, -v2, v141, v0
	v_fmac_f32_e32 v141, v142, v138
	v_fma_f32 v0, -v2, v141, v0
	v_div_fmas_f32 v0, v0, v138, v141
	v_div_fixup_f32 v0, v0, v139, v3
	ds_read2_b32 v[2:3], v137 offset0:160 offset1:176
	ds_read2_b32 v[138:139], v140 offset0:160 offset1:176
	v_pk_mul_f32 v[50:51], v[50:51], v[0:1] op_sel_hi:[1,0]
	v_pk_mul_f32 v[48:49], v[48:49], v[0:1] op_sel_hi:[1,0]
	v_pk_mul_f32 v[46:47], v[46:47], v[0:1] op_sel_hi:[1,0]
	v_pk_mul_f32 v[44:45], v[44:45], v[0:1] op_sel_hi:[1,0]
	s_waitcnt lgkmcnt(0)
	v_div_scale_f32 v137, s[2:3], v138, v138, v2
	v_rcp_f32_e32 v140, v137
	v_pk_mul_f32 v[42:43], v[42:43], v[0:1] op_sel_hi:[1,0]
	v_pk_mul_f32 v[40:41], v[40:41], v[0:1] op_sel_hi:[1,0]
	v_pk_mul_f32 v[38:39], v[38:39], v[0:1] op_sel_hi:[1,0]
	v_pk_mul_f32 v[36:37], v[36:37], v[0:1] op_sel_hi:[1,0]
	v_fma_f32 v0, -v137, v140, 1.0
	v_fmac_f32_e32 v140, v0, v140
	v_div_scale_f32 v0, vcc, v2, v138, v2
	v_mul_f32_e32 v141, v0, v140
	v_fma_f32 v142, -v137, v141, v0
	v_fmac_f32_e32 v141, v142, v140
	v_fma_f32 v0, -v137, v141, v0
	v_div_fmas_f32 v0, v0, v140, v141
	v_div_fixup_f32 v0, v0, v138, v2
	v_div_scale_f32 v2, s[2:3], v139, v139, v3
	v_rcp_f32_e32 v137, v2
	v_pk_mul_f32 v[34:35], v[34:35], v[0:1] op_sel_hi:[1,0]
	v_pk_mul_f32 v[32:33], v[32:33], v[0:1] op_sel_hi:[1,0]
	v_pk_mul_f32 v[30:31], v[30:31], v[0:1] op_sel_hi:[1,0]
	v_pk_mul_f32 v[28:29], v[28:29], v[0:1] op_sel_hi:[1,0]
	v_pk_mul_f32 v[26:27], v[26:27], v[0:1] op_sel_hi:[1,0]
	v_pk_mul_f32 v[24:25], v[24:25], v[0:1] op_sel_hi:[1,0]
	v_pk_mul_f32 v[22:23], v[22:23], v[0:1] op_sel_hi:[1,0]
	v_pk_mul_f32 v[20:21], v[20:21], v[0:1] op_sel_hi:[1,0]
	v_fma_f32 v0, -v2, v137, 1.0
	v_fmac_f32_e32 v137, v0, v137
	v_div_scale_f32 v0, vcc, v3, v139, v3
	v_mul_f32_e32 v138, v0, v137
	v_fma_f32 v140, -v2, v138, v0
	v_fmac_f32_e32 v138, v140, v137
	v_fma_f32 v0, -v2, v138, v0
	v_div_fmas_f32 v0, v0, v137, v138
	v_div_fixup_f32 v0, v0, v139, v3
	v_pk_mul_f32 v[18:19], v[18:19], v[0:1] op_sel_hi:[1,0]
	v_pk_mul_f32 v[16:17], v[16:17], v[0:1] op_sel_hi:[1,0]
	v_pk_mul_f32 v[14:15], v[14:15], v[0:1] op_sel_hi:[1,0]
	v_pk_mul_f32 v[12:13], v[12:13], v[0:1] op_sel_hi:[1,0]
	v_pk_mul_f32 v[10:11], v[10:11], v[0:1] op_sel_hi:[1,0]
	v_pk_mul_f32 v[8:9], v[8:9], v[0:1] op_sel_hi:[1,0]
	v_pk_mul_f32 v[6:7], v[6:7], v[0:1] op_sel_hi:[1,0]
	v_pk_mul_f32 v[4:5], v[4:5], v[0:1] op_sel_hi:[1,0]
	s_branch .LBB0_1035

;     __device__ bool next(int i, Unit& u) const { const int L = i * G + c; if (L >= 192) return false; u.pm = L / 6; u.pn = L % 6; return true; }
;     __device__ __forceinline__ size_t a_extra(const Unit& u) const { return (size_t)(u.pn >> 1) * ((size_t)T * 512 * 2); }
;     __device__ bool next(int i, Unit& u) const { const int L = i * G + c; if (L >= 256) return false; u.pm = L >> 3; u.pn = L & 7; return true; }
;     __device__ __forceinline__ size_t a_extra(const Unit& u) const { return (size_t)(u.pn >> 1) * 512 * 2; }
;     __device__ __forceinline__ size_t b_extra(const Unit& u) const { return (size_t)(u.pn >> 1) * 512 * 2 - (size_t)(u.pn & ~1) * ((size_t)256 * D * 2); }
; #define PG8_STAGE(bufoff, gbase, voff) do { _Pragma("unroll") for (int _i = 0; _i < 2; ++_i) \
;         __builtin_amdgcn_global_load_lds((const unsigned*)((const char*)(gbase) + (voff)[_i]), (PG8_LAS unsigned*)(lds + (bufoff) + ldsw + _i * 8192), 16, 0, 0); } while (0)
; template <class Epi, class Sched, bool ALIGN_EPI = true, bool SP2 = true, bool GS = false>
; __device__ __forceinline__ void gemm_phase(PG8_LAS unsigned char* lds, const Gemm g, const Sched& S, const Epi& E, const float* gs_ss = nullptr) {
;     ...
;         const bool has_next = S.next(ui + 1, nxt);
;         const char* nA = has_next ? (const char*)g.A + S.a_extra(nxt) + (size_t)nxt.pm * tstep : cA; const char* nB = has_next ? (const char*)g.Bt + S.b_extra(nxt) + (size_t)nxt.pn * tstep : cB;
;         for (int t = 0; t < nt; t += 2) {
;             const bool last = (t == nt - 2);
;             const char* a1 = cA + (size_t)(t + 1) * kstep;
;             const char* a2 = last ? nA : cA + (size_t)(t + 2) * kstep; const char* b2 = last ? nB : cB + (size_t)(t + 2) * kstep;
;             const char* a3 = a2 + kstep; const char* b3 = b2 + kstep;
;             if constexpr (SP2) {
;             PG8_LDB(B0, 0, 0); PG8_LDB(B1, 0, 1); PG8_SCHED; PG8_LDA(At, 0, 0); PG8_STAGE(PG8_SA(1, 1), a1 + hstep, voffA);
;             PG8_WAIT_V(8); PG8_WAIT_L(0); PG8_BAR; PG8_MMA(0, 0, At, B0); PG8_MMA(0, 1, At, B1); PG8_BAR; PG8_SCHED;
;             PG8_LDA(At, 0, 1); PG8_STAGE(PG8_SB(0, 0), b2, voffB); PG8_STAGE(PG8_SB(0, 1), b2 + hstep, voffB); PG8_STAGE(PG8_SA(0, 0), a2, voffA);
;             PG8_WAIT_V(8); PG8_WAIT_L(0); PG8_BAR; PG8_MMA(1, 0, At, B0); PG8_MMA(1, 1, At, B1); PG8_BAR; PG8_SCHED;
.LBB0_1119:
	s_add_u32 s2, s44, 0xfff80080
	s_addc_u32 s3, s45, -1
	s_add_i32 s59, 0, 0x10000
	s_cmp_eq_u32 s58, 4
	s_cselect_b32 s21, s52, s3
	s_cselect_b32 s20, s53, s2
	v_add_u32_e32 v0, s59, v145
	s_cselect_b32 s3, s54, s57
	s_cselect_b32 s2, s55, s56
	s_add_i32 s62, 0, 0x14000
	ds_read_b128 v[148:151], v0
	ds_read_b128 v[152:155], v0 offset:1024
	ds_read_b128 v[156:159], v0 offset:2048
	ds_read_b128 v[160:163], v0 offset:3072
	v_add_u32_e32 v0, s62, v145
	ds_read_b128 v[164:167], v0
	ds_read_b128 v[168:171], v0 offset:1024
	ds_read_b128 v[172:175], v0 offset:2048
	ds_read_b128 v[180:183], v0 offset:3072
	v_lshl_add_u64 v[142:143], s[44:45], 0, v[138:139]
	s_add_i32 m0, s9, 0xc000
	ds_read_b128 v[184:187], v147
	ds_read_b128 v[188:191], v147 offset:1024
	ds_read_b128 v[192:195], v147 offset:2048
	ds_read_b128 v[196:199], v147 offset:3072
	ds_read_b128 v[200:203], v147 offset:4096
	ds_read_b128 v[204:207], v147 offset:5120
	ds_read_b128 v[208:211], v147 offset:6144
	ds_read_b128 v[212:215], v147 offset:7168
	global_load_lds_dwordx4 v[142:143], off
	v_lshl_add_u64 v[142:143], s[44:45], 0, v[140:141]
	s_add_i32 m0, s9, 0xe000
	s_nop 0
	global_load_lds_dwordx4 v[142:143], off
	s_waitcnt vmcnt(8)
	s_waitcnt lgkmcnt(0)
	s_barrier
	s_setprio 1
	s_waitcnt lgkmcnt(0)
	v_mfma_f32_16x16x32_bf16 v[126:129], v[148:151], v[184:187], v[126:129]
	v_mfma_f32_16x16x32_bf16 v[122:125], v[156:159], v[184:187], v[122:125]
	v_mfma_f32_16x16x32_bf16 v[118:121], v[148:151], v[192:195], v[118:121]
	v_mfma_f32_16x16x32_bf16 v[110:113], v[156:159], v[192:195], v[110:113]
	v_mfma_f32_16x16x32_bf16 v[102:105], v[148:151], v[200:203], v[102:105]
	v_mfma_f32_16x16x32_bf16 v[94:97], v[156:159], v[200:203], v[94:97]
	v_mfma_f32_16x16x32_bf16 v[86:89], v[148:151], v[208:211], v[86:89]
	v_mfma_f32_16x16x32_bf16 v[78:81], v[156:159], v[208:211], v[78:81]
	s_setprio 0
	s_setprio 1
	v_mfma_f32_16x16x32_bf16 v[126:129], v[152:155], v[188:191], v[126:129]
	v_mfma_f32_16x16x32_bf16 v[122:125], v[160:163], v[188:191], v[122:125]
	v_mfma_f32_16x16x32_bf16 v[118:121], v[152:155], v[196:199], v[118:121]
	v_mfma_f32_16x16x32_bf16 v[110:113], v[160:163], v[196:199], v[110:113]
	v_mfma_f32_16x16x32_bf16 v[102:105], v[152:155], v[204:207], v[102:105]
	v_mfma_f32_16x16x32_bf16 v[94:97], v[160:163], v[204:207], v[94:97]
	v_mfma_f32_16x16x32_bf16 v[86:89], v[152:155], v[212:215], v[86:89]
	v_mfma_f32_16x16x32_bf16 v[78:81], v[160:163], v[212:215], v[78:81]
	s_setprio 0
	s_setprio 1
	v_mfma_f32_16x16x32_bf16 v[114:117], v[164:167], v[184:187], v[114:117]
	v_mfma_f32_16x16x32_bf16 v[106:109], v[172:175], v[184:187], v[106:109]
	v_mfma_f32_16x16x32_bf16 v[98:101], v[164:167], v[192:195], v[98:101]
	v_mfma_f32_16x16x32_bf16 v[90:93], v[172:175], v[192:195], v[90:93]
	v_mfma_f32_16x16x32_bf16 v[82:85], v[164:167], v[200:203], v[82:85]
	v_mfma_f32_16x16x32_bf16 v[74:77], v[172:175], v[200:203], v[74:77]
	v_mfma_f32_16x16x32_bf16 v[70:73], v[164:167], v[208:211], v[70:73]
	v_mfma_f32_16x16x32_bf16 v[66:69], v[172:175], v[208:211], v[66:69]
	s_setprio 0
	s_setprio 1
	v_mfma_f32_16x16x32_bf16 v[114:117], v[168:171], v[188:191], v[114:117]
	v_mfma_f32_16x16x32_bf16 v[106:109], v[180:183], v[188:191], v[106:109]
	v_mfma_f32_16x16x32_bf16 v[98:101], v[168:171], v[196:199], v[98:101]
	v_mfma_f32_16x16x32_bf16 v[90:93], v[180:183], v[196:199], v[90:93]
	v_mfma_f32_16x16x32_bf16 v[82:85], v[168:171], v[204:207], v[82:85]
	v_mfma_f32_16x16x32_bf16 v[74:77], v[180:183], v[204:207], v[74:77]
	v_mfma_f32_16x16x32_bf16 v[70:73], v[168:171], v[212:215], v[70:73]
	v_mfma_f32_16x16x32_bf16 v[66:69], v[180:183], v[212:215], v[66:69]
	s_setprio 0
	s_barrier
	s_add_i32 s59, s59, s23
	v_lshl_add_u64 v[142:143], s[2:3], 0, v[134:135]
	s_mov_b32 m0, s59
	ds_read_b128 v[184:187], v147 offset:16384
	ds_read_b128 v[188:191], v147 offset:17408
	ds_read_b128 v[192:195], v147 offset:18432
	ds_read_b128 v[196:199], v147 offset:19456
	ds_read_b128 v[200:203], v147 offset:20480
	ds_read_b128 v[204:207], v147 offset:21504
	ds_read_b128 v[208:211], v147 offset:22528
	ds_read_b128 v[212:215], v147 offset:23552
	global_load_lds_dwordx4 v[142:143], off
	s_add_i32 m0, s59, 0x2000
	s_add_u32 s60, s2, 0x80000
	v_lshl_add_u64 v[176:177], s[2:3], 0, v[130:131]
	s_addc_u32 s61, s3, 0
	s_add_i32 s59, s62, s23
	global_load_lds_dwordx4 v[176:177], off
	v_lshl_add_u64 v[216:217], s[60:61], 0, v[134:135]
	s_mov_b32 m0, s59
	v_lshl_add_u64 v[218:219], s[20:21], 0, v[132:133]
	global_load_lds_dwordx4 v[216:217], off
	v_lshl_add_u64 v[216:217], s[60:61], 0, v[130:131]
	s_add_i32 m0, s59, 0x2000
	s_nop 0
	global_load_lds_dwordx4 v[216:217], off
	v_lshl_add_u64 v[216:217], s[20:21], 0, v[136:137]
	s_mov_b32 m0, s9
	s_nop 0
	global_load_lds_dwordx4 v[216:217], off
	s_mov_b32 m0, s25
	s_nop 0
	global_load_lds_dwordx4 v[218:219], off
	s_waitcnt vmcnt(8)
	s_waitcnt lgkmcnt(0)
	s_barrier
; #define PG8_STAGE(bufoff, gbase, voff) do { _Pragma("unroll") for (int _i = 0; _i < 2; ++_i) \
;         __builtin_amdgcn_global_load_lds((const unsigned*)((const char*)(gbase) + (voff)[_i]), (PG8_LAS unsigned*)(lds + (bufoff) + ldsw + _i * 8192), 16, 0, 0); } while (0)
; #define PG8_LDA(dst, b, h) do { _Pragma("unroll") for (int m = 0; m < 4; ++m) _Pragma("unroll") for (int k = 0; k < 2; ++k) dst[m][k] = *(const PG8_LAS bf16x8*)(lds + PG8_SA(b, h) + aoff + m * 2048 + k * 1024); } while (0)
; #define PG8_LDB(dst, b, h) do { _Pragma("unroll") for (int n = 0; n < 2; ++n) _Pragma("unroll") for (int k = 0; k < 2; ++k) dst[n][k] = *(const PG8_LAS bf16x8*)(lds + PG8_SB(b, h) + boff + n * 2048 + k * 1024); } while (0)
; #define PG8_MMA(ai, bj, At, Bt) do { __builtin_amdgcn_s_setprio(1); _Pragma("unroll") for (int m = 0; m < 4; ++m) _Pragma("unroll") for (int n = 0; n < 2; ++n) _Pragma("unroll") for (int k = 0; k < 2; ++k) \
;         acc[ai][bj][m][n] = __builtin_amdgcn_mfma_f32_16x16x32_bf16(Bt[n][k], At[m][k], acc[ai][bj][m][n], 0, 0, 0); __builtin_amdgcn_s_setprio(0); } while (0)
; #define PG8_WAIT_V(n) asm volatile("s_waitcnt vmcnt(" #n ")" ::: "memory")
; #define PG8_WAIT_L(n) asm volatile("s_waitcnt lgkmcnt(" #n ")" ::: "memory")
; #define PG8_BAR __builtin_amdgcn_s_barrier()
; #define PG8_SCHED __builtin_amdgcn_sched_barrier(0)
; template <class Epi, class Sched, bool ALIGN_EPI = true, bool SP2 = true, bool GS = false>
; __device__ __forceinline__ void gemm_phase(PG8_LAS unsigned char* lds, const Gemm g, const Sched& S, const Epi& E, const float* gs_ss = nullptr) {
;     ...
;             PG8_WAIT_V(8); PG8_WAIT_L(0); PG8_BAR; PG8_MMA(1, 0, At, B0); PG8_MMA(1, 1, At, B1); PG8_BAR; PG8_SCHED;
;             PG8_LDB(B0, 1, 0); PG8_LDB(B1, 1, 1); PG8_SCHED; PG8_LDA(At, 1, 0); PG8_STAGE(PG8_SA(0, 1), a2 + hstep, voffA);
;             PG8_WAIT_V(8); PG8_WAIT_L(0); PG8_BAR; PG8_MMA(0, 0, At, B0); PG8_MMA(0, 1, At, B1); PG8_BAR; PG8_SCHED;
	s_setprio 1
	s_waitcnt lgkmcnt(0)
	v_mfma_f32_16x16x32_bf16 v[62:65], v[148:151], v[184:187], v[62:65]
	v_mfma_f32_16x16x32_bf16 v[58:61], v[156:159], v[184:187], v[58:61]
	v_mfma_f32_16x16x32_bf16 v[54:57], v[148:151], v[192:195], v[54:57]
	v_mfma_f32_16x16x32_bf16 v[46:49], v[156:159], v[192:195], v[46:49]
	v_mfma_f32_16x16x32_bf16 v[38:41], v[148:151], v[200:203], v[38:41]
	v_mfma_f32_16x16x32_bf16 v[30:33], v[156:159], v[200:203], v[30:33]
	v_mfma_f32_16x16x32_bf16 v[22:25], v[148:151], v[208:211], v[22:25]
	v_mfma_f32_16x16x32_bf16 v[14:17], v[156:159], v[208:211], v[14:17]
	s_setprio 0
	s_setprio 1
	v_mfma_f32_16x16x32_bf16 v[62:65], v[152:155], v[188:191], v[62:65]
	v_mfma_f32_16x16x32_bf16 v[58:61], v[160:163], v[188:191], v[58:61]
	v_mfma_f32_16x16x32_bf16 v[54:57], v[152:155], v[196:199], v[54:57]
	v_mfma_f32_16x16x32_bf16 v[46:49], v[160:163], v[196:199], v[46:49]
	v_mfma_f32_16x16x32_bf16 v[38:41], v[152:155], v[204:207], v[38:41]
	v_mfma_f32_16x16x32_bf16 v[30:33], v[160:163], v[204:207], v[30:33]
	v_mfma_f32_16x16x32_bf16 v[22:25], v[152:155], v[212:215], v[22:25]
	v_mfma_f32_16x16x32_bf16 v[14:17], v[160:163], v[212:215], v[14:17]
	s_setprio 0
	s_setprio 1
	v_mfma_f32_16x16x32_bf16 v[50:53], v[164:167], v[184:187], v[50:53]
	v_mfma_f32_16x16x32_bf16 v[42:45], v[172:175], v[184:187], v[42:45]
	v_mfma_f32_16x16x32_bf16 v[34:37], v[164:167], v[192:195], v[34:37]
	v_mfma_f32_16x16x32_bf16 v[26:29], v[172:175], v[192:195], v[26:29]
	v_mfma_f32_16x16x32_bf16 v[18:21], v[164:167], v[200:203], v[18:21]
	v_mfma_f32_16x16x32_bf16 v[10:13], v[172:175], v[200:203], v[10:13]
	v_mfma_f32_16x16x32_bf16 v[6:9], v[164:167], v[208:211], v[6:9]
	v_mfma_f32_16x16x32_bf16 v[2:5], v[172:175], v[208:211], v[2:5]
	s_setprio 0
	s_setprio 1
	v_mfma_f32_16x16x32_bf16 v[50:53], v[168:171], v[188:191], v[50:53]
	v_mfma_f32_16x16x32_bf16 v[42:45], v[180:183], v[188:191], v[42:45]
	v_mfma_f32_16x16x32_bf16 v[34:37], v[168:171], v[196:199], v[34:37]
	v_mfma_f32_16x16x32_bf16 v[26:29], v[180:183], v[196:199], v[26:29]
	v_mfma_f32_16x16x32_bf16 v[18:21], v[168:171], v[204:207], v[18:21]
	v_mfma_f32_16x16x32_bf16 v[10:13], v[180:183], v[204:207], v[10:13]
	v_mfma_f32_16x16x32_bf16 v[6:9], v[168:171], v[212:215], v[6:9]
	v_mfma_f32_16x16x32_bf16 v[2:5], v[180:183], v[212:215], v[2:5]
	s_setprio 0
	s_barrier
	s_add_i32 s59, 0, 0x18000
	v_add_u32_e32 v0, s59, v145
	s_add_i32 s60, 0, 0x1c000
	ds_read_b128 v[148:151], v0
	ds_read_b128 v[152:155], v0 offset:1024
	ds_read_b128 v[156:159], v0 offset:2048
	ds_read_b128 v[160:163], v0 offset:3072
	v_add_u32_e32 v0, s60, v145
	ds_read_b128 v[164:167], v0
	ds_read_b128 v[168:171], v0 offset:1024
	ds_read_b128 v[172:175], v0 offset:2048
	ds_read_b128 v[180:183], v0 offset:3072
	s_add_u32 s20, s20, 0x80000
	s_addc_u32 s21, s21, 0
	s_mov_b32 m0, s30
	v_lshl_add_u64 v[220:221], s[20:21], 0, v[136:137]
	ds_read_b128 v[184:187], v147 offset:32768
	ds_read_b128 v[188:191], v147 offset:33792
	ds_read_b128 v[192:195], v147 offset:34816
	ds_read_b128 v[196:199], v147 offset:35840
	ds_read_b128 v[200:203], v147 offset:36864
	ds_read_b128 v[204:207], v147 offset:37888
	ds_read_b128 v[208:211], v147 offset:38912
	ds_read_b128 v[212:215], v147 offset:39936
	global_load_lds_dwordx4 v[220:221], off
	v_lshl_add_u64 v[220:221], s[20:21], 0, v[132:133]
	s_mov_b32 m0, s36
	s_nop 0
	global_load_lds_dwordx4 v[220:221], off
	s_waitcnt vmcnt(8)
	s_waitcnt lgkmcnt(0)
	s_barrier
	s_setprio 1
	s_waitcnt lgkmcnt(0)
	v_mfma_f32_16x16x32_bf16 v[126:129], v[148:151], v[184:187], v[126:129]
	v_mfma_f32_16x16x32_bf16 v[122:125], v[156:159], v[184:187], v[122:125]
	v_mfma_f32_16x16x32_bf16 v[118:121], v[148:151], v[192:195], v[118:121]
	v_mfma_f32_16x16x32_bf16 v[110:113], v[156:159], v[192:195], v[110:113]
	v_mfma_f32_16x16x32_bf16 v[102:105], v[148:151], v[200:203], v[102:105]
	v_mfma_f32_16x16x32_bf16 v[94:97], v[156:159], v[200:203], v[94:97]
	v_mfma_f32_16x16x32_bf16 v[86:89], v[148:151], v[208:211], v[86:89]
	v_mfma_f32_16x16x32_bf16 v[78:81], v[156:159], v[208:211], v[78:81]
	s_setprio 0
	s_setprio 1
	v_mfma_f32_16x16x32_bf16 v[126:129], v[152:155], v[188:191], v[126:129]
	v_mfma_f32_16x16x32_bf16 v[122:125], v[160:163], v[188:191], v[122:125]
	v_mfma_f32_16x16x32_bf16 v[118:121], v[152:155], v[196:199], v[118:121]
	v_mfma_f32_16x16x32_bf16 v[110:113], v[160:163], v[196:199], v[110:113]
	v_mfma_f32_16x16x32_bf16 v[102:105], v[152:155], v[204:207], v[102:105]
	v_mfma_f32_16x16x32_bf16 v[94:97], v[160:163], v[204:207], v[94:97]
	v_mfma_f32_16x16x32_bf16 v[86:89], v[152:155], v[212:215], v[86:89]
	v_mfma_f32_16x16x32_bf16 v[78:81], v[160:163], v[212:215], v[78:81]
	s_setprio 0
	s_setprio 1
	v_mfma_f32_16x16x32_bf16 v[114:117], v[164:167], v[184:187], v[114:117]
	v_mfma_f32_16x16x32_bf16 v[106:109], v[172:175], v[184:187], v[106:109]
	v_mfma_f32_16x16x32_bf16 v[98:101], v[164:167], v[192:195], v[98:101]
	v_mfma_f32_16x16x32_bf16 v[90:93], v[172:175], v[192:195], v[90:93]
	v_mfma_f32_16x16x32_bf16 v[82:85], v[164:167], v[200:203], v[82:85]
	v_mfma_f32_16x16x32_bf16 v[74:77], v[172:175], v[200:203], v[74:77]
	v_mfma_f32_16x16x32_bf16 v[70:73], v[164:167], v[208:211], v[70:73]
	v_mfma_f32_16x16x32_bf16 v[66:69], v[172:175], v[208:211], v[66:69]
	s_setprio 0
	s_setprio 1
	v_mfma_f32_16x16x32_bf16 v[114:117], v[168:171], v[188:191], v[114:117]
	v_mfma_f32_16x16x32_bf16 v[106:109], v[180:183], v[188:191], v[106:109]
	v_mfma_f32_16x16x32_bf16 v[98:101], v[168:171], v[196:199], v[98:101]
	v_mfma_f32_16x16x32_bf16 v[90:93], v[180:183], v[196:199], v[90:93]
	v_mfma_f32_16x16x32_bf16 v[82:85], v[168:171], v[204:207], v[82:85]
	v_mfma_f32_16x16x32_bf16 v[74:77], v[180:183], v[204:207], v[74:77]
	v_mfma_f32_16x16x32_bf16 v[70:73], v[168:171], v[212:215], v[70:73]
	v_mfma_f32_16x16x32_bf16 v[66:69], v[180:183], v[212:215], v[66:69]
	s_setprio 0
	s_barrier
; #define PG8_STAGE(bufoff, gbase, voff) do { _Pragma("unroll") for (int _i = 0; _i < 2; ++_i) \
;         __builtin_amdgcn_global_load_lds((const unsigned*)((const char*)(gbase) + (voff)[_i]), (PG8_LAS unsigned*)(lds + (bufoff) + ldsw + _i * 8192), 16, 0, 0); } while (0)
; #define PG8_LDA(dst, b, h) do { _Pragma("unroll") for (int m = 0; m < 4; ++m) _Pragma("unroll") for (int k = 0; k < 2; ++k) dst[m][k] = *(const PG8_LAS bf16x8*)(lds + PG8_SA(b, h) + aoff + m * 2048 + k * 1024); } while (0)
; #define PG8_MMA(ai, bj, At, Bt) do { __builtin_amdgcn_s_setprio(1); _Pragma("unroll") for (int m = 0; m < 4; ++m) _Pragma("unroll") for (int n = 0; n < 2; ++n) _Pragma("unroll") for (int k = 0; k < 2; ++k) \
;         acc[ai][bj][m][n] = __builtin_amdgcn_mfma_f32_16x16x32_bf16(Bt[n][k], At[m][k], acc[ai][bj][m][n], 0, 0, 0); __builtin_amdgcn_s_setprio(0); } while (0)
; #define PG8_WAIT_V(n) asm volatile("s_waitcnt vmcnt(" #n ")" ::: "memory")
; #define PG8_WAIT_L(n) asm volatile("s_waitcnt lgkmcnt(" #n ")" ::: "memory")
; #define PG8_BAR __builtin_amdgcn_s_barrier()
; #define PG8_SCHED __builtin_amdgcn_sched_barrier(0)
; template <class Epi, class Sched, bool ALIGN_EPI = true, bool SP2 = true, bool GS = false>
; __device__ __forceinline__ void gemm_phase(PG8_LAS unsigned char* lds, const Gemm g, const Sched& S, const Epi& E, const float* gs_ss = nullptr) {
;     ...
;             PG8_LDA(At, 1, 1); PG8_STAGE(PG8_SB(1, 0), b3, voffB); PG8_STAGE(PG8_SB(1, 1), b3 + hstep, voffB); PG8_STAGE(PG8_SA(1, 0), a3, voffA);
;             PG8_WAIT_V(8); PG8_WAIT_L(0); PG8_BAR; PG8_MMA(1, 0, At, B0); PG8_MMA(1, 1, At, B1); PG8_BAR; PG8_SCHED;
;     ...
;         }
;         if constexpr (ALIGN_EPI) { if (wr == 0) PG8_BAR; }
	s_add_i32 s20, s59, s23
	v_lshl_add_u64 v[142:143], v[142:143], 0, s[26:27]
	s_mov_b32 m0, s20
	ds_read_b128 v[184:187], v147 offset:49152
	ds_read_b128 v[188:191], v147 offset:50176
	ds_read_b128 v[192:195], v147 offset:51200
	ds_read_b128 v[196:199], v147 offset:52224
	ds_read_b128 v[200:203], v147 offset:53248
	ds_read_b128 v[204:207], v147 offset:54272
	ds_read_b128 v[208:211], v147 offset:55296
	ds_read_b128 v[212:215], v147 offset:56320
	global_load_lds_dwordx4 v[142:143], off
	s_add_i32 m0, s20, 0x2000
	s_add_u32 s2, s2, 0x80080
	v_lshl_add_u64 v[142:143], v[176:177], 0, s[26:27]
	s_addc_u32 s3, s3, 0
	s_add_i32 s20, s60, s23
	global_load_lds_dwordx4 v[142:143], off
	v_lshl_add_u64 v[142:143], s[2:3], 0, v[134:135]
	s_mov_b32 m0, s20
	s_nop 0
	global_load_lds_dwordx4 v[142:143], off
	v_lshl_add_u64 v[142:143], s[2:3], 0, v[130:131]
	s_add_i32 m0, s20, 0x2000
	s_nop 0
	global_load_lds_dwordx4 v[142:143], off
	v_lshl_add_u64 v[142:143], v[216:217], 0, s[26:27]
	s_mov_b32 m0, s47
	s_nop 0
	global_load_lds_dwordx4 v[142:143], off
	v_lshl_add_u64 v[142:143], v[218:219], 0, s[26:27]
	s_mov_b32 m0, s48
	s_nop 0
	global_load_lds_dwordx4 v[142:143], off
	s_waitcnt vmcnt(8)
	s_waitcnt lgkmcnt(0)
	s_barrier
	s_setprio 1
	s_waitcnt lgkmcnt(0)
	v_mfma_f32_16x16x32_bf16 v[62:65], v[148:151], v[184:187], v[62:65]
	v_mfma_f32_16x16x32_bf16 v[58:61], v[156:159], v[184:187], v[58:61]
	v_mfma_f32_16x16x32_bf16 v[54:57], v[148:151], v[192:195], v[54:57]
	v_mfma_f32_16x16x32_bf16 v[46:49], v[156:159], v[192:195], v[46:49]
	v_mfma_f32_16x16x32_bf16 v[38:41], v[148:151], v[200:203], v[38:41]
	v_mfma_f32_16x16x32_bf16 v[30:33], v[156:159], v[200:203], v[30:33]
	v_mfma_f32_16x16x32_bf16 v[22:25], v[148:151], v[208:211], v[22:25]
	v_mfma_f32_16x16x32_bf16 v[14:17], v[156:159], v[208:211], v[14:17]
	s_setprio 0
	s_setprio 1
	v_mfma_f32_16x16x32_bf16 v[62:65], v[152:155], v[188:191], v[62:65]
	v_mfma_f32_16x16x32_bf16 v[58:61], v[160:163], v[188:191], v[58:61]
	v_mfma_f32_16x16x32_bf16 v[54:57], v[152:155], v[196:199], v[54:57]
	v_mfma_f32_16x16x32_bf16 v[46:49], v[160:163], v[196:199], v[46:49]
	v_mfma_f32_16x16x32_bf16 v[38:41], v[152:155], v[204:207], v[38:41]
	v_mfma_f32_16x16x32_bf16 v[30:33], v[160:163], v[204:207], v[30:33]
	v_mfma_f32_16x16x32_bf16 v[22:25], v[152:155], v[212:215], v[22:25]
	v_mfma_f32_16x16x32_bf16 v[14:17], v[160:163], v[212:215], v[14:17]
	s_setprio 0
	s_setprio 1
	v_mfma_f32_16x16x32_bf16 v[50:53], v[164:167], v[184:187], v[50:53]
	v_mfma_f32_16x16x32_bf16 v[42:45], v[172:175], v[184:187], v[42:45]
	v_mfma_f32_16x16x32_bf16 v[34:37], v[164:167], v[192:195], v[34:37]
	v_mfma_f32_16x16x32_bf16 v[26:29], v[172:175], v[192:195], v[26:29]
	v_mfma_f32_16x16x32_bf16 v[18:21], v[164:167], v[200:203], v[18:21]
	v_mfma_f32_16x16x32_bf16 v[10:13], v[172:175], v[200:203], v[10:13]
	v_mfma_f32_16x16x32_bf16 v[6:9], v[164:167], v[208:211], v[6:9]
	v_mfma_f32_16x16x32_bf16 v[2:5], v[172:175], v[208:211], v[2:5]
	s_setprio 0
	s_setprio 1
	v_mfma_f32_16x16x32_bf16 v[50:53], v[168:171], v[188:191], v[50:53]
	v_mfma_f32_16x16x32_bf16 v[42:45], v[180:183], v[188:191], v[42:45]
	v_mfma_f32_16x16x32_bf16 v[34:37], v[168:171], v[196:199], v[34:37]
	v_mfma_f32_16x16x32_bf16 v[26:29], v[180:183], v[196:199], v[26:29]
	v_mfma_f32_16x16x32_bf16 v[18:21], v[168:171], v[204:207], v[18:21]
	v_mfma_f32_16x16x32_bf16 v[10:13], v[180:183], v[204:207], v[10:13]
	v_mfma_f32_16x16x32_bf16 v[6:9], v[168:171], v[212:215], v[6:9]
	v_mfma_f32_16x16x32_bf16 v[2:5], v[180:183], v[212:215], v[2:5]
	s_setprio 0
	s_barrier
	s_add_i32 s58, s58, 2
	s_add_u32 s44, s44, 0x100
	s_addc_u32 s45, s45, 0
	s_add_u32 s56, s56, 0x100
	s_addc_u32 s57, s57, 0
	s_cmp_gt_u32 s58, 5
	s_cbranch_scc0 .LBB0_1119
	s_and_b64 vcc, exec, s[38:39]
	s_cbranch_vccz .LBB0_1122
	s_barrier

;     __device__ bool next(int i, Unit& u) const { const int L = i * G + c; if (L >= 192) return false; u.pm = L / 6; u.pn = L % 6; return true; }
;     __device__ __forceinline__ size_t a_extra(const Unit& u) const { return (size_t)(u.pn >> 1) * ((size_t)T * 512 * 2); }
;     __device__ bool next(int i, Unit& u) const { const int L = i * G + c; if (L >= 256) return false; u.pm = L >> 3; u.pn = L & 7; return true; }
;     __device__ __forceinline__ size_t a_extra(const Unit& u) const { return (size_t)(u.pn >> 1) * 512 * 2; }
;     __device__ __forceinline__ size_t b_extra(const Unit& u) const { return (size_t)(u.pn >> 1) * 512 * 2 - (size_t)(u.pn & ~1) * ((size_t)256 * D * 2); }
; #define PG8_STAGE(bufoff, gbase, voff) do { _Pragma("unroll") for (int _i = 0; _i < 2; ++_i) \
;         __builtin_amdgcn_global_load_lds((const unsigned*)((const char*)(gbase) + (voff)[_i]), (PG8_LAS unsigned*)(lds + (bufoff) + ldsw + _i * 8192), 16, 0, 0); } while (0)
; template <class Epi, class Sched, bool ALIGN_EPI = true, bool SP2 = true, bool GS = false>
; __device__ __forceinline__ void gemm_phase(PG8_LAS unsigned char* lds, const Gemm g, const Sched& S, const Epi& E, const float* gs_ss = nullptr) {
;     ...
;         const bool has_next = S.next(ui + 1, nxt);
;         const char* nA = has_next ? (const char*)g.A + S.a_extra(nxt) + (size_t)nxt.pm * tstep : cA; const char* nB = has_next ? (const char*)g.Bt + S.b_extra(nxt) + (size_t)nxt.pn * tstep : cB;
;         for (int t = 0; t < nt; t += 2) {
;             const bool last = (t == nt - 2);
;             const char* a1 = cA + (size_t)(t + 1) * kstep;
;             const char* a2 = last ? nA : cA + (size_t)(t + 2) * kstep; const char* b2 = last ? nB : cB + (size_t)(t + 2) * kstep;
;             const char* a3 = a2 + kstep; const char* b3 = b2 + kstep;
;             if constexpr (SP2) {
;             PG8_LDB(B0, 0, 0); PG8_LDB(B1, 0, 1); PG8_SCHED; PG8_LDA(At, 0, 0); PG8_STAGE(PG8_SA(1, 1), a1 + hstep, voffA);
;             PG8_WAIT_V(8); PG8_WAIT_L(0); PG8_BAR; PG8_MMA(0, 0, At, B0); PG8_MMA(0, 1, At, B1); PG8_BAR; PG8_SCHED;
;             PG8_LDA(At, 0, 1); PG8_STAGE(PG8_SB(0, 0), b2, voffB); PG8_STAGE(PG8_SB(0, 1), b2 + hstep, voffB); PG8_STAGE(PG8_SA(0, 0), a2, voffA);
;             PG8_WAIT_V(8); PG8_WAIT_L(0); PG8_BAR; PG8_MMA(1, 0, At, B0); PG8_MMA(1, 1, At, B1); PG8_BAR; PG8_SCHED;
.LBB0_1252:
	s_add_u32 s2, s56, 0xfffe0080
	s_addc_u32 s3, s57, -1
	s_add_i32 s65, 0, 0x10000
	s_cmp_eq_u32 s64, 4
	s_cselect_b32 s21, s18, s3
	s_cselect_b32 s20, s51, s2
	s_cselect_b32 s3, s49, s59
	s_cselect_b32 s2, s63, s58
	s_add_i32 s67, 0, 0x14000
	v_add_u32_e32 v142, s65, v183
	v_add_u32_e32 v168, s67, v183
	ds_read_b128 v[122:125], v142
	ds_read_b128 v[130:133], v142 offset:1024
	ds_read_b128 v[138:141], v142 offset:2048
	ds_read_b128 v[142:145], v142 offset:3072
	ds_read_b128 v[156:159], v168
	ds_read_b128 v[160:163], v168 offset:1024
	ds_read_b128 v[164:167], v168 offset:2048
	ds_read_b128 v[168:171], v168 offset:3072
	v_lshl_add_u64 v[176:177], s[56:57], 0, v[152:153]
	s_add_i32 m0, s9, 0xc000
	ds_read_b128 v[172:175], v197
	ds_read_b128 v[184:187], v197 offset:1024
	ds_read_b128 v[188:191], v197 offset:2048
	ds_read_b128 v[192:195], v197 offset:3072
	ds_read_b128 v[198:201], v197 offset:4096
	ds_read_b128 v[202:205], v197 offset:5120
	ds_read_b128 v[206:209], v197 offset:6144
	ds_read_b128 v[210:213], v197 offset:7168
	global_load_lds_dwordx4 v[176:177], off
	v_lshl_add_u64 v[176:177], s[56:57], 0, v[154:155]
	s_add_i32 m0, s9, 0xe000
	s_nop 0
	global_load_lds_dwordx4 v[176:177], off
	s_waitcnt vmcnt(8)
	s_waitcnt lgkmcnt(0)
	s_barrier
	s_setprio 1
	s_waitcnt lgkmcnt(0)
	v_mfma_f32_16x16x32_bf16 v[134:137], v[122:125], v[172:175], v[134:137]
	v_mfma_f32_16x16x32_bf16 v[126:129], v[138:141], v[172:175], v[126:129]
	v_mfma_f32_16x16x32_bf16 v[110:113], v[122:125], v[188:191], v[110:113]
	v_mfma_f32_16x16x32_bf16 v[106:109], v[138:141], v[188:191], v[106:109]
	v_mfma_f32_16x16x32_bf16 v[94:97], v[122:125], v[198:201], v[94:97]
	v_mfma_f32_16x16x32_bf16 v[90:93], v[138:141], v[198:201], v[90:93]
	v_mfma_f32_16x16x32_bf16 v[78:81], v[122:125], v[206:209], v[78:81]
	v_mfma_f32_16x16x32_bf16 v[74:77], v[138:141], v[206:209], v[74:77]
	s_setprio 0
	s_setprio 1
	v_mfma_f32_16x16x32_bf16 v[134:137], v[130:133], v[184:187], v[134:137]
	v_mfma_f32_16x16x32_bf16 v[126:129], v[142:145], v[184:187], v[126:129]
	v_mfma_f32_16x16x32_bf16 v[110:113], v[130:133], v[192:195], v[110:113]
	v_mfma_f32_16x16x32_bf16 v[106:109], v[142:145], v[192:195], v[106:109]
	v_mfma_f32_16x16x32_bf16 v[94:97], v[130:133], v[202:205], v[94:97]
	v_mfma_f32_16x16x32_bf16 v[90:93], v[142:145], v[202:205], v[90:93]
	v_mfma_f32_16x16x32_bf16 v[78:81], v[130:133], v[210:213], v[78:81]
	v_mfma_f32_16x16x32_bf16 v[74:77], v[142:145], v[210:213], v[74:77]
	s_setprio 0
	s_setprio 1
	v_mfma_f32_16x16x32_bf16 v[118:121], v[156:159], v[172:175], v[118:121]
	v_mfma_f32_16x16x32_bf16 v[114:117], v[164:167], v[172:175], v[114:117]
	v_mfma_f32_16x16x32_bf16 v[102:105], v[156:159], v[188:191], v[102:105]
	v_mfma_f32_16x16x32_bf16 v[98:101], v[164:167], v[188:191], v[98:101]
	v_mfma_f32_16x16x32_bf16 v[86:89], v[156:159], v[198:201], v[86:89]
	v_mfma_f32_16x16x32_bf16 v[82:85], v[164:167], v[198:201], v[82:85]
	v_mfma_f32_16x16x32_bf16 v[70:73], v[156:159], v[206:209], v[70:73]
	v_mfma_f32_16x16x32_bf16 v[66:69], v[164:167], v[206:209], v[66:69]
	s_setprio 0
	s_setprio 1
	v_mfma_f32_16x16x32_bf16 v[118:121], v[160:163], v[184:187], v[118:121]
	v_mfma_f32_16x16x32_bf16 v[114:117], v[168:171], v[184:187], v[114:117]
	v_mfma_f32_16x16x32_bf16 v[102:105], v[160:163], v[192:195], v[102:105]
	v_mfma_f32_16x16x32_bf16 v[98:101], v[168:171], v[192:195], v[98:101]
	v_mfma_f32_16x16x32_bf16 v[86:89], v[160:163], v[202:205], v[86:89]
	v_mfma_f32_16x16x32_bf16 v[82:85], v[168:171], v[202:205], v[82:85]
	v_mfma_f32_16x16x32_bf16 v[70:73], v[160:163], v[210:213], v[70:73]
	v_mfma_f32_16x16x32_bf16 v[66:69], v[168:171], v[210:213], v[66:69]
	s_setprio 0
	s_barrier
	s_add_i32 s65, s65, s24
	v_lshl_add_u64 v[176:177], s[2:3], 0, v[0:1]
	s_mov_b32 m0, s65
	ds_read_b128 v[172:175], v197 offset:16384
	ds_read_b128 v[184:187], v197 offset:17408
	ds_read_b128 v[188:191], v197 offset:18432
	ds_read_b128 v[192:195], v197 offset:19456
	ds_read_b128 v[198:201], v197 offset:20480
	ds_read_b128 v[202:205], v197 offset:21504
	ds_read_b128 v[206:209], v197 offset:22528
	ds_read_b128 v[210:213], v197 offset:23552
	global_load_lds_dwordx4 v[176:177], off
	s_add_i32 m0, s65, 0x2000
	s_add_u32 s70, s2, 0x20000
	v_lshl_add_u64 v[180:181], s[2:3], 0, v[150:151]
	s_addc_u32 s71, s3, 0
	s_add_i32 s65, s67, s24
	global_load_lds_dwordx4 v[180:181], off
	v_lshl_add_u64 v[214:215], s[70:71], 0, v[0:1]
	s_mov_b32 m0, s65
	v_lshl_add_u64 v[216:217], s[20:21], 0, v[148:149]
	global_load_lds_dwordx4 v[214:215], off
	v_lshl_add_u64 v[214:215], s[70:71], 0, v[150:151]
	s_add_i32 m0, s65, 0x2000
	s_nop 0
	global_load_lds_dwordx4 v[214:215], off
	v_lshl_add_u64 v[214:215], s[20:21], 0, v[146:147]
	s_mov_b32 m0, s9
	s_nop 0
	global_load_lds_dwordx4 v[214:215], off
	s_mov_b32 m0, s13
	s_nop 0
	global_load_lds_dwordx4 v[216:217], off
	s_waitcnt vmcnt(8)
	s_waitcnt lgkmcnt(0)
	s_barrier
; #define PG8_STAGE(bufoff, gbase, voff) do { _Pragma("unroll") for (int _i = 0; _i < 2; ++_i) \
;         __builtin_amdgcn_global_load_lds((const unsigned*)((const char*)(gbase) + (voff)[_i]), (PG8_LAS unsigned*)(lds + (bufoff) + ldsw + _i * 8192), 16, 0, 0); } while (0)
; #define PG8_LDA(dst, b, h) do { _Pragma("unroll") for (int m = 0; m < 4; ++m) _Pragma("unroll") for (int k = 0; k < 2; ++k) dst[m][k] = *(const PG8_LAS bf16x8*)(lds + PG8_SA(b, h) + aoff + m * 2048 + k * 1024); } while (0)
; #define PG8_LDB(dst, b, h) do { _Pragma("unroll") for (int n = 0; n < 2; ++n) _Pragma("unroll") for (int k = 0; k < 2; ++k) dst[n][k] = *(const PG8_LAS bf16x8*)(lds + PG8_SB(b, h) + boff + n * 2048 + k * 1024); } while (0)
; #define PG8_MMA(ai, bj, At, Bt) do { __builtin_amdgcn_s_setprio(1); _Pragma("unroll") for (int m = 0; m < 4; ++m) _Pragma("unroll") for (int n = 0; n < 2; ++n) _Pragma("unroll") for (int k = 0; k < 2; ++k) \
;         acc[ai][bj][m][n] = __builtin_amdgcn_mfma_f32_16x16x32_bf16(Bt[n][k], At[m][k], acc[ai][bj][m][n], 0, 0, 0); __builtin_amdgcn_s_setprio(0); } while (0)
; #define PG8_WAIT_V(n) asm volatile("s_waitcnt vmcnt(" #n ")" ::: "memory")
; #define PG8_WAIT_L(n) asm volatile("s_waitcnt lgkmcnt(" #n ")" ::: "memory")
; #define PG8_BAR __builtin_amdgcn_s_barrier()
; #define PG8_SCHED __builtin_amdgcn_sched_barrier(0)
; template <class Epi, class Sched, bool ALIGN_EPI = true, bool SP2 = true, bool GS = false>
; __device__ __forceinline__ void gemm_phase(PG8_LAS unsigned char* lds, const Gemm g, const Sched& S, const Epi& E, const float* gs_ss = nullptr) {
;     ...
;             PG8_WAIT_V(8); PG8_WAIT_L(0); PG8_BAR; PG8_MMA(1, 0, At, B0); PG8_MMA(1, 1, At, B1); PG8_BAR; PG8_SCHED;
;             PG8_LDB(B0, 1, 0); PG8_LDB(B1, 1, 1); PG8_SCHED; PG8_LDA(At, 1, 0); PG8_STAGE(PG8_SA(0, 1), a2 + hstep, voffA);
;             PG8_WAIT_V(8); PG8_WAIT_L(0); PG8_BAR; PG8_MMA(0, 0, At, B0); PG8_MMA(0, 1, At, B1); PG8_BAR; PG8_SCHED;
	s_setprio 1
	s_waitcnt lgkmcnt(0)
	v_mfma_f32_16x16x32_bf16 v[62:65], v[122:125], v[172:175], v[62:65]
	v_mfma_f32_16x16x32_bf16 v[58:61], v[138:141], v[172:175], v[58:61]
	v_mfma_f32_16x16x32_bf16 v[46:49], v[122:125], v[188:191], v[46:49]
	v_mfma_f32_16x16x32_bf16 v[42:45], v[138:141], v[188:191], v[42:45]
	v_mfma_f32_16x16x32_bf16 v[30:33], v[122:125], v[198:201], v[30:33]
	v_mfma_f32_16x16x32_bf16 v[26:29], v[138:141], v[198:201], v[26:29]
	v_mfma_f32_16x16x32_bf16 v[14:17], v[122:125], v[206:209], v[14:17]
	v_mfma_f32_16x16x32_bf16 v[10:13], v[138:141], v[206:209], v[10:13]
	s_setprio 0
	s_setprio 1
	v_mfma_f32_16x16x32_bf16 v[62:65], v[130:133], v[184:187], v[62:65]
	v_mfma_f32_16x16x32_bf16 v[58:61], v[142:145], v[184:187], v[58:61]
	v_mfma_f32_16x16x32_bf16 v[46:49], v[130:133], v[192:195], v[46:49]
	v_mfma_f32_16x16x32_bf16 v[42:45], v[142:145], v[192:195], v[42:45]
	v_mfma_f32_16x16x32_bf16 v[30:33], v[130:133], v[202:205], v[30:33]
	v_mfma_f32_16x16x32_bf16 v[26:29], v[142:145], v[202:205], v[26:29]
	v_mfma_f32_16x16x32_bf16 v[14:17], v[130:133], v[210:213], v[14:17]
	v_mfma_f32_16x16x32_bf16 v[10:13], v[142:145], v[210:213], v[10:13]
	s_setprio 0
	s_setprio 1
	v_mfma_f32_16x16x32_bf16 v[54:57], v[156:159], v[172:175], v[54:57]
	v_mfma_f32_16x16x32_bf16 v[50:53], v[164:167], v[172:175], v[50:53]
	v_mfma_f32_16x16x32_bf16 v[38:41], v[156:159], v[188:191], v[38:41]
	v_mfma_f32_16x16x32_bf16 v[34:37], v[164:167], v[188:191], v[34:37]
	v_mfma_f32_16x16x32_bf16 v[22:25], v[156:159], v[198:201], v[22:25]
	v_mfma_f32_16x16x32_bf16 v[18:21], v[164:167], v[198:201], v[18:21]
	v_mfma_f32_16x16x32_bf16 v[6:9], v[156:159], v[206:209], v[6:9]
	v_mfma_f32_16x16x32_bf16 v[2:5], v[164:167], v[206:209], v[2:5]
	s_setprio 0
	s_setprio 1
	v_mfma_f32_16x16x32_bf16 v[54:57], v[160:163], v[184:187], v[54:57]
	v_mfma_f32_16x16x32_bf16 v[50:53], v[168:171], v[184:187], v[50:53]
	v_mfma_f32_16x16x32_bf16 v[38:41], v[160:163], v[192:195], v[38:41]
	v_mfma_f32_16x16x32_bf16 v[34:37], v[168:171], v[192:195], v[34:37]
	v_mfma_f32_16x16x32_bf16 v[22:25], v[160:163], v[202:205], v[22:25]
	v_mfma_f32_16x16x32_bf16 v[18:21], v[168:171], v[202:205], v[18:21]
	v_mfma_f32_16x16x32_bf16 v[6:9], v[160:163], v[210:213], v[6:9]
	v_mfma_f32_16x16x32_bf16 v[2:5], v[168:171], v[210:213], v[2:5]
	s_setprio 0
	s_barrier
	s_add_i32 s65, 0, 0x18000
	s_add_i32 s67, 0, 0x1c000
	v_add_u32_e32 v142, s65, v183
	v_add_u32_e32 v168, s67, v183
	ds_read_b128 v[122:125], v142
	ds_read_b128 v[130:133], v142 offset:1024
	ds_read_b128 v[138:141], v142 offset:2048
	ds_read_b128 v[142:145], v142 offset:3072
	ds_read_b128 v[156:159], v168
	ds_read_b128 v[160:163], v168 offset:1024
	ds_read_b128 v[164:167], v168 offset:2048
	ds_read_b128 v[168:171], v168 offset:3072
	s_add_u32 s20, s20, 0x20000
	s_addc_u32 s21, s21, 0
	s_mov_b32 m0, s25
	v_lshl_add_u64 v[218:219], s[20:21], 0, v[146:147]
	ds_read_b128 v[172:175], v197 offset:32768
	ds_read_b128 v[184:187], v197 offset:33792
	ds_read_b128 v[188:191], v197 offset:34816
	ds_read_b128 v[192:195], v197 offset:35840
	ds_read_b128 v[198:201], v197 offset:36864
	ds_read_b128 v[202:205], v197 offset:37888
	ds_read_b128 v[206:209], v197 offset:38912
	ds_read_b128 v[210:213], v197 offset:39936
	global_load_lds_dwordx4 v[218:219], off
	v_lshl_add_u64 v[218:219], s[20:21], 0, v[148:149]
	s_mov_b32 m0, s30
	s_nop 0
	global_load_lds_dwordx4 v[218:219], off
	s_waitcnt vmcnt(8)
	s_waitcnt lgkmcnt(0)
	s_barrier
	s_setprio 1
	s_waitcnt lgkmcnt(0)
	v_mfma_f32_16x16x32_bf16 v[134:137], v[122:125], v[172:175], v[134:137]
	v_mfma_f32_16x16x32_bf16 v[126:129], v[138:141], v[172:175], v[126:129]
	v_mfma_f32_16x16x32_bf16 v[110:113], v[122:125], v[188:191], v[110:113]
	v_mfma_f32_16x16x32_bf16 v[106:109], v[138:141], v[188:191], v[106:109]
	v_mfma_f32_16x16x32_bf16 v[94:97], v[122:125], v[198:201], v[94:97]
	v_mfma_f32_16x16x32_bf16 v[90:93], v[138:141], v[198:201], v[90:93]
	v_mfma_f32_16x16x32_bf16 v[78:81], v[122:125], v[206:209], v[78:81]
	v_mfma_f32_16x16x32_bf16 v[74:77], v[138:141], v[206:209], v[74:77]
	s_setprio 0
	s_setprio 1
	v_mfma_f32_16x16x32_bf16 v[134:137], v[130:133], v[184:187], v[134:137]
	v_mfma_f32_16x16x32_bf16 v[126:129], v[142:145], v[184:187], v[126:129]
	v_mfma_f32_16x16x32_bf16 v[110:113], v[130:133], v[192:195], v[110:113]
	v_mfma_f32_16x16x32_bf16 v[106:109], v[142:145], v[192:195], v[106:109]
	v_mfma_f32_16x16x32_bf16 v[94:97], v[130:133], v[202:205], v[94:97]
	v_mfma_f32_16x16x32_bf16 v[90:93], v[142:145], v[202:205], v[90:93]
	v_mfma_f32_16x16x32_bf16 v[78:81], v[130:133], v[210:213], v[78:81]
	v_mfma_f32_16x16x32_bf16 v[74:77], v[142:145], v[210:213], v[74:77]
	s_setprio 0
	s_setprio 1
	v_mfma_f32_16x16x32_bf16 v[118:121], v[156:159], v[172:175], v[118:121]
	v_mfma_f32_16x16x32_bf16 v[114:117], v[164:167], v[172:175], v[114:117]
	v_mfma_f32_16x16x32_bf16 v[102:105], v[156:159], v[188:191], v[102:105]
	v_mfma_f32_16x16x32_bf16 v[98:101], v[164:167], v[188:191], v[98:101]
	v_mfma_f32_16x16x32_bf16 v[86:89], v[156:159], v[198:201], v[86:89]
	v_mfma_f32_16x16x32_bf16 v[82:85], v[164:167], v[198:201], v[82:85]
	v_mfma_f32_16x16x32_bf16 v[70:73], v[156:159], v[206:209], v[70:73]
	v_mfma_f32_16x16x32_bf16 v[66:69], v[164:167], v[206:209], v[66:69]
	s_setprio 0
	s_setprio 1
	v_mfma_f32_16x16x32_bf16 v[118:121], v[160:163], v[184:187], v[118:121]
	v_mfma_f32_16x16x32_bf16 v[114:117], v[168:171], v[184:187], v[114:117]
	v_mfma_f32_16x16x32_bf16 v[102:105], v[160:163], v[192:195], v[102:105]
	v_mfma_f32_16x16x32_bf16 v[98:101], v[168:171], v[192:195], v[98:101]
	v_mfma_f32_16x16x32_bf16 v[86:89], v[160:163], v[202:205], v[86:89]
	v_mfma_f32_16x16x32_bf16 v[82:85], v[168:171], v[202:205], v[82:85]
	v_mfma_f32_16x16x32_bf16 v[70:73], v[160:163], v[210:213], v[70:73]
	v_mfma_f32_16x16x32_bf16 v[66:69], v[168:171], v[210:213], v[66:69]
	s_setprio 0
	s_barrier
; #define PG8_STAGE(bufoff, gbase, voff) do { _Pragma("unroll") for (int _i = 0; _i < 2; ++_i) \
;         __builtin_amdgcn_global_load_lds((const unsigned*)((const char*)(gbase) + (voff)[_i]), (PG8_LAS unsigned*)(lds + (bufoff) + ldsw + _i * 8192), 16, 0, 0); } while (0)
; #define PG8_LDA(dst, b, h) do { _Pragma("unroll") for (int m = 0; m < 4; ++m) _Pragma("unroll") for (int k = 0; k < 2; ++k) dst[m][k] = *(const PG8_LAS bf16x8*)(lds + PG8_SA(b, h) + aoff + m * 2048 + k * 1024); } while (0)
; #define PG8_MMA(ai, bj, At, Bt) do { __builtin_amdgcn_s_setprio(1); _Pragma("unroll") for (int m = 0; m < 4; ++m) _Pragma("unroll") for (int n = 0; n < 2; ++n) _Pragma("unroll") for (int k = 0; k < 2; ++k) \
;         acc[ai][bj][m][n] = __builtin_amdgcn_mfma_f32_16x16x32_bf16(Bt[n][k], At[m][k], acc[ai][bj][m][n], 0, 0, 0); __builtin_amdgcn_s_setprio(0); } while (0)
; #define PG8_WAIT_V(n) asm volatile("s_waitcnt vmcnt(" #n ")" ::: "memory")
; #define PG8_WAIT_L(n) asm volatile("s_waitcnt lgkmcnt(" #n ")" ::: "memory")
; #define PG8_BAR __builtin_amdgcn_s_barrier()
; #define PG8_SCHED __builtin_amdgcn_sched_barrier(0)
; template <class Epi, class Sched, bool ALIGN_EPI = true, bool SP2 = true, bool GS = false>
; __device__ __forceinline__ void gemm_phase(PG8_LAS unsigned char* lds, const Gemm g, const Sched& S, const Epi& E, const float* gs_ss = nullptr) {
;     ...
;             PG8_LDA(At, 1, 1); PG8_STAGE(PG8_SB(1, 0), b3, voffB); PG8_STAGE(PG8_SB(1, 1), b3 + hstep, voffB); PG8_STAGE(PG8_SA(1, 0), a3, voffA);
;             PG8_WAIT_V(8); PG8_WAIT_L(0); PG8_BAR; PG8_MMA(1, 0, At, B0); PG8_MMA(1, 1, At, B1); PG8_BAR; PG8_SCHED;
;     ...
;         }
;         if constexpr (ALIGN_EPI) { if (wr == 0) PG8_BAR; }
	s_add_i32 s20, s65, s24
	v_lshl_add_u64 v[176:177], v[176:177], 0, s[26:27]
	s_mov_b32 m0, s20
	ds_read_b128 v[172:175], v197 offset:49152
	ds_read_b128 v[184:187], v197 offset:50176
	ds_read_b128 v[188:191], v197 offset:51200
	ds_read_b128 v[192:195], v197 offset:52224
	ds_read_b128 v[198:201], v197 offset:53248
	ds_read_b128 v[202:205], v197 offset:54272
	ds_read_b128 v[206:209], v197 offset:55296
	ds_read_b128 v[210:213], v197 offset:56320
	global_load_lds_dwordx4 v[176:177], off
	s_add_i32 m0, s20, 0x2000
	s_add_u32 s2, s2, 0x20080
	v_lshl_add_u64 v[176:177], v[180:181], 0, s[26:27]
	s_addc_u32 s3, s3, 0
	s_add_i32 s20, s67, s24
	global_load_lds_dwordx4 v[176:177], off
	v_lshl_add_u64 v[176:177], s[2:3], 0, v[0:1]
	s_mov_b32 m0, s20
	s_nop 0
	global_load_lds_dwordx4 v[176:177], off
	v_lshl_add_u64 v[176:177], s[2:3], 0, v[150:151]
	s_add_i32 m0, s20, 0x2000
	s_nop 0
	global_load_lds_dwordx4 v[176:177], off
	v_lshl_add_u64 v[176:177], v[214:215], 0, s[26:27]
	s_mov_b32 m0, s37
	s_nop 0
	global_load_lds_dwordx4 v[176:177], off
	v_lshl_add_u64 v[176:177], v[216:217], 0, s[26:27]
	s_mov_b32 m0, s60
	s_nop 0
	global_load_lds_dwordx4 v[176:177], off
	s_waitcnt vmcnt(8)
	s_waitcnt lgkmcnt(0)
	s_barrier
	s_setprio 1
	s_waitcnt lgkmcnt(0)
	v_mfma_f32_16x16x32_bf16 v[62:65], v[122:125], v[172:175], v[62:65]
	v_mfma_f32_16x16x32_bf16 v[58:61], v[138:141], v[172:175], v[58:61]
	v_mfma_f32_16x16x32_bf16 v[46:49], v[122:125], v[188:191], v[46:49]
	v_mfma_f32_16x16x32_bf16 v[42:45], v[138:141], v[188:191], v[42:45]
	v_mfma_f32_16x16x32_bf16 v[30:33], v[122:125], v[198:201], v[30:33]
	v_mfma_f32_16x16x32_bf16 v[26:29], v[138:141], v[198:201], v[26:29]
	v_mfma_f32_16x16x32_bf16 v[14:17], v[122:125], v[206:209], v[14:17]
	v_mfma_f32_16x16x32_bf16 v[10:13], v[138:141], v[206:209], v[10:13]
	s_setprio 0
	s_setprio 1
	v_mfma_f32_16x16x32_bf16 v[62:65], v[130:133], v[184:187], v[62:65]
	v_mfma_f32_16x16x32_bf16 v[58:61], v[142:145], v[184:187], v[58:61]
	v_mfma_f32_16x16x32_bf16 v[46:49], v[130:133], v[192:195], v[46:49]
	v_mfma_f32_16x16x32_bf16 v[42:45], v[142:145], v[192:195], v[42:45]
	v_mfma_f32_16x16x32_bf16 v[30:33], v[130:133], v[202:205], v[30:33]
	v_mfma_f32_16x16x32_bf16 v[26:29], v[142:145], v[202:205], v[26:29]
	v_mfma_f32_16x16x32_bf16 v[14:17], v[130:133], v[210:213], v[14:17]
	v_mfma_f32_16x16x32_bf16 v[10:13], v[142:145], v[210:213], v[10:13]
	s_setprio 0
	s_setprio 1
	v_mfma_f32_16x16x32_bf16 v[54:57], v[156:159], v[172:175], v[54:57]
	v_mfma_f32_16x16x32_bf16 v[50:53], v[164:167], v[172:175], v[50:53]
	v_mfma_f32_16x16x32_bf16 v[38:41], v[156:159], v[188:191], v[38:41]
	v_mfma_f32_16x16x32_bf16 v[34:37], v[164:167], v[188:191], v[34:37]
	v_mfma_f32_16x16x32_bf16 v[22:25], v[156:159], v[198:201], v[22:25]
	v_mfma_f32_16x16x32_bf16 v[18:21], v[164:167], v[198:201], v[18:21]
	v_mfma_f32_16x16x32_bf16 v[6:9], v[156:159], v[206:209], v[6:9]
	v_mfma_f32_16x16x32_bf16 v[2:5], v[164:167], v[206:209], v[2:5]
	s_setprio 0
	s_setprio 1
	v_mfma_f32_16x16x32_bf16 v[54:57], v[160:163], v[184:187], v[54:57]
	v_mfma_f32_16x16x32_bf16 v[50:53], v[168:171], v[184:187], v[50:53]
	v_mfma_f32_16x16x32_bf16 v[38:41], v[160:163], v[192:195], v[38:41]
	v_mfma_f32_16x16x32_bf16 v[34:37], v[168:171], v[192:195], v[34:37]
	v_mfma_f32_16x16x32_bf16 v[22:25], v[160:163], v[202:205], v[22:25]
	v_mfma_f32_16x16x32_bf16 v[18:21], v[168:171], v[202:205], v[18:21]
	v_mfma_f32_16x16x32_bf16 v[6:9], v[160:163], v[210:213], v[6:9]
	v_mfma_f32_16x16x32_bf16 v[2:5], v[168:171], v[210:213], v[2:5]
	s_setprio 0
	s_barrier
	s_add_i32 s64, s64, 2
	s_add_u32 s56, s56, 0x100
	s_addc_u32 s57, s57, 0
	s_add_u32 s58, s58, 0x100
	s_addc_u32 s59, s59, 0
	s_cmp_gt_u32 s64, 5
	s_cbranch_scc0 .LBB0_1252
	s_and_b64 vcc, exec, s[46:47]
	s_cbranch_vccz .LBB0_1255
	s_barrier

;     __device__ bool next(int i, Unit& u) const { const int L = i * G + c; if (L >= 192) return false; u.pm = L / 6; u.pn = L % 6; return true; }
;     __device__ __forceinline__ size_t a_extra(const Unit& u) const { return (size_t)(u.pn >> 1) * ((size_t)T * 512 * 2); }
;     __device__ bool next(int i, Unit& u) const { const int L = i * G + c; if (L >= 256) return false; u.pm = L >> 3; u.pn = L & 7; return true; }
;     __device__ __forceinline__ size_t a_extra(const Unit& u) const { return (size_t)(u.pn >> 1) * 512 * 2; }
;     __device__ __forceinline__ size_t b_extra(const Unit& u) const { return (size_t)(u.pn >> 1) * 512 * 2 - (size_t)(u.pn & ~1) * ((size_t)256 * D * 2); }
; #define PG8_STAGE(bufoff, gbase, voff) do { _Pragma("unroll") for (int _i = 0; _i < 2; ++_i) \
;         __builtin_amdgcn_global_load_lds((const unsigned*)((const char*)(gbase) + (voff)[_i]), (PG8_LAS unsigned*)(lds + (bufoff) + ldsw + _i * 8192), 16, 0, 0); } while (0)
; template <class Epi, class Sched, bool ALIGN_EPI = true, bool SP2 = true, bool GS = false>
; __device__ __forceinline__ void gemm_phase(PG8_LAS unsigned char* lds, const Gemm g, const Sched& S, const Epi& E, const float* gs_ss = nullptr) {
;     ...
;         const bool has_next = S.next(ui + 1, nxt);
;         const char* nA = has_next ? (const char*)g.A + S.a_extra(nxt) + (size_t)nxt.pm * tstep : cA; const char* nB = has_next ? (const char*)g.Bt + S.b_extra(nxt) + (size_t)nxt.pn * tstep : cB;
;         for (int t = 0; t < nt; t += 2) {
;             const bool last = (t == nt - 2);
;             const char* a1 = cA + (size_t)(t + 1) * kstep;
;             const char* a2 = last ? nA : cA + (size_t)(t + 2) * kstep; const char* b2 = last ? nB : cB + (size_t)(t + 2) * kstep;
;             const char* a3 = a2 + kstep; const char* b3 = b2 + kstep;
;             if constexpr (SP2) {
;             PG8_LDB(B0, 0, 0); PG8_LDB(B1, 0, 1); PG8_SCHED; PG8_LDA(At, 0, 0); PG8_STAGE(PG8_SA(1, 1), a1 + hstep, voffA);
;             PG8_WAIT_V(8); PG8_WAIT_L(0); PG8_BAR; PG8_MMA(0, 0, At, B0); PG8_MMA(0, 1, At, B1); PG8_BAR; PG8_SCHED;
;             PG8_LDA(At, 0, 1); PG8_STAGE(PG8_SB(0, 0), b2, voffB); PG8_STAGE(PG8_SB(0, 1), b2 + hstep, voffB); PG8_STAGE(PG8_SA(0, 0), a2, voffA);
;             PG8_WAIT_V(8); PG8_WAIT_L(0); PG8_BAR; PG8_MMA(1, 0, At, B0); PG8_MMA(1, 1, At, B1); PG8_BAR; PG8_SCHED;
.LBB0_1344:
	s_add_u32 s2, s50, 0xfff80080
	s_addc_u32 s3, s51, -1
	s_add_i32 s60, 0, 0x10000
	s_cmp_eq_u32 s59, 28
	s_cselect_b32 s21, s43, s3
	s_cselect_b32 s20, s57, s2
	v_add_u32_e32 v140, s60, v143
	s_cselect_b32 s3, s41, s53
	s_cselect_b32 s2, s58, s52
	s_add_i32 s62, 0, 0x14000
	ds_read_b128 v[146:149], v140
	ds_read_b128 v[150:153], v140 offset:1024
	ds_read_b128 v[154:157], v140 offset:2048
	ds_read_b128 v[158:161], v140 offset:3072
	v_add_u32_e32 v140, s62, v143
	ds_read_b128 v[162:165], v140
	ds_read_b128 v[166:169], v140 offset:1024
	ds_read_b128 v[170:173], v140 offset:2048
	ds_read_b128 v[174:177], v140 offset:3072
	v_lshl_add_u64 v[140:141], s[50:51], 0, v[136:137]
	s_add_i32 m0, s30, 0xc000
	ds_read_b128 v[180:183], v145
	ds_read_b128 v[184:187], v145 offset:1024
	ds_read_b128 v[188:191], v145 offset:2048
	ds_read_b128 v[192:195], v145 offset:3072
	ds_read_b128 v[196:199], v145 offset:4096
	ds_read_b128 v[200:203], v145 offset:5120
	ds_read_b128 v[204:207], v145 offset:6144
	ds_read_b128 v[208:211], v145 offset:7168
	global_load_lds_dwordx4 v[140:141], off
	v_lshl_add_u64 v[140:141], s[50:51], 0, v[138:139]
	s_add_i32 m0, s30, 0xe000
	s_nop 0
	global_load_lds_dwordx4 v[140:141], off
	s_waitcnt vmcnt(8)
	s_waitcnt lgkmcnt(0)
	s_barrier
	s_setprio 1
	s_waitcnt lgkmcnt(0)
	v_mfma_f32_16x16x32_bf16 v[126:129], v[146:149], v[180:183], v[126:129]
	v_mfma_f32_16x16x32_bf16 v[122:125], v[154:157], v[180:183], v[122:125]
	v_mfma_f32_16x16x32_bf16 v[110:113], v[146:149], v[188:191], v[110:113]
	v_mfma_f32_16x16x32_bf16 v[106:109], v[154:157], v[188:191], v[106:109]
	v_mfma_f32_16x16x32_bf16 v[94:97], v[146:149], v[196:199], v[94:97]
	v_mfma_f32_16x16x32_bf16 v[90:93], v[154:157], v[196:199], v[90:93]
	v_mfma_f32_16x16x32_bf16 v[78:81], v[146:149], v[204:207], v[78:81]
	v_mfma_f32_16x16x32_bf16 v[74:77], v[154:157], v[204:207], v[74:77]
	s_setprio 0
	s_setprio 1
	v_mfma_f32_16x16x32_bf16 v[126:129], v[150:153], v[184:187], v[126:129]
	v_mfma_f32_16x16x32_bf16 v[122:125], v[158:161], v[184:187], v[122:125]
	v_mfma_f32_16x16x32_bf16 v[110:113], v[150:153], v[192:195], v[110:113]
	v_mfma_f32_16x16x32_bf16 v[106:109], v[158:161], v[192:195], v[106:109]
	v_mfma_f32_16x16x32_bf16 v[94:97], v[150:153], v[200:203], v[94:97]
	v_mfma_f32_16x16x32_bf16 v[90:93], v[158:161], v[200:203], v[90:93]
	v_mfma_f32_16x16x32_bf16 v[78:81], v[150:153], v[208:211], v[78:81]
	v_mfma_f32_16x16x32_bf16 v[74:77], v[158:161], v[208:211], v[74:77]
	s_setprio 0
	s_setprio 1
	v_mfma_f32_16x16x32_bf16 v[118:121], v[162:165], v[180:183], v[118:121]
	v_mfma_f32_16x16x32_bf16 v[114:117], v[170:173], v[180:183], v[114:117]
	v_mfma_f32_16x16x32_bf16 v[102:105], v[162:165], v[188:191], v[102:105]
	v_mfma_f32_16x16x32_bf16 v[98:101], v[170:173], v[188:191], v[98:101]
	v_mfma_f32_16x16x32_bf16 v[86:89], v[162:165], v[196:199], v[86:89]
	v_mfma_f32_16x16x32_bf16 v[82:85], v[170:173], v[196:199], v[82:85]
	v_mfma_f32_16x16x32_bf16 v[70:73], v[162:165], v[204:207], v[70:73]
	v_mfma_f32_16x16x32_bf16 v[66:69], v[170:173], v[204:207], v[66:69]
	s_setprio 0
	s_setprio 1
	v_mfma_f32_16x16x32_bf16 v[118:121], v[166:169], v[184:187], v[118:121]
	v_mfma_f32_16x16x32_bf16 v[114:117], v[174:177], v[184:187], v[114:117]
	v_mfma_f32_16x16x32_bf16 v[102:105], v[166:169], v[192:195], v[102:105]
	v_mfma_f32_16x16x32_bf16 v[98:101], v[174:177], v[192:195], v[98:101]
	v_mfma_f32_16x16x32_bf16 v[86:89], v[166:169], v[200:203], v[86:89]
	v_mfma_f32_16x16x32_bf16 v[82:85], v[174:177], v[200:203], v[82:85]
	v_mfma_f32_16x16x32_bf16 v[70:73], v[166:169], v[208:211], v[70:73]
	v_mfma_f32_16x16x32_bf16 v[66:69], v[174:177], v[208:211], v[66:69]
	s_setprio 0
	s_barrier
	s_add_i32 s60, s60, s25
	v_lshl_add_u64 v[140:141], s[2:3], 0, v[0:1]
	s_mov_b32 m0, s60
	ds_read_b128 v[180:183], v145 offset:16384
	ds_read_b128 v[184:187], v145 offset:17408
	ds_read_b128 v[188:191], v145 offset:18432
	ds_read_b128 v[192:195], v145 offset:19456
	ds_read_b128 v[196:199], v145 offset:20480
	ds_read_b128 v[200:203], v145 offset:21504
	ds_read_b128 v[204:207], v145 offset:22528
	ds_read_b128 v[208:211], v145 offset:23552
	global_load_lds_dwordx4 v[140:141], off
	s_add_i32 m0, s60, 0x2000
	s_add_u32 s60, s2, 0x80000
	v_lshl_add_u64 v[212:213], s[2:3], 0, v[134:135]
	s_addc_u32 s61, s3, 0
	s_add_i32 s62, s62, s25
	global_load_lds_dwordx4 v[212:213], off
	v_lshl_add_u64 v[214:215], s[60:61], 0, v[0:1]
	s_mov_b32 m0, s62
	v_lshl_add_u64 v[216:217], s[20:21], 0, v[132:133]
	global_load_lds_dwordx4 v[214:215], off
	v_lshl_add_u64 v[214:215], s[60:61], 0, v[134:135]
	s_add_i32 m0, s62, 0x2000
	s_nop 0
	global_load_lds_dwordx4 v[214:215], off
	v_lshl_add_u64 v[214:215], s[20:21], 0, v[130:131]
	s_mov_b32 m0, s30
	s_nop 0
	global_load_lds_dwordx4 v[214:215], off
	s_mov_b32 m0, s36
	s_nop 0
	global_load_lds_dwordx4 v[216:217], off
	s_waitcnt vmcnt(8)
	s_waitcnt lgkmcnt(0)
	s_barrier
; #define PG8_STAGE(bufoff, gbase, voff) do { _Pragma("unroll") for (int _i = 0; _i < 2; ++_i) \
;         __builtin_amdgcn_global_load_lds((const unsigned*)((const char*)(gbase) + (voff)[_i]), (PG8_LAS unsigned*)(lds + (bufoff) + ldsw + _i * 8192), 16, 0, 0); } while (0)
; #define PG8_LDA(dst, b, h) do { _Pragma("unroll") for (int m = 0; m < 4; ++m) _Pragma("unroll") for (int k = 0; k < 2; ++k) dst[m][k] = *(const PG8_LAS bf16x8*)(lds + PG8_SA(b, h) + aoff + m * 2048 + k * 1024); } while (0)
; #define PG8_LDB(dst, b, h) do { _Pragma("unroll") for (int n = 0; n < 2; ++n) _Pragma("unroll") for (int k = 0; k < 2; ++k) dst[n][k] = *(const PG8_LAS bf16x8*)(lds + PG8_SB(b, h) + boff + n * 2048 + k * 1024); } while (0)
; #define PG8_MMA(ai, bj, At, Bt) do { __builtin_amdgcn_s_setprio(1); _Pragma("unroll") for (int m = 0; m < 4; ++m) _Pragma("unroll") for (int n = 0; n < 2; ++n) _Pragma("unroll") for (int k = 0; k < 2; ++k) \
;         acc[ai][bj][m][n] = __builtin_amdgcn_mfma_f32_16x16x32_bf16(Bt[n][k], At[m][k], acc[ai][bj][m][n], 0, 0, 0); __builtin_amdgcn_s_setprio(0); } while (0)
; #define PG8_WAIT_V(n) asm volatile("s_waitcnt vmcnt(" #n ")" ::: "memory")
; #define PG8_WAIT_L(n) asm volatile("s_waitcnt lgkmcnt(" #n ")" ::: "memory")
; #define PG8_BAR __builtin_amdgcn_s_barrier()
; #define PG8_SCHED __builtin_amdgcn_sched_barrier(0)
; template <class Epi, class Sched, bool ALIGN_EPI = true, bool SP2 = true, bool GS = false>
; __device__ __forceinline__ void gemm_phase(PG8_LAS unsigned char* lds, const Gemm g, const Sched& S, const Epi& E, const float* gs_ss = nullptr) {
;     ...
;             PG8_WAIT_V(8); PG8_WAIT_L(0); PG8_BAR; PG8_MMA(1, 0, At, B0); PG8_MMA(1, 1, At, B1); PG8_BAR; PG8_SCHED;
;             PG8_LDB(B0, 1, 0); PG8_LDB(B1, 1, 1); PG8_SCHED; PG8_LDA(At, 1, 0); PG8_STAGE(PG8_SA(0, 1), a2 + hstep, voffA);
;             PG8_WAIT_V(8); PG8_WAIT_L(0); PG8_BAR; PG8_MMA(0, 0, At, B0); PG8_MMA(0, 1, At, B1); PG8_BAR; PG8_SCHED;
	s_setprio 1
	s_waitcnt lgkmcnt(0)
	v_mfma_f32_16x16x32_bf16 v[62:65], v[146:149], v[180:183], v[62:65]
	v_mfma_f32_16x16x32_bf16 v[58:61], v[154:157], v[180:183], v[58:61]
	v_mfma_f32_16x16x32_bf16 v[46:49], v[146:149], v[188:191], v[46:49]
	v_mfma_f32_16x16x32_bf16 v[42:45], v[154:157], v[188:191], v[42:45]
	v_mfma_f32_16x16x32_bf16 v[30:33], v[146:149], v[196:199], v[30:33]
	v_mfma_f32_16x16x32_bf16 v[26:29], v[154:157], v[196:199], v[26:29]
	v_mfma_f32_16x16x32_bf16 v[14:17], v[146:149], v[204:207], v[14:17]
	v_mfma_f32_16x16x32_bf16 v[10:13], v[154:157], v[204:207], v[10:13]
	s_setprio 0
	s_setprio 1
	v_mfma_f32_16x16x32_bf16 v[62:65], v[150:153], v[184:187], v[62:65]
	v_mfma_f32_16x16x32_bf16 v[58:61], v[158:161], v[184:187], v[58:61]
	v_mfma_f32_16x16x32_bf16 v[46:49], v[150:153], v[192:195], v[46:49]
	v_mfma_f32_16x16x32_bf16 v[42:45], v[158:161], v[192:195], v[42:45]
	v_mfma_f32_16x16x32_bf16 v[30:33], v[150:153], v[200:203], v[30:33]
	v_mfma_f32_16x16x32_bf16 v[26:29], v[158:161], v[200:203], v[26:29]
	v_mfma_f32_16x16x32_bf16 v[14:17], v[150:153], v[208:211], v[14:17]
	v_mfma_f32_16x16x32_bf16 v[10:13], v[158:161], v[208:211], v[10:13]
	s_setprio 0
	s_setprio 1
	v_mfma_f32_16x16x32_bf16 v[54:57], v[162:165], v[180:183], v[54:57]
	v_mfma_f32_16x16x32_bf16 v[50:53], v[170:173], v[180:183], v[50:53]
	v_mfma_f32_16x16x32_bf16 v[38:41], v[162:165], v[188:191], v[38:41]
	v_mfma_f32_16x16x32_bf16 v[34:37], v[170:173], v[188:191], v[34:37]
	v_mfma_f32_16x16x32_bf16 v[22:25], v[162:165], v[196:199], v[22:25]
	v_mfma_f32_16x16x32_bf16 v[18:21], v[170:173], v[196:199], v[18:21]
	v_mfma_f32_16x16x32_bf16 v[6:9], v[162:165], v[204:207], v[6:9]
	v_mfma_f32_16x16x32_bf16 v[2:5], v[170:173], v[204:207], v[2:5]
	s_setprio 0
	s_setprio 1
	v_mfma_f32_16x16x32_bf16 v[54:57], v[166:169], v[184:187], v[54:57]
	v_mfma_f32_16x16x32_bf16 v[50:53], v[174:177], v[184:187], v[50:53]
	v_mfma_f32_16x16x32_bf16 v[38:41], v[166:169], v[192:195], v[38:41]
	v_mfma_f32_16x16x32_bf16 v[34:37], v[174:177], v[192:195], v[34:37]
	v_mfma_f32_16x16x32_bf16 v[22:25], v[166:169], v[200:203], v[22:25]
	v_mfma_f32_16x16x32_bf16 v[18:21], v[174:177], v[200:203], v[18:21]
	v_mfma_f32_16x16x32_bf16 v[6:9], v[166:169], v[208:211], v[6:9]
	v_mfma_f32_16x16x32_bf16 v[2:5], v[174:177], v[208:211], v[2:5]
	s_setprio 0
	s_barrier
	s_add_i32 s60, 0, 0x18000
	s_add_i32 s61, 0, 0x1c000
	v_add_u32_e32 v158, s60, v143
	v_add_u32_e32 v174, s61, v143
	ds_read_b128 v[146:149], v158
	ds_read_b128 v[150:153], v158 offset:1024
	ds_read_b128 v[154:157], v158 offset:2048
	ds_read_b128 v[158:161], v158 offset:3072
	ds_read_b128 v[162:165], v174
	ds_read_b128 v[166:169], v174 offset:1024
	ds_read_b128 v[170:173], v174 offset:2048
	ds_read_b128 v[174:177], v174 offset:3072
	s_add_u32 s20, s20, 0x80000
	s_addc_u32 s21, s21, 0
	s_mov_b32 m0, s37
	v_lshl_add_u64 v[218:219], s[20:21], 0, v[130:131]
	ds_read_b128 v[180:183], v145 offset:32768
	ds_read_b128 v[184:187], v145 offset:33792
	ds_read_b128 v[188:191], v145 offset:34816
	ds_read_b128 v[192:195], v145 offset:35840
	ds_read_b128 v[196:199], v145 offset:36864
	ds_read_b128 v[200:203], v145 offset:37888
	ds_read_b128 v[204:207], v145 offset:38912
	ds_read_b128 v[208:211], v145 offset:39936
	global_load_lds_dwordx4 v[218:219], off
	v_lshl_add_u64 v[218:219], s[20:21], 0, v[132:133]
	s_mov_b32 m0, s49
	s_nop 0
	global_load_lds_dwordx4 v[218:219], off
	s_waitcnt vmcnt(8)
	s_waitcnt lgkmcnt(0)
	s_barrier
	s_setprio 1
	s_waitcnt lgkmcnt(0)
	v_mfma_f32_16x16x32_bf16 v[126:129], v[146:149], v[180:183], v[126:129]
	v_mfma_f32_16x16x32_bf16 v[122:125], v[154:157], v[180:183], v[122:125]
	v_mfma_f32_16x16x32_bf16 v[110:113], v[146:149], v[188:191], v[110:113]
	v_mfma_f32_16x16x32_bf16 v[106:109], v[154:157], v[188:191], v[106:109]
	v_mfma_f32_16x16x32_bf16 v[94:97], v[146:149], v[196:199], v[94:97]
	v_mfma_f32_16x16x32_bf16 v[90:93], v[154:157], v[196:199], v[90:93]
	v_mfma_f32_16x16x32_bf16 v[78:81], v[146:149], v[204:207], v[78:81]
	v_mfma_f32_16x16x32_bf16 v[74:77], v[154:157], v[204:207], v[74:77]
	s_setprio 0
	s_setprio 1
	v_mfma_f32_16x16x32_bf16 v[126:129], v[150:153], v[184:187], v[126:129]
	v_mfma_f32_16x16x32_bf16 v[122:125], v[158:161], v[184:187], v[122:125]
	v_mfma_f32_16x16x32_bf16 v[110:113], v[150:153], v[192:195], v[110:113]
	v_mfma_f32_16x16x32_bf16 v[106:109], v[158:161], v[192:195], v[106:109]
	v_mfma_f32_16x16x32_bf16 v[94:97], v[150:153], v[200:203], v[94:97]
	v_mfma_f32_16x16x32_bf16 v[90:93], v[158:161], v[200:203], v[90:93]
	v_mfma_f32_16x16x32_bf16 v[78:81], v[150:153], v[208:211], v[78:81]
	v_mfma_f32_16x16x32_bf16 v[74:77], v[158:161], v[208:211], v[74:77]
	s_setprio 0
	s_setprio 1
	v_mfma_f32_16x16x32_bf16 v[118:121], v[162:165], v[180:183], v[118:121]
	v_mfma_f32_16x16x32_bf16 v[114:117], v[170:173], v[180:183], v[114:117]
	v_mfma_f32_16x16x32_bf16 v[102:105], v[162:165], v[188:191], v[102:105]
	v_mfma_f32_16x16x32_bf16 v[98:101], v[170:173], v[188:191], v[98:101]
	v_mfma_f32_16x16x32_bf16 v[86:89], v[162:165], v[196:199], v[86:89]
	v_mfma_f32_16x16x32_bf16 v[82:85], v[170:173], v[196:199], v[82:85]
	v_mfma_f32_16x16x32_bf16 v[70:73], v[162:165], v[204:207], v[70:73]
	v_mfma_f32_16x16x32_bf16 v[66:69], v[170:173], v[204:207], v[66:69]
	s_setprio 0
	s_setprio 1
	v_mfma_f32_16x16x32_bf16 v[118:121], v[166:169], v[184:187], v[118:121]
	v_mfma_f32_16x16x32_bf16 v[114:117], v[174:177], v[184:187], v[114:117]
	v_mfma_f32_16x16x32_bf16 v[102:105], v[166:169], v[192:195], v[102:105]
	v_mfma_f32_16x16x32_bf16 v[98:101], v[174:177], v[192:195], v[98:101]
	v_mfma_f32_16x16x32_bf16 v[86:89], v[166:169], v[200:203], v[86:89]
	v_mfma_f32_16x16x32_bf16 v[82:85], v[174:177], v[200:203], v[82:85]
	v_mfma_f32_16x16x32_bf16 v[70:73], v[166:169], v[208:211], v[70:73]
	v_mfma_f32_16x16x32_bf16 v[66:69], v[174:177], v[208:211], v[66:69]
	s_setprio 0
	s_barrier
; #define PG8_STAGE(bufoff, gbase, voff) do { _Pragma("unroll") for (int _i = 0; _i < 2; ++_i) \
;         __builtin_amdgcn_global_load_lds((const unsigned*)((const char*)(gbase) + (voff)[_i]), (PG8_LAS unsigned*)(lds + (bufoff) + ldsw + _i * 8192), 16, 0, 0); } while (0)
; #define PG8_LDA(dst, b, h) do { _Pragma("unroll") for (int m = 0; m < 4; ++m) _Pragma("unroll") for (int k = 0; k < 2; ++k) dst[m][k] = *(const PG8_LAS bf16x8*)(lds + PG8_SA(b, h) + aoff + m * 2048 + k * 1024); } while (0)
; #define PG8_MMA(ai, bj, At, Bt) do { __builtin_amdgcn_s_setprio(1); _Pragma("unroll") for (int m = 0; m < 4; ++m) _Pragma("unroll") for (int n = 0; n < 2; ++n) _Pragma("unroll") for (int k = 0; k < 2; ++k) \
;         acc[ai][bj][m][n] = __builtin_amdgcn_mfma_f32_16x16x32_bf16(Bt[n][k], At[m][k], acc[ai][bj][m][n], 0, 0, 0); __builtin_amdgcn_s_setprio(0); } while (0)
; #define PG8_WAIT_V(n) asm volatile("s_waitcnt vmcnt(" #n ")" ::: "memory")
; #define PG8_WAIT_L(n) asm volatile("s_waitcnt lgkmcnt(" #n ")" ::: "memory")
; #define PG8_BAR __builtin_amdgcn_s_barrier()
; #define PG8_SCHED __builtin_amdgcn_sched_barrier(0)
; template <class Epi, class Sched, bool ALIGN_EPI = true, bool SP2 = true, bool GS = false>
; __device__ __forceinline__ void gemm_phase(PG8_LAS unsigned char* lds, const Gemm g, const Sched& S, const Epi& E, const float* gs_ss = nullptr) {
;     ...
;             PG8_LDA(At, 1, 1); PG8_STAGE(PG8_SB(1, 0), b3, voffB); PG8_STAGE(PG8_SB(1, 1), b3 + hstep, voffB); PG8_STAGE(PG8_SA(1, 0), a3, voffA);
;             PG8_WAIT_V(8); PG8_WAIT_L(0); PG8_BAR; PG8_MMA(1, 0, At, B0); PG8_MMA(1, 1, At, B1); PG8_BAR; PG8_SCHED;
;     ...
;         }
;         if constexpr (ALIGN_EPI) { if (wr == 0) PG8_BAR; }
	s_add_i32 s20, s60, s25
	v_lshl_add_u64 v[140:141], v[140:141], 0, s[26:27]
	s_mov_b32 m0, s20
	ds_read_b128 v[180:183], v145 offset:49152
	ds_read_b128 v[184:187], v145 offset:50176
	ds_read_b128 v[188:191], v145 offset:51200
	ds_read_b128 v[192:195], v145 offset:52224
	ds_read_b128 v[196:199], v145 offset:53248
	ds_read_b128 v[200:203], v145 offset:54272
	ds_read_b128 v[204:207], v145 offset:55296
	ds_read_b128 v[208:211], v145 offset:56320
	global_load_lds_dwordx4 v[140:141], off
	s_add_i32 m0, s20, 0x2000
	s_add_u32 s2, s2, 0x80080
	v_lshl_add_u64 v[140:141], v[212:213], 0, s[26:27]
	s_addc_u32 s3, s3, 0
	s_add_i32 s20, s61, s25
	global_load_lds_dwordx4 v[140:141], off
	v_lshl_add_u64 v[140:141], s[2:3], 0, v[0:1]
	s_mov_b32 m0, s20
	s_nop 0
	global_load_lds_dwordx4 v[140:141], off
	v_lshl_add_u64 v[140:141], s[2:3], 0, v[134:135]
	s_add_i32 m0, s20, 0x2000
	s_nop 0
	global_load_lds_dwordx4 v[140:141], off
	v_lshl_add_u64 v[140:141], v[214:215], 0, s[26:27]
	s_mov_b32 m0, s18
	s_nop 0
	global_load_lds_dwordx4 v[140:141], off
	v_lshl_add_u64 v[140:141], v[216:217], 0, s[26:27]
	s_mov_b32 m0, s54
	s_nop 0
	global_load_lds_dwordx4 v[140:141], off
	s_waitcnt vmcnt(8)
	s_waitcnt lgkmcnt(0)
	s_barrier
	s_setprio 1
	s_waitcnt lgkmcnt(0)
	v_mfma_f32_16x16x32_bf16 v[62:65], v[146:149], v[180:183], v[62:65]
	v_mfma_f32_16x16x32_bf16 v[58:61], v[154:157], v[180:183], v[58:61]
	v_mfma_f32_16x16x32_bf16 v[46:49], v[146:149], v[188:191], v[46:49]
	v_mfma_f32_16x16x32_bf16 v[42:45], v[154:157], v[188:191], v[42:45]
	v_mfma_f32_16x16x32_bf16 v[30:33], v[146:149], v[196:199], v[30:33]
	v_mfma_f32_16x16x32_bf16 v[26:29], v[154:157], v[196:199], v[26:29]
	v_mfma_f32_16x16x32_bf16 v[14:17], v[146:149], v[204:207], v[14:17]
	v_mfma_f32_16x16x32_bf16 v[10:13], v[154:157], v[204:207], v[10:13]
	s_setprio 0
	s_setprio 1
	v_mfma_f32_16x16x32_bf16 v[62:65], v[150:153], v[184:187], v[62:65]
	v_mfma_f32_16x16x32_bf16 v[58:61], v[158:161], v[184:187], v[58:61]
	v_mfma_f32_16x16x32_bf16 v[46:49], v[150:153], v[192:195], v[46:49]
	v_mfma_f32_16x16x32_bf16 v[42:45], v[158:161], v[192:195], v[42:45]
	v_mfma_f32_16x16x32_bf16 v[30:33], v[150:153], v[200:203], v[30:33]
	v_mfma_f32_16x16x32_bf16 v[26:29], v[158:161], v[200:203], v[26:29]
	v_mfma_f32_16x16x32_bf16 v[14:17], v[150:153], v[208:211], v[14:17]
	v_mfma_f32_16x16x32_bf16 v[10:13], v[158:161], v[208:211], v[10:13]
	s_setprio 0
	s_setprio 1
	v_mfma_f32_16x16x32_bf16 v[54:57], v[162:165], v[180:183], v[54:57]
	v_mfma_f32_16x16x32_bf16 v[50:53], v[170:173], v[180:183], v[50:53]
	v_mfma_f32_16x16x32_bf16 v[38:41], v[162:165], v[188:191], v[38:41]
	v_mfma_f32_16x16x32_bf16 v[34:37], v[170:173], v[188:191], v[34:37]
	v_mfma_f32_16x16x32_bf16 v[22:25], v[162:165], v[196:199], v[22:25]
	v_mfma_f32_16x16x32_bf16 v[18:21], v[170:173], v[196:199], v[18:21]
	v_mfma_f32_16x16x32_bf16 v[6:9], v[162:165], v[204:207], v[6:9]
	v_mfma_f32_16x16x32_bf16 v[2:5], v[170:173], v[204:207], v[2:5]
	s_setprio 0
	s_setprio 1
	v_mfma_f32_16x16x32_bf16 v[54:57], v[166:169], v[184:187], v[54:57]
	v_mfma_f32_16x16x32_bf16 v[50:53], v[174:177], v[184:187], v[50:53]
	v_mfma_f32_16x16x32_bf16 v[38:41], v[166:169], v[192:195], v[38:41]
	v_mfma_f32_16x16x32_bf16 v[34:37], v[174:177], v[192:195], v[34:37]
	v_mfma_f32_16x16x32_bf16 v[22:25], v[166:169], v[200:203], v[22:25]
	v_mfma_f32_16x16x32_bf16 v[18:21], v[174:177], v[200:203], v[18:21]
	v_mfma_f32_16x16x32_bf16 v[6:9], v[166:169], v[208:211], v[6:9]
	v_mfma_f32_16x16x32_bf16 v[2:5], v[174:177], v[208:211], v[2:5]
	s_setprio 0
	s_barrier
	s_add_i32 s59, s59, 2
	s_add_u32 s50, s50, 0x100
	s_addc_u32 s51, s51, 0
	s_add_u32 s52, s52, 0x100
	s_addc_u32 s53, s53, 0
	s_cmp_gt_u32 s59, 29
	s_cbranch_scc0 .LBB0_1344
	s_and_b64 vcc, exec, s[34:35]
	s_cbranch_vccz .LBB0_1347
	s_barrier

;     __device__ bool next(int i, Unit& u) const { const int L = i * G + c; if (L >= 192) return false; u.pm = L / 6; u.pn = L % 6; return true; }
;     __device__ __forceinline__ size_t a_extra(const Unit& u) const { return (size_t)(u.pn >> 1) * ((size_t)T * 512 * 2); }
;     __device__ bool next(int i, Unit& u) const { const int L = i * G + c; if (L >= 256) return false; u.pm = L >> 3; u.pn = L & 7; return true; }
;     __device__ __forceinline__ size_t a_extra(const Unit& u) const { return (size_t)(u.pn >> 1) * 512 * 2; }
;     __device__ __forceinline__ size_t b_extra(const Unit& u) const { return (size_t)(u.pn >> 1) * 512 * 2 - (size_t)(u.pn & ~1) * ((size_t)256 * D * 2); }
; #define PG8_STAGE(bufoff, gbase, voff) do { _Pragma("unroll") for (int _i = 0; _i < 2; ++_i) \
;         __builtin_amdgcn_global_load_lds((const unsigned*)((const char*)(gbase) + (voff)[_i]), (PG8_LAS unsigned*)(lds + (bufoff) + ldsw + _i * 8192), 16, 0, 0); } while (0)
; template <class Epi, class Sched, bool ALIGN_EPI = true, bool SP2 = true, bool GS = false>
; __device__ __forceinline__ void gemm_phase(PG8_LAS unsigned char* lds, const Gemm g, const Sched& S, const Epi& E, const float* gs_ss = nullptr) {
;     ...
;         const bool has_next = S.next(ui + 1, nxt);
;         const char* nA = has_next ? (const char*)g.A + S.a_extra(nxt) + (size_t)nxt.pm * tstep : cA; const char* nB = has_next ? (const char*)g.Bt + S.b_extra(nxt) + (size_t)nxt.pn * tstep : cB;
;         for (int t = 0; t < nt; t += 2) {
;             const bool last = (t == nt - 2);
;             const char* a1 = cA + (size_t)(t + 1) * kstep;
;             const char* a2 = last ? nA : cA + (size_t)(t + 2) * kstep; const char* b2 = last ? nB : cB + (size_t)(t + 2) * kstep;
;             const char* a3 = a2 + kstep; const char* b3 = b2 + kstep;
;             if constexpr (SP2) {
;             PG8_LDB(B0, 0, 0); PG8_LDB(B1, 0, 1); PG8_SCHED; PG8_LDA(At, 0, 0); PG8_STAGE(PG8_SA(1, 1), a1 + hstep, voffA);
;             PG8_WAIT_V(8); PG8_WAIT_L(0); PG8_BAR; PG8_MMA(0, 0, At, B0); PG8_MMA(0, 1, At, B1); PG8_BAR; PG8_SCHED;
;             PG8_LDA(At, 0, 1); PG8_STAGE(PG8_SB(0, 0), b2, voffB); PG8_STAGE(PG8_SB(0, 1), b2 + hstep, voffB); PG8_STAGE(PG8_SA(0, 0), a2, voffA);
;             PG8_WAIT_V(8); PG8_WAIT_L(0); PG8_BAR; PG8_MMA(1, 0, At, B0); PG8_MMA(1, 1, At, B1); PG8_BAR; PG8_SCHED;
.LBB0_1422:
	s_add_u32 s2, s56, 0xffe00080
	s_addc_u32 s3, s57, -1
	s_add_i32 s65, 0, 0x10000
	s_cmpk_eq_i32 s64, 0x7c
	s_cselect_b32 s21, s18, s3
	s_cselect_b32 s20, s51, s2
	s_cselect_b32 s3, s49, s59
	s_cselect_b32 s2, s63, s58
	s_add_i32 s67, 0, 0x14000
	v_add_u32_e32 v142, s65, v236
	v_add_u32_e32 v170, s67, v236
	ds_read_b128 v[130:133], v142
	ds_read_b128 v[134:137], v142 offset:1024
	ds_read_b128 v[138:141], v142 offset:2048
	ds_read_b128 v[142:145], v142 offset:3072
	ds_read_b128 v[158:161], v170
	ds_read_b128 v[162:165], v170 offset:1024
	ds_read_b128 v[166:169], v170 offset:2048
	ds_read_b128 v[170:173], v170 offset:3072
	v_lshl_add_u64 v[180:181], s[56:57], 0, v[154:155]
	s_add_i32 m0, s9, 0xc000
	ds_read_b128 v[174:177], v238
	ds_read_b128 v[184:187], v238 offset:1024
	ds_read_b128 v[188:191], v238 offset:2048
	ds_read_b128 v[192:195], v238 offset:3072
	ds_read_b128 v[196:199], v238 offset:4096
	ds_read_b128 v[200:203], v238 offset:5120
	ds_read_b128 v[204:207], v238 offset:6144
	ds_read_b128 v[208:211], v238 offset:7168
	global_load_lds_dwordx4 v[180:181], off
	v_lshl_add_u64 v[180:181], s[56:57], 0, v[156:157]
	s_add_i32 m0, s9, 0xe000
	s_nop 0
	global_load_lds_dwordx4 v[180:181], off
	s_waitcnt vmcnt(8)
	s_waitcnt lgkmcnt(0)
	s_barrier
	s_setprio 1
	s_waitcnt lgkmcnt(0)
	v_mfma_f32_16x16x32_bf16 v[126:129], v[130:133], v[174:177], v[126:129]
	v_mfma_f32_16x16x32_bf16 v[122:125], v[138:141], v[174:177], v[122:125]
	v_mfma_f32_16x16x32_bf16 v[110:113], v[130:133], v[188:191], v[110:113]
	v_mfma_f32_16x16x32_bf16 v[106:109], v[138:141], v[188:191], v[106:109]
	v_mfma_f32_16x16x32_bf16 v[94:97], v[130:133], v[196:199], v[94:97]
	v_mfma_f32_16x16x32_bf16 v[90:93], v[138:141], v[196:199], v[90:93]
	v_mfma_f32_16x16x32_bf16 v[78:81], v[130:133], v[204:207], v[78:81]
	v_mfma_f32_16x16x32_bf16 v[74:77], v[138:141], v[204:207], v[74:77]
	s_setprio 0
	s_setprio 1
	v_mfma_f32_16x16x32_bf16 v[126:129], v[134:137], v[184:187], v[126:129]
	v_mfma_f32_16x16x32_bf16 v[122:125], v[142:145], v[184:187], v[122:125]
	v_mfma_f32_16x16x32_bf16 v[110:113], v[134:137], v[192:195], v[110:113]
	v_mfma_f32_16x16x32_bf16 v[106:109], v[142:145], v[192:195], v[106:109]
	v_mfma_f32_16x16x32_bf16 v[94:97], v[134:137], v[200:203], v[94:97]
	v_mfma_f32_16x16x32_bf16 v[90:93], v[142:145], v[200:203], v[90:93]
	v_mfma_f32_16x16x32_bf16 v[78:81], v[134:137], v[208:211], v[78:81]
	v_mfma_f32_16x16x32_bf16 v[74:77], v[142:145], v[208:211], v[74:77]
	s_setprio 0
	s_setprio 1
	v_mfma_f32_16x16x32_bf16 v[118:121], v[158:161], v[174:177], v[118:121]
	v_mfma_f32_16x16x32_bf16 v[114:117], v[166:169], v[174:177], v[114:117]
	v_mfma_f32_16x16x32_bf16 v[102:105], v[158:161], v[188:191], v[102:105]
	v_mfma_f32_16x16x32_bf16 v[98:101], v[166:169], v[188:191], v[98:101]
	v_mfma_f32_16x16x32_bf16 v[86:89], v[158:161], v[196:199], v[86:89]
	v_mfma_f32_16x16x32_bf16 v[82:85], v[166:169], v[196:199], v[82:85]
	v_mfma_f32_16x16x32_bf16 v[70:73], v[158:161], v[204:207], v[70:73]
	v_mfma_f32_16x16x32_bf16 v[66:69], v[166:169], v[204:207], v[66:69]
	s_setprio 0
	s_setprio 1
	v_mfma_f32_16x16x32_bf16 v[118:121], v[162:165], v[184:187], v[118:121]
	v_mfma_f32_16x16x32_bf16 v[114:117], v[170:173], v[184:187], v[114:117]
	v_mfma_f32_16x16x32_bf16 v[102:105], v[162:165], v[192:195], v[102:105]
	v_mfma_f32_16x16x32_bf16 v[98:101], v[170:173], v[192:195], v[98:101]
	v_mfma_f32_16x16x32_bf16 v[86:89], v[162:165], v[200:203], v[86:89]
	v_mfma_f32_16x16x32_bf16 v[82:85], v[170:173], v[200:203], v[82:85]
	v_mfma_f32_16x16x32_bf16 v[70:73], v[162:165], v[208:211], v[70:73]
	v_mfma_f32_16x16x32_bf16 v[66:69], v[170:173], v[208:211], v[66:69]
	s_setprio 0
	s_barrier
	s_add_i32 s65, s65, s24
	v_lshl_add_u64 v[180:181], s[2:3], 0, v[0:1]
	s_mov_b32 m0, s65
	ds_read_b128 v[174:177], v238 offset:16384
	ds_read_b128 v[184:187], v238 offset:17408
	ds_read_b128 v[188:191], v238 offset:18432
	ds_read_b128 v[192:195], v238 offset:19456
	ds_read_b128 v[196:199], v238 offset:20480
	ds_read_b128 v[200:203], v238 offset:21504
	ds_read_b128 v[204:207], v238 offset:22528
	ds_read_b128 v[208:211], v238 offset:23552
	global_load_lds_dwordx4 v[180:181], off
	s_add_i32 m0, s65, 0x2000
	s_add_u32 s70, s2, 0x200000
	v_lshl_add_u64 v[212:213], s[2:3], 0, v[150:151]
	s_addc_u32 s71, s3, 0
	s_add_i32 s65, s67, s24
	global_load_lds_dwordx4 v[212:213], off
	v_lshl_add_u64 v[214:215], s[70:71], 0, v[0:1]
	s_mov_b32 m0, s65
	v_lshl_add_u64 v[216:217], s[20:21], 0, v[148:149]
	global_load_lds_dwordx4 v[214:215], off
	v_lshl_add_u64 v[214:215], s[70:71], 0, v[150:151]
	s_add_i32 m0, s65, 0x2000
	s_nop 0
	global_load_lds_dwordx4 v[214:215], off
	v_lshl_add_u64 v[214:215], s[20:21], 0, v[146:147]
	s_mov_b32 m0, s9
	s_nop 0
	global_load_lds_dwordx4 v[214:215], off
	s_mov_b32 m0, s13
	s_nop 0
	global_load_lds_dwordx4 v[216:217], off
	s_waitcnt vmcnt(8)
	s_waitcnt lgkmcnt(0)
	s_barrier
; #define PG8_STAGE(bufoff, gbase, voff) do { _Pragma("unroll") for (int _i = 0; _i < 2; ++_i) \
;         __builtin_amdgcn_global_load_lds((const unsigned*)((const char*)(gbase) + (voff)[_i]), (PG8_LAS unsigned*)(lds + (bufoff) + ldsw + _i * 8192), 16, 0, 0); } while (0)
; #define PG8_LDA(dst, b, h) do { _Pragma("unroll") for (int m = 0; m < 4; ++m) _Pragma("unroll") for (int k = 0; k < 2; ++k) dst[m][k] = *(const PG8_LAS bf16x8*)(lds + PG8_SA(b, h) + aoff + m * 2048 + k * 1024); } while (0)
; #define PG8_LDB(dst, b, h) do { _Pragma("unroll") for (int n = 0; n < 2; ++n) _Pragma("unroll") for (int k = 0; k < 2; ++k) dst[n][k] = *(const PG8_LAS bf16x8*)(lds + PG8_SB(b, h) + boff + n * 2048 + k * 1024); } while (0)
; #define PG8_MMA(ai, bj, At, Bt) do { __builtin_amdgcn_s_setprio(1); _Pragma("unroll") for (int m = 0; m < 4; ++m) _Pragma("unroll") for (int n = 0; n < 2; ++n) _Pragma("unroll") for (int k = 0; k < 2; ++k) \
;         acc[ai][bj][m][n] = __builtin_amdgcn_mfma_f32_16x16x32_bf16(Bt[n][k], At[m][k], acc[ai][bj][m][n], 0, 0, 0); __builtin_amdgcn_s_setprio(0); } while (0)
; #define PG8_WAIT_V(n) asm volatile("s_waitcnt vmcnt(" #n ")" ::: "memory")
; #define PG8_WAIT_L(n) asm volatile("s_waitcnt lgkmcnt(" #n ")" ::: "memory")
; #define PG8_BAR __builtin_amdgcn_s_barrier()
; #define PG8_SCHED __builtin_amdgcn_sched_barrier(0)
; template <class Epi, class Sched, bool ALIGN_EPI = true, bool SP2 = true, bool GS = false>
; __device__ __forceinline__ void gemm_phase(PG8_LAS unsigned char* lds, const Gemm g, const Sched& S, const Epi& E, const float* gs_ss = nullptr) {
;     ...
;             PG8_WAIT_V(8); PG8_WAIT_L(0); PG8_BAR; PG8_MMA(1, 0, At, B0); PG8_MMA(1, 1, At, B1); PG8_BAR; PG8_SCHED;
;             PG8_LDB(B0, 1, 0); PG8_LDB(B1, 1, 1); PG8_SCHED; PG8_LDA(At, 1, 0); PG8_STAGE(PG8_SA(0, 1), a2 + hstep, voffA);
;             PG8_WAIT_V(8); PG8_WAIT_L(0); PG8_BAR; PG8_MMA(0, 0, At, B0); PG8_MMA(0, 1, At, B1); PG8_BAR; PG8_SCHED;
	s_setprio 1
	s_waitcnt lgkmcnt(0)
	v_mfma_f32_16x16x32_bf16 v[62:65], v[130:133], v[174:177], v[62:65]
	v_mfma_f32_16x16x32_bf16 v[58:61], v[138:141], v[174:177], v[58:61]
	v_mfma_f32_16x16x32_bf16 v[46:49], v[130:133], v[188:191], v[46:49]
	v_mfma_f32_16x16x32_bf16 v[42:45], v[138:141], v[188:191], v[42:45]
	v_mfma_f32_16x16x32_bf16 v[30:33], v[130:133], v[196:199], v[30:33]
	v_mfma_f32_16x16x32_bf16 v[26:29], v[138:141], v[196:199], v[26:29]
	v_mfma_f32_16x16x32_bf16 v[14:17], v[130:133], v[204:207], v[14:17]
	v_mfma_f32_16x16x32_bf16 v[10:13], v[138:141], v[204:207], v[10:13]
	s_setprio 0
	s_setprio 1
	v_mfma_f32_16x16x32_bf16 v[62:65], v[134:137], v[184:187], v[62:65]
	v_mfma_f32_16x16x32_bf16 v[58:61], v[142:145], v[184:187], v[58:61]
	v_mfma_f32_16x16x32_bf16 v[46:49], v[134:137], v[192:195], v[46:49]
	v_mfma_f32_16x16x32_bf16 v[42:45], v[142:145], v[192:195], v[42:45]
	v_mfma_f32_16x16x32_bf16 v[30:33], v[134:137], v[200:203], v[30:33]
	v_mfma_f32_16x16x32_bf16 v[26:29], v[142:145], v[200:203], v[26:29]
	v_mfma_f32_16x16x32_bf16 v[14:17], v[134:137], v[208:211], v[14:17]
	v_mfma_f32_16x16x32_bf16 v[10:13], v[142:145], v[208:211], v[10:13]
	s_setprio 0
	s_setprio 1
	v_mfma_f32_16x16x32_bf16 v[54:57], v[158:161], v[174:177], v[54:57]
	v_mfma_f32_16x16x32_bf16 v[50:53], v[166:169], v[174:177], v[50:53]
	v_mfma_f32_16x16x32_bf16 v[38:41], v[158:161], v[188:191], v[38:41]
	v_mfma_f32_16x16x32_bf16 v[34:37], v[166:169], v[188:191], v[34:37]
	v_mfma_f32_16x16x32_bf16 v[22:25], v[158:161], v[196:199], v[22:25]
	v_mfma_f32_16x16x32_bf16 v[18:21], v[166:169], v[196:199], v[18:21]
	v_mfma_f32_16x16x32_bf16 v[6:9], v[158:161], v[204:207], v[6:9]
	v_mfma_f32_16x16x32_bf16 v[2:5], v[166:169], v[204:207], v[2:5]
	s_setprio 0
	s_setprio 1
	v_mfma_f32_16x16x32_bf16 v[54:57], v[162:165], v[184:187], v[54:57]
	v_mfma_f32_16x16x32_bf16 v[50:53], v[170:173], v[184:187], v[50:53]
	v_mfma_f32_16x16x32_bf16 v[38:41], v[162:165], v[192:195], v[38:41]
	v_mfma_f32_16x16x32_bf16 v[34:37], v[170:173], v[192:195], v[34:37]
	v_mfma_f32_16x16x32_bf16 v[22:25], v[162:165], v[200:203], v[22:25]
	v_mfma_f32_16x16x32_bf16 v[18:21], v[170:173], v[200:203], v[18:21]
	v_mfma_f32_16x16x32_bf16 v[6:9], v[162:165], v[208:211], v[6:9]
	v_mfma_f32_16x16x32_bf16 v[2:5], v[170:173], v[208:211], v[2:5]
	s_setprio 0
	s_barrier
	s_add_i32 s65, 0, 0x18000
	s_add_i32 s67, 0, 0x1c000
	v_add_u32_e32 v142, s65, v236
	v_add_u32_e32 v170, s67, v236
	ds_read_b128 v[130:133], v142
	ds_read_b128 v[134:137], v142 offset:1024
	ds_read_b128 v[138:141], v142 offset:2048
	ds_read_b128 v[142:145], v142 offset:3072
	ds_read_b128 v[158:161], v170
	ds_read_b128 v[162:165], v170 offset:1024
	ds_read_b128 v[166:169], v170 offset:2048
	ds_read_b128 v[170:173], v170 offset:3072
	s_add_u32 s20, s20, 0x200000
	s_addc_u32 s21, s21, 0
	s_mov_b32 m0, s25
	v_lshl_add_u64 v[218:219], s[20:21], 0, v[146:147]
	ds_read_b128 v[174:177], v238 offset:32768
	ds_read_b128 v[184:187], v238 offset:33792
	ds_read_b128 v[188:191], v238 offset:34816
	ds_read_b128 v[192:195], v238 offset:35840
	ds_read_b128 v[196:199], v238 offset:36864
	ds_read_b128 v[200:203], v238 offset:37888
	ds_read_b128 v[204:207], v238 offset:38912
	ds_read_b128 v[208:211], v238 offset:39936
	global_load_lds_dwordx4 v[218:219], off
	v_lshl_add_u64 v[218:219], s[20:21], 0, v[148:149]
	s_mov_b32 m0, s30
	s_nop 0
	global_load_lds_dwordx4 v[218:219], off
	s_waitcnt vmcnt(8)
	s_waitcnt lgkmcnt(0)
	s_barrier
	s_setprio 1
	s_waitcnt lgkmcnt(0)
	v_mfma_f32_16x16x32_bf16 v[126:129], v[130:133], v[174:177], v[126:129]
	v_mfma_f32_16x16x32_bf16 v[122:125], v[138:141], v[174:177], v[122:125]
	v_mfma_f32_16x16x32_bf16 v[110:113], v[130:133], v[188:191], v[110:113]
	v_mfma_f32_16x16x32_bf16 v[106:109], v[138:141], v[188:191], v[106:109]
	v_mfma_f32_16x16x32_bf16 v[94:97], v[130:133], v[196:199], v[94:97]
	v_mfma_f32_16x16x32_bf16 v[90:93], v[138:141], v[196:199], v[90:93]
	v_mfma_f32_16x16x32_bf16 v[78:81], v[130:133], v[204:207], v[78:81]
	v_mfma_f32_16x16x32_bf16 v[74:77], v[138:141], v[204:207], v[74:77]
	s_setprio 0
	s_setprio 1
	v_mfma_f32_16x16x32_bf16 v[126:129], v[134:137], v[184:187], v[126:129]
	v_mfma_f32_16x16x32_bf16 v[122:125], v[142:145], v[184:187], v[122:125]
	v_mfma_f32_16x16x32_bf16 v[110:113], v[134:137], v[192:195], v[110:113]
	v_mfma_f32_16x16x32_bf16 v[106:109], v[142:145], v[192:195], v[106:109]
	v_mfma_f32_16x16x32_bf16 v[94:97], v[134:137], v[200:203], v[94:97]
	v_mfma_f32_16x16x32_bf16 v[90:93], v[142:145], v[200:203], v[90:93]
	v_mfma_f32_16x16x32_bf16 v[78:81], v[134:137], v[208:211], v[78:81]
	v_mfma_f32_16x16x32_bf16 v[74:77], v[142:145], v[208:211], v[74:77]
	s_setprio 0
	s_setprio 1
	v_mfma_f32_16x16x32_bf16 v[118:121], v[158:161], v[174:177], v[118:121]
	v_mfma_f32_16x16x32_bf16 v[114:117], v[166:169], v[174:177], v[114:117]
	v_mfma_f32_16x16x32_bf16 v[102:105], v[158:161], v[188:191], v[102:105]
	v_mfma_f32_16x16x32_bf16 v[98:101], v[166:169], v[188:191], v[98:101]
	v_mfma_f32_16x16x32_bf16 v[86:89], v[158:161], v[196:199], v[86:89]
	v_mfma_f32_16x16x32_bf16 v[82:85], v[166:169], v[196:199], v[82:85]
	v_mfma_f32_16x16x32_bf16 v[70:73], v[158:161], v[204:207], v[70:73]
	v_mfma_f32_16x16x32_bf16 v[66:69], v[166:169], v[204:207], v[66:69]
	s_setprio 0
	s_setprio 1
	v_mfma_f32_16x16x32_bf16 v[118:121], v[162:165], v[184:187], v[118:121]
	v_mfma_f32_16x16x32_bf16 v[114:117], v[170:173], v[184:187], v[114:117]
	v_mfma_f32_16x16x32_bf16 v[102:105], v[162:165], v[192:195], v[102:105]
	v_mfma_f32_16x16x32_bf16 v[98:101], v[170:173], v[192:195], v[98:101]
	v_mfma_f32_16x16x32_bf16 v[86:89], v[162:165], v[200:203], v[86:89]
	v_mfma_f32_16x16x32_bf16 v[82:85], v[170:173], v[200:203], v[82:85]
	v_mfma_f32_16x16x32_bf16 v[70:73], v[162:165], v[208:211], v[70:73]
	v_mfma_f32_16x16x32_bf16 v[66:69], v[170:173], v[208:211], v[66:69]
	s_setprio 0
	s_barrier
; #define PG8_STAGE(bufoff, gbase, voff) do { _Pragma("unroll") for (int _i = 0; _i < 2; ++_i) \
;         __builtin_amdgcn_global_load_lds((const unsigned*)((const char*)(gbase) + (voff)[_i]), (PG8_LAS unsigned*)(lds + (bufoff) + ldsw + _i * 8192), 16, 0, 0); } while (0)
; #define PG8_LDA(dst, b, h) do { _Pragma("unroll") for (int m = 0; m < 4; ++m) _Pragma("unroll") for (int k = 0; k < 2; ++k) dst[m][k] = *(const PG8_LAS bf16x8*)(lds + PG8_SA(b, h) + aoff + m * 2048 + k * 1024); } while (0)
; #define PG8_MMA(ai, bj, At, Bt) do { __builtin_amdgcn_s_setprio(1); _Pragma("unroll") for (int m = 0; m < 4; ++m) _Pragma("unroll") for (int n = 0; n < 2; ++n) _Pragma("unroll") for (int k = 0; k < 2; ++k) \
;         acc[ai][bj][m][n] = __builtin_amdgcn_mfma_f32_16x16x32_bf16(Bt[n][k], At[m][k], acc[ai][bj][m][n], 0, 0, 0); __builtin_amdgcn_s_setprio(0); } while (0)
; #define PG8_WAIT_V(n) asm volatile("s_waitcnt vmcnt(" #n ")" ::: "memory")
; #define PG8_WAIT_L(n) asm volatile("s_waitcnt lgkmcnt(" #n ")" ::: "memory")
; #define PG8_BAR __builtin_amdgcn_s_barrier()
; #define PG8_SCHED __builtin_amdgcn_sched_barrier(0)
; template <class Epi, class Sched, bool ALIGN_EPI = true, bool SP2 = true, bool GS = false>
; __device__ __forceinline__ void gemm_phase(PG8_LAS unsigned char* lds, const Gemm g, const Sched& S, const Epi& E, const float* gs_ss = nullptr) {
;     ...
;             PG8_LDA(At, 1, 1); PG8_STAGE(PG8_SB(1, 0), b3, voffB); PG8_STAGE(PG8_SB(1, 1), b3 + hstep, voffB); PG8_STAGE(PG8_SA(1, 0), a3, voffA);
;             PG8_WAIT_V(8); PG8_WAIT_L(0); PG8_BAR; PG8_MMA(1, 0, At, B0); PG8_MMA(1, 1, At, B1); PG8_BAR; PG8_SCHED;
;     ...
;         }
;         if constexpr (ALIGN_EPI) { if (wr == 0) PG8_BAR; }
	s_add_i32 s20, s65, s24
	v_lshl_add_u64 v[180:181], v[180:181], 0, s[26:27]
	s_mov_b32 m0, s20
	ds_read_b128 v[174:177], v238 offset:49152
	ds_read_b128 v[184:187], v238 offset:50176
	ds_read_b128 v[188:191], v238 offset:51200
	ds_read_b128 v[192:195], v238 offset:52224
	ds_read_b128 v[196:199], v238 offset:53248
	ds_read_b128 v[200:203], v238 offset:54272
	ds_read_b128 v[204:207], v238 offset:55296
	ds_read_b128 v[208:211], v238 offset:56320
	global_load_lds_dwordx4 v[180:181], off
	s_add_i32 m0, s20, 0x2000
	s_add_u32 s2, s2, 0x200080
	v_lshl_add_u64 v[180:181], v[212:213], 0, s[26:27]
	s_addc_u32 s3, s3, 0
	s_add_i32 s20, s67, s24
	global_load_lds_dwordx4 v[180:181], off
	v_lshl_add_u64 v[180:181], s[2:3], 0, v[0:1]
	s_mov_b32 m0, s20
	s_nop 0
	global_load_lds_dwordx4 v[180:181], off
	v_lshl_add_u64 v[180:181], s[2:3], 0, v[150:151]
	s_add_i32 m0, s20, 0x2000
	s_nop 0
	global_load_lds_dwordx4 v[180:181], off
	v_lshl_add_u64 v[180:181], v[214:215], 0, s[26:27]
	s_mov_b32 m0, s37
	s_nop 0
	global_load_lds_dwordx4 v[180:181], off
	v_lshl_add_u64 v[180:181], v[216:217], 0, s[26:27]
	s_mov_b32 m0, s60
	s_nop 0
	global_load_lds_dwordx4 v[180:181], off
	s_waitcnt vmcnt(8)
	s_waitcnt lgkmcnt(0)
	s_barrier
	s_setprio 1
	s_waitcnt lgkmcnt(0)
	v_mfma_f32_16x16x32_bf16 v[62:65], v[130:133], v[174:177], v[62:65]
	v_mfma_f32_16x16x32_bf16 v[58:61], v[138:141], v[174:177], v[58:61]
	v_mfma_f32_16x16x32_bf16 v[46:49], v[130:133], v[188:191], v[46:49]
	v_mfma_f32_16x16x32_bf16 v[42:45], v[138:141], v[188:191], v[42:45]
	v_mfma_f32_16x16x32_bf16 v[30:33], v[130:133], v[196:199], v[30:33]
	v_mfma_f32_16x16x32_bf16 v[26:29], v[138:141], v[196:199], v[26:29]
	v_mfma_f32_16x16x32_bf16 v[14:17], v[130:133], v[204:207], v[14:17]
	v_mfma_f32_16x16x32_bf16 v[10:13], v[138:141], v[204:207], v[10:13]
	s_setprio 0
	s_setprio 1
	v_mfma_f32_16x16x32_bf16 v[62:65], v[134:137], v[184:187], v[62:65]
	v_mfma_f32_16x16x32_bf16 v[58:61], v[142:145], v[184:187], v[58:61]
	v_mfma_f32_16x16x32_bf16 v[46:49], v[134:137], v[192:195], v[46:49]
	v_mfma_f32_16x16x32_bf16 v[42:45], v[142:145], v[192:195], v[42:45]
	v_mfma_f32_16x16x32_bf16 v[30:33], v[134:137], v[200:203], v[30:33]
	v_mfma_f32_16x16x32_bf16 v[26:29], v[142:145], v[200:203], v[26:29]
	v_mfma_f32_16x16x32_bf16 v[14:17], v[134:137], v[208:211], v[14:17]
	v_mfma_f32_16x16x32_bf16 v[10:13], v[142:145], v[208:211], v[10:13]
	s_setprio 0
	s_setprio 1
	v_mfma_f32_16x16x32_bf16 v[54:57], v[158:161], v[174:177], v[54:57]
	v_mfma_f32_16x16x32_bf16 v[50:53], v[166:169], v[174:177], v[50:53]
	v_mfma_f32_16x16x32_bf16 v[38:41], v[158:161], v[188:191], v[38:41]
	v_mfma_f32_16x16x32_bf16 v[34:37], v[166:169], v[188:191], v[34:37]
	v_mfma_f32_16x16x32_bf16 v[22:25], v[158:161], v[196:199], v[22:25]
	v_mfma_f32_16x16x32_bf16 v[18:21], v[166:169], v[196:199], v[18:21]
	v_mfma_f32_16x16x32_bf16 v[6:9], v[158:161], v[204:207], v[6:9]
	v_mfma_f32_16x16x32_bf16 v[2:5], v[166:169], v[204:207], v[2:5]
	s_setprio 0
	s_setprio 1
	v_mfma_f32_16x16x32_bf16 v[54:57], v[162:165], v[184:187], v[54:57]
	v_mfma_f32_16x16x32_bf16 v[50:53], v[170:173], v[184:187], v[50:53]
	v_mfma_f32_16x16x32_bf16 v[38:41], v[162:165], v[192:195], v[38:41]
	v_mfma_f32_16x16x32_bf16 v[34:37], v[170:173], v[192:195], v[34:37]
	v_mfma_f32_16x16x32_bf16 v[22:25], v[162:165], v[200:203], v[22:25]
	v_mfma_f32_16x16x32_bf16 v[18:21], v[170:173], v[200:203], v[18:21]
	v_mfma_f32_16x16x32_bf16 v[6:9], v[162:165], v[208:211], v[6:9]
	v_mfma_f32_16x16x32_bf16 v[2:5], v[170:173], v[208:211], v[2:5]
	s_setprio 0
	s_barrier
	s_add_i32 s64, s64, 2
	s_add_u32 s56, s56, 0x100
	s_addc_u32 s57, s57, 0
	s_add_u32 s58, s58, 0x100
	s_addc_u32 s59, s59, 0
	s_cmpk_gt_u32 s64, 0x7d
	s_cbranch_scc0 .LBB0_1422
	s_and_b64 vcc, exec, s[46:47]
	s_cbranch_vccz .LBB0_1425
	s_barrier
